# fused conv+gate epilogue now in both layers ctx-half up-GEMMs (L0 and L1); both convgate-hf0 phases and 4 grid barriers removed; workgroup barrier kept at the skip point
# speedup vs baseline: 1.0173x; 1.0173x over previous
.LBB0_818:
	s_add_u32 s33, s70, 0xa00000
	s_mov_b64 s[2:3], s[82:83]
	s_addc_u32 s82, s71, 0
	s_cmpk_lt_i32 s84, 0x2c0
	s_cselect_b64 s[4:5], -1, 0
	s_ashr_i32 s85, s84, 31
	s_lshr_b32 s0, s85, 29
	s_add_i32 s0, s84, s0
	s_ashr_i32 s1, s0, 3
	s_and_b32 s0, s0, -8
	s_sub_i32 s0, s84, s0
	s_cmp_lt_i32 s0, 0
	v_writelane_b32 v254, s1, 61
	s_cselect_b64 s[6:7], -1, 0
	v_writelane_b32 v254, s6, 62
	s_cmp_gt_i32 s0, -1
	s_mov_b32 s18, s2
	v_writelane_b32 v254, s7, 63
	v_writelane_b32 v254, s0, 51
	s_cselect_b64 s[0:1], -1, 0
	s_ashr_i32 s19, s2, 31
	v_writelane_b32 v255, s0, 0
	s_cmpk_eq_i32 s2, 0x100
	v_cmp_eq_u32_e64 s[2:3], 0, v230
	v_writelane_b32 v255, s1, 1
	s_cselect_b64 s[0:1], -1, 0
	s_cmpk_gt_u32 s84, 0xbf
	s_cselect_b64 s[6:7], -1, 0
	s_and_b64 s[8:9], s[6:7], s[0:1]
	s_lshl_b32 s1, s84, 3
	s_add_i32 s83, s1, 0xfffffa00
	s_cmp_gt_i32 s72, 7
	v_writelane_b32 v254, s2, 59
	s_cselect_b64 s[6:7], -1, 0
	s_cmp_lt_i32 s73, 8
	v_cndmask_b32_e64 v0, 0, 1, s[4:5]
	v_writelane_b32 v254, s3, 60
	s_cselect_b64 s[12:13], -1, 0
	v_cmp_ne_u32_e64 s[2:3], 1, v0
	s_or_b64 s[6:7], s[6:7], s[12:13]
	s_and_b64 vcc, exec, s[6:7]
	v_writelane_b32 v255, s2, 2
	s_nop 1
	v_writelane_b32 v255, s3, 3
	s_cbranch_vccnz .LBB0_899
	v_readlane_b32 s2, v255, 2
	v_mov_b32_e32 v14, v230
	v_readlane_b32 s3, v255, 3
	s_and_b64 vcc, exec, s[2:3]
	v_readfirstlane_b32 s5, v14
	s_cbranch_vccnz .LBB0_834
	v_lshlrev_b32_e32 v0, 4, v14
	s_waitcnt lgkmcnt(0)
	v_add_u32_e32 v1, 0x2000, v0
	v_ashrrev_i32_e32 v2, 31, v1
	v_lshrrev_b32_e32 v2, 22, v2
	v_add_u32_e32 v2, v1, v2
	v_ashrrev_i32_e32 v8, 10, v2
	v_mul_i32_i24_e32 v2, 0x400, v8
	v_sub_u32_e32 v1, v1, v2
	v_lshrrev_b32_e32 v2, 4, v1
	v_bitop3_b32 v1, v2, v1, 32 bitop3:0x6c
	v_ashrrev_i32_e32 v2, 31, v1
	v_lshrrev_b32_e32 v2, 26, v2
	v_add_u32_e32 v2, v1, v2
	v_lshlrev_b32_e32 v3, 3, v8
	v_ashrrev_i32_e32 v9, 6, v2
	v_and_b32_e32 v3, -16, v3
	v_add_u32_e32 v3, v9, v3
	v_and_b32_e32 v4, 3, v9
	s_mov_b32 s4, 0x1fffe0
	v_lshrrev_b32_e32 v5, 2, v3
	v_lshlrev_b32_e32 v6, 1, v3
	v_and_b32_e32 v2, 0xc0, v2
	v_and_or_b32 v4, v3, s4, v4
	v_and_b32_e32 v5, 4, v5
	v_and_b32_e32 v6, 24, v6
	v_sub_u32_e32 v1, v1, v2
	v_mov_b32_e32 v2, 1
	v_or3_b32 v4, v4, v5, v6
	v_lshlrev_b32_e32 v5, 5, v8
	v_ashrrev_i16_sdwa v1, v2, sext(v1) dst_sel:DWORD dst_unused:UNUSED_PAD src0_sel:DWORD src1_sel:BYTE_0
	v_and_b32_e32 v5, 32, v5
	v_bfe_i32 v10, v1, 0, 16
	v_add_lshl_u32 v1, v5, v10, 1
	v_lshl_add_u32 v144, v4, 11, v1
	v_lshl_add_u32 v146, v3, 11, v1
	v_bfe_i32 v1, v14, 27, 1
	v_lshrrev_b32_e32 v1, 22, v1
	v_add_u32_e32 v1, v0, v1
	v_and_b32_e32 v1, 0xfffffc00, v1
	v_sub_u32_e32 v0, v0, v1
	v_lshrrev_b32_e32 v1, 4, v0
	v_ashrrev_i32_e32 v3, 31, v14
	v_bitop3_b32 v0, v1, v0, 32 bitop3:0x6c
	v_lshrrev_b32_e32 v3, 26, v3
	v_ashrrev_i32_e32 v1, 31, v0
	v_add_u32_e32 v3, v14, v3
	s_add_u32 s0, s70, 0xcb00000
	v_lshrrev_b32_e32 v1, 26, v1
	v_ashrrev_i32_e32 v12, 6, v3
	s_addc_u32 s20, s71, 0
	s_ashr_i32 s6, s5, 6
	v_add_u32_e32 v1, v0, v1
	v_lshlrev_b32_e32 v3, 3, v12
	v_readlane_b32 s2, v254, 62
	s_ashr_i32 s7, s5, 8
	s_lshl_b32 s21, s6, 10
	v_ashrrev_i32_e32 v11, 6, v1
	v_and_b32_e32 v3, -16, v3
	v_readlane_b32 s3, v254, 63
	v_add_u32_e32 v3, v11, v3
	v_and_b32_e32 v4, 3, v11
	s_movk_i32 s30, 0x59
	s_and_b64 s[12:13], s[2:3], exec
	v_and_or_b32 v4, v3, s4, v4
	s_cselect_b32 s4, s30, 0x58
	v_readlane_b32 s2, v254, 51
	s_mul_i32 s4, s4, s2
	v_readlane_b32 s2, v254, 61
	s_add_i32 s4, s4, s2
	s_mul_hi_i32 s12, s4, 0x2e8ba2e9
	s_lshr_b32 s13, s12, 31
	s_ashr_i32 s12, s12, 5
	s_add_i32 s12, s12, s13
	s_lshl_b32 s13, s12, 3
	s_mulk_i32 s12, 0xb0
	s_sub_i32 s12, s4, s12
	s_bfe_u32 s4, s12, 0x3001c
	s_add_i32 s14, s12, s4
	s_sext_i32_i16 s4, s14
	s_and_b32 s14, s14, 0xfff8
	s_sub_i32 s12, s12, s14
	s_sext_i32_i16 s12, s12
	v_lshrrev_b32_e32 v5, 2, v3
	v_lshlrev_b32_e32 v6, 1, v3
	v_and_b32_e32 v1, 0xc0, v1
	s_lshr_b32 s4, s4, 3
	s_add_i32 s88, s13, s12
	v_and_b32_e32 v5, 4, v5
	v_and_b32_e32 v6, 24, v6
	v_sub_u32_e32 v0, v0, v1
	s_ashr_i32 s89, s88, 31
	s_bfe_i64 s[14:15], s[4:5], 0x100000
	v_or3_b32 v4, v4, v5, v6
	v_lshlrev_b32_e32 v5, 5, v12
	v_ashrrev_i16_sdwa v0, v2, sext(v0) dst_sel:DWORD dst_unused:UNUSED_PAD src0_sel:DWORD src1_sel:BYTE_0
	s_lshl_b64 s[12:13], s[88:89], 19
	s_lshl_b64 s[14:15], s[14:15], 18
	v_and_b32_e32 v5, 32, v5
	v_bfe_i32 v13, v0, 0, 16
	s_add_u32 s92, s33, s14
	v_add_lshl_u32 v0, v5, v13, 1
	s_addc_u32 s93, s82, s15
	s_add_i32 s31, s21, 0
	v_lshl_add_u32 v148, v4, 11, v0
	s_add_i32 m0, s31, 0x10000
	v_lshl_add_u32 v150, v3, 11, v0
	global_load_lds_dwordx4 v148, s[92:93]
	s_add_i32 m0, s31, 0x12000
	s_add_u32 s14, s92, 0x580000
	global_load_lds_dwordx4 v144, s[92:93]
	s_addc_u32 s15, s93, 0
	s_add_i32 m0, s31, 0x14000
	v_mov_b32_e32 v149, 0
	global_load_lds_dwordx4 v148, s[14:15]
	s_add_i32 m0, s31, 0x16000
	s_add_u32 s90, s0, s12
	s_addc_u32 s91, s20, s13
	s_add_i32 s52, s31, 0x2000
	global_load_lds_dwordx4 v144, s[14:15]
	s_mov_b32 m0, s31
	s_add_u32 s12, s90, 0x40000
	global_load_lds_dwordx4 v150, s[90:91]
	s_mov_b32 m0, s52
	s_addc_u32 s13, s91, 0
	s_add_i32 s53, s31, 0x4000
	global_load_lds_dwordx4 v146, s[90:91]
	s_mov_b32 m0, s53
	s_add_i32 s58, s31, 0x6000
	global_load_lds_dwordx4 v150, s[12:13]
	s_mov_b32 m0, s58
	v_mov_b32_e32 v145, v149
	global_load_lds_dwordx4 v146, s[12:13]
	v_mov_b32_e32 v151, v149
	v_mov_b32_e32 v147, v149
	s_cmp_eq_u32 s7, 1
	s_mov_b32 s59, 0
	v_lshl_add_u64 v[6:7], s[92:93], 0, v[148:149]
	v_lshl_add_u64 v[4:5], s[92:93], 0, v[144:145]
	v_lshl_add_u64 v[0:1], s[90:91], 0, v[150:151]
	s_cselect_b64 s[12:13], -1, 0
	s_cmp_lg_u32 s7, 1
	v_lshl_add_u64 v[2:3], s[90:91], 0, v[146:147]
	s_cbranch_scc1 .LBB0_822
	s_barrier
.LBB0_822:
	v_lshrrev_b32_e32 v16, 1, v14
	v_and_b32_e32 v16, 24, v16
	s_add_u32 s14, s70, 0x3b00000
	v_and_b32_e32 v15, 15, v14
	v_lshlrev_b32_e32 v17, 1, v16
	v_lshlrev_b32_e32 v14, 2, v14
	s_sext_i32_i16 s66, s4
	s_addc_u32 s15, s71, 0
	v_lshl_or_b32 v170, s7, 6, v15
	v_lshl_or_b32 v15, v15, 6, v17
	s_lshl_b32 s4, s7, 13
	v_and_b32_e32 v14, 32, v14
	v_bitop3_b32 v17, v15, s4, v14 bitop3:0xde
	s_lshl_b32 s4, s6, 5
	s_mov_b64 s[16:17], 0x80
	s_and_b32 s4, s4, 0x60
	s_add_i32 m0, s31, 0x18000
	v_lshl_add_u64 v[6:7], v[6:7], 0, s[16:17]
	s_lshl_b32 s6, s4, 7
	s_waitcnt vmcnt(2)
	s_barrier
	global_load_lds_dwordx4 v[6:7], off
	v_lshl_add_u64 v[4:5], v[4:5], 0, s[16:17]
	s_add_i32 m0, s31, 0x1a000
	s_add_i32 s60, s31, 0x8000
	s_add_i32 s61, s31, 0xa000
	v_bitop3_b32 v171, v15, s6, v14 bitop3:0xde
	global_load_lds_dwordx4 v[4:5], off
	v_lshl_add_u64 v[0:1], v[0:1], 0, s[16:17]
	s_mov_b32 m0, s60
	s_add_u32 s6, s92, 0x580080
	global_load_lds_dwordx4 v[0:1], off
	v_lshl_add_u64 v[0:1], v[2:3], 0, s[16:17]
	s_mov_b32 m0, s61
	s_addc_u32 s7, s93, 0
	global_load_lds_dwordx4 v[0:1], off
	s_add_i32 m0, s31, 0x1c000
	v_lshl_add_u64 v[0:1], s[6:7], 0, v[148:149]
	global_load_lds_dwordx4 v[0:1], off
	v_lshl_add_u64 v[0:1], s[6:7], 0, v[144:145]
	s_add_i32 m0, s31, 0x1e000
	s_cmpk_lt_u32 s5, 0x100
	global_load_lds_dwordx4 v[0:1], off
	v_lshlrev_b32_e32 v0, 14, v12
	v_and_b32_e32 v0, 0xffff8000, v0
	v_lshl_add_u32 v0, v11, 11, v0
	v_and_b32_e32 v1, 1, v12
	v_lshl_or_b32 v0, v1, 6, v0
	v_lshl_add_u32 v152, v13, 1, v0
	v_lshlrev_b32_e32 v0, 14, v8
	v_and_b32_e32 v0, 0xffff8000, v0
	s_waitcnt vmcnt(6)
	v_lshl_add_u32 v0, v9, 11, v0
	v_and_b32_e32 v1, 1, v8
	s_cselect_b64 s[34:35], -1, 0
	v_lshl_or_b32 v0, v1, 6, v0
	s_add_i32 s62, 0, 0x10000
	s_add_i32 s63, 0, 0x14000
	v_or_b32_e32 v172, s4, v16
	v_mov_b32_e32 v153, v149
	v_lshl_add_u32 v154, v10, 1, v0
	v_mov_b32_e32 v155, v149
	v_mov_b64_e32 v[156:157], 0x2c0
	v_mov_b64_e32 v[158:159], 0x2bf
	v_add_u32_e32 v173, s62, v171
	v_add_u32_e32 v174, s63, v171
	v_add_u32_e32 v175, 0, v17
	v_mov_b32_e32 v176, 0x358637bd
	s_mov_b32 s64, 0x800000
	s_movk_i32 s65, 0x2c00
	s_barrier
	s_branch .LBB0_825

.LBB0_827:
	s_ashr_i32 s57, s56, 31
	s_lshl_b64 s[4:5], s[56:57], 19
	s_add_u32 s74, s0, s4
	s_addc_u32 s75, s20, s5
	s_and_b64 s[4:5], s[6:7], exec
	s_cselect_b32 s4, s75, s91
	s_cselect_b32 s5, s74, s90
	s_ashr_i32 s55, s54, 31
	s_lshl_b64 s[76:77], s[54:55], 18
	s_add_u32 s86, s33, s76
	s_addc_u32 s87, s82, s77
	s_and_b64 s[76:77], s[6:7], exec
	s_cselect_b32 s55, s87, s93
	s_cselect_b32 s57, s86, s92
	s_add_u32 s90, s90, 0x40080
	s_addc_u32 s91, s91, 0
	s_add_u32 s67, s92, 0x100
	v_mov_b32_e32 v0, 0
	s_addc_u32 s76, s93, 0
	s_mov_b32 s77, -2
	v_mov_b32_e32 v1, v0
	v_mov_b32_e32 v2, v0
	v_mov_b32_e32 v3, v0
	v_mov_b32_e32 v4, v0
	v_mov_b32_e32 v5, v0
	v_mov_b32_e32 v6, v0
	v_mov_b32_e32 v7, v0
	v_mov_b32_e32 v16, v0
	v_mov_b32_e32 v17, v0
	v_mov_b32_e32 v18, v0
	v_mov_b32_e32 v19, v0
	v_mov_b32_e32 v20, v0
	v_mov_b32_e32 v21, v0
	v_mov_b32_e32 v22, v0
	v_mov_b32_e32 v23, v0
	v_mov_b32_e32 v32, v0
	v_mov_b32_e32 v33, v0
	v_mov_b32_e32 v34, v0
	v_mov_b32_e32 v35, v0
	v_mov_b32_e32 v36, v0
	v_mov_b32_e32 v37, v0
	v_mov_b32_e32 v38, v0
	v_mov_b32_e32 v39, v0
	v_mov_b32_e32 v48, v0
	v_mov_b32_e32 v49, v0
	v_mov_b32_e32 v50, v0
	v_mov_b32_e32 v51, v0
	v_mov_b32_e32 v52, v0
	v_mov_b32_e32 v53, v0
	v_mov_b32_e32 v54, v0
	v_mov_b32_e32 v55, v0
	v_mov_b32_e32 v8, v0
	v_mov_b32_e32 v9, v0
	v_mov_b32_e32 v10, v0
	v_mov_b32_e32 v11, v0
	v_mov_b32_e32 v12, v0
	v_mov_b32_e32 v13, v0
	v_mov_b32_e32 v14, v0
	v_mov_b32_e32 v15, v0
	v_mov_b32_e32 v24, v0
	v_mov_b32_e32 v25, v0
	v_mov_b32_e32 v26, v0
	v_mov_b32_e32 v27, v0
	v_mov_b32_e32 v28, v0
	v_mov_b32_e32 v29, v0
	v_mov_b32_e32 v30, v0
	v_mov_b32_e32 v31, v0
	v_mov_b32_e32 v40, v0
	v_mov_b32_e32 v41, v0
	v_mov_b32_e32 v42, v0
	v_mov_b32_e32 v43, v0
	v_mov_b32_e32 v44, v0
	v_mov_b32_e32 v45, v0
	v_mov_b32_e32 v46, v0
	v_mov_b32_e32 v47, v0
	v_mov_b32_e32 v56, v0
	v_mov_b32_e32 v57, v0
	v_mov_b32_e32 v58, v0
	v_mov_b32_e32 v59, v0
	v_mov_b32_e32 v60, v0
	v_mov_b32_e32 v61, v0
	v_mov_b32_e32 v62, v0
	v_mov_b32_e32 v63, v0
	v_mov_b32_e32 v64, v0
	v_mov_b32_e32 v65, v0
	v_mov_b32_e32 v66, v0
	v_mov_b32_e32 v67, v0
	v_mov_b32_e32 v68, v0
	v_mov_b32_e32 v69, v0
	v_mov_b32_e32 v70, v0
	v_mov_b32_e32 v71, v0
	v_mov_b32_e32 v80, v0
	v_mov_b32_e32 v81, v0
	v_mov_b32_e32 v82, v0
	v_mov_b32_e32 v83, v0
	v_mov_b32_e32 v84, v0
	v_mov_b32_e32 v85, v0
	v_mov_b32_e32 v86, v0
	v_mov_b32_e32 v87, v0
	v_mov_b32_e32 v96, v0
	v_mov_b32_e32 v97, v0
	v_mov_b32_e32 v98, v0
	v_mov_b32_e32 v99, v0
	v_mov_b32_e32 v100, v0
	v_mov_b32_e32 v101, v0
	v_mov_b32_e32 v102, v0
	v_mov_b32_e32 v103, v0
	v_mov_b32_e32 v112, v0
	v_mov_b32_e32 v113, v0
	v_mov_b32_e32 v114, v0
	v_mov_b32_e32 v115, v0
	v_mov_b32_e32 v120, v0
	v_mov_b32_e32 v121, v0
	v_mov_b32_e32 v122, v0
	v_mov_b32_e32 v123, v0
	v_mov_b32_e32 v72, v0
	v_mov_b32_e32 v73, v0
	v_mov_b32_e32 v74, v0
	v_mov_b32_e32 v75, v0
	v_mov_b32_e32 v76, v0
	v_mov_b32_e32 v77, v0
	v_mov_b32_e32 v78, v0
	v_mov_b32_e32 v79, v0
	v_mov_b32_e32 v88, v0
	v_mov_b32_e32 v89, v0
	v_mov_b32_e32 v90, v0
	v_mov_b32_e32 v91, v0
	v_mov_b32_e32 v92, v0
	v_mov_b32_e32 v93, v0
	v_mov_b32_e32 v94, v0
	v_mov_b32_e32 v95, v0
	v_mov_b32_e32 v104, v0
	v_mov_b32_e32 v105, v0
	v_mov_b32_e32 v106, v0
	v_mov_b32_e32 v107, v0
	v_mov_b32_e32 v108, v0
	v_mov_b32_e32 v109, v0
	v_mov_b32_e32 v110, v0
	v_mov_b32_e32 v111, v0
	v_mov_b32_e32 v136, v0
	v_mov_b32_e32 v137, v0
	v_mov_b32_e32 v138, v0
	v_mov_b32_e32 v139, v0
	v_mov_b32_e32 v140, v0
	v_mov_b32_e32 v141, v0
	v_mov_b32_e32 v142, v0
	v_mov_b32_e32 v143, v0
.LBB0_828:
	ds_read_b128 v[116:119], v173
	ds_read_b128 v[124:127], v173 offset:1024
	ds_read_b128 v[128:131], v173 offset:2048
	ds_read_b128 v[132:135], v173 offset:3072
	ds_read_b128 v[160:163], v174
	ds_read_b128 v[164:167], v174 offset:1024
	ds_read_b128 v[178:181], v174 offset:2048
	ds_read_b128 v[182:185], v174 offset:3072
	s_add_u32 s78, s90, 0xfffc0080
	s_addc_u32 s79, s91, -1
	s_cmp_eq_u32 s77, 12
	s_cselect_b32 s95, s4, s79
	s_cselect_b32 s94, s5, s78
	s_cselect_b32 s93, s55, s76
	s_cselect_b32 s92, s57, s67
	v_lshl_add_u64 v[168:169], s[90:91], 0, v[152:153]
	s_add_i32 m0, s31, 0xc000
	ds_read_b128 v[186:189], v175
	ds_read_b128 v[190:193], v175 offset:1024
	ds_read_b128 v[194:197], v175 offset:2048
	ds_read_b128 v[198:201], v175 offset:3072
	ds_read_b128 v[202:205], v175 offset:4096
	ds_read_b128 v[206:209], v175 offset:5120
	ds_read_b128 v[210:213], v175 offset:6144
	ds_read_b128 v[214:217], v175 offset:7168
	global_load_lds_dwordx4 v[168:169], off
	v_lshl_add_u64 v[168:169], s[90:91], 0, v[154:155]
	s_add_i32 m0, s31, 0xe000
	s_nop 0
	global_load_lds_dwordx4 v[168:169], off
	s_waitcnt vmcnt(8)
	s_waitcnt lgkmcnt(0)
	s_barrier
	s_setprio 1
	s_waitcnt lgkmcnt(0)
	v_mfma_f32_16x16x32_bf16 v[140:143], v[116:119], v[186:189], v[140:143]
	v_mfma_f32_16x16x32_bf16 v[136:139], v[128:131], v[186:189], v[136:139]
	v_mfma_f32_16x16x32_bf16 v[108:111], v[116:119], v[194:197], v[108:111]
	v_mfma_f32_16x16x32_bf16 v[104:107], v[128:131], v[194:197], v[104:107]
	v_mfma_f32_16x16x32_bf16 v[92:95], v[116:119], v[202:205], v[92:95]
	v_mfma_f32_16x16x32_bf16 v[88:91], v[128:131], v[202:205], v[88:91]
	v_mfma_f32_16x16x32_bf16 v[76:79], v[116:119], v[210:213], v[76:79]
	v_mfma_f32_16x16x32_bf16 v[72:75], v[128:131], v[210:213], v[72:75]
	v_mfma_f32_16x16x32_bf16 v[140:143], v[124:127], v[190:193], v[140:143]
	v_mfma_f32_16x16x32_bf16 v[136:139], v[132:135], v[190:193], v[136:139]
	v_mfma_f32_16x16x32_bf16 v[108:111], v[124:127], v[198:201], v[108:111]
	v_mfma_f32_16x16x32_bf16 v[104:107], v[132:135], v[198:201], v[104:107]
	v_mfma_f32_16x16x32_bf16 v[92:95], v[124:127], v[206:209], v[92:95]
	v_mfma_f32_16x16x32_bf16 v[88:91], v[132:135], v[206:209], v[88:91]
	v_mfma_f32_16x16x32_bf16 v[76:79], v[124:127], v[214:217], v[76:79]
	v_mfma_f32_16x16x32_bf16 v[72:75], v[132:135], v[214:217], v[72:75]
	s_setprio 0
	s_setprio 1
	v_mfma_f32_16x16x32_bf16 v[120:123], v[160:163], v[186:189], v[120:123]
	v_mfma_f32_16x16x32_bf16 v[112:115], v[178:181], v[186:189], v[112:115]
	v_mfma_f32_16x16x32_bf16 v[100:103], v[160:163], v[194:197], v[100:103]
	v_mfma_f32_16x16x32_bf16 v[96:99], v[178:181], v[194:197], v[96:99]
	v_mfma_f32_16x16x32_bf16 v[84:87], v[160:163], v[202:205], v[84:87]
	v_mfma_f32_16x16x32_bf16 v[80:83], v[178:181], v[202:205], v[80:83]
	v_mfma_f32_16x16x32_bf16 v[68:71], v[160:163], v[210:213], v[68:71]
	v_mfma_f32_16x16x32_bf16 v[64:67], v[178:181], v[210:213], v[64:67]
	v_mfma_f32_16x16x32_bf16 v[120:123], v[164:167], v[190:193], v[120:123]
	v_mfma_f32_16x16x32_bf16 v[112:115], v[182:185], v[190:193], v[112:115]
	v_mfma_f32_16x16x32_bf16 v[100:103], v[164:167], v[198:201], v[100:103]
	v_mfma_f32_16x16x32_bf16 v[96:99], v[182:185], v[198:201], v[96:99]
	v_mfma_f32_16x16x32_bf16 v[84:87], v[164:167], v[206:209], v[84:87]
	v_mfma_f32_16x16x32_bf16 v[80:83], v[182:185], v[206:209], v[80:83]
	v_mfma_f32_16x16x32_bf16 v[68:71], v[164:167], v[214:217], v[68:71]
	v_mfma_f32_16x16x32_bf16 v[64:67], v[182:185], v[214:217], v[64:67]
	s_setprio 0
	s_barrier
	s_add_i32 s78, s62, s21
	v_lshl_add_u64 v[168:169], s[92:93], 0, v[148:149]
	s_mov_b32 m0, s78
	ds_read_b128 v[186:189], v175 offset:16384
	ds_read_b128 v[190:193], v175 offset:17408
	ds_read_b128 v[194:197], v175 offset:18432
	ds_read_b128 v[198:201], v175 offset:19456
	ds_read_b128 v[202:205], v175 offset:20480
	ds_read_b128 v[206:209], v175 offset:21504
	ds_read_b128 v[210:213], v175 offset:22528
	ds_read_b128 v[214:217], v175 offset:23552
	global_load_lds_dwordx4 v[168:169], off
	s_add_i32 m0, s78, 0x2000
	s_add_u32 s78, s92, 0x580000
	v_lshl_add_u64 v[218:219], s[92:93], 0, v[144:145]
	s_addc_u32 s79, s93, 0
	s_add_i32 s80, s63, s21
	global_load_lds_dwordx4 v[218:219], off
	v_lshl_add_u64 v[220:221], s[78:79], 0, v[148:149]
	s_mov_b32 m0, s80
	v_lshl_add_u64 v[222:223], s[94:95], 0, v[146:147]
	global_load_lds_dwordx4 v[220:221], off
	v_lshl_add_u64 v[220:221], s[78:79], 0, v[144:145]
	s_add_i32 m0, s80, 0x2000
	s_nop 0
	global_load_lds_dwordx4 v[220:221], off
	v_lshl_add_u64 v[220:221], s[94:95], 0, v[150:151]
	s_mov_b32 m0, s31
	s_nop 0
	global_load_lds_dwordx4 v[220:221], off
	s_mov_b32 m0, s52
	s_nop 0
	global_load_lds_dwordx4 v[222:223], off
	s_waitcnt vmcnt(8)
	s_waitcnt lgkmcnt(0)
	s_barrier
	s_setprio 1
	s_waitcnt lgkmcnt(0)
	v_mfma_f32_16x16x32_bf16 v[60:63], v[116:119], v[186:189], v[60:63]
	v_mfma_f32_16x16x32_bf16 v[56:59], v[128:131], v[186:189], v[56:59]
	v_mfma_f32_16x16x32_bf16 v[44:47], v[116:119], v[194:197], v[44:47]
	v_mfma_f32_16x16x32_bf16 v[40:43], v[128:131], v[194:197], v[40:43]
	v_mfma_f32_16x16x32_bf16 v[28:31], v[116:119], v[202:205], v[28:31]
	v_mfma_f32_16x16x32_bf16 v[24:27], v[128:131], v[202:205], v[24:27]
	v_mfma_f32_16x16x32_bf16 v[12:15], v[116:119], v[210:213], v[12:15]
	v_mfma_f32_16x16x32_bf16 v[8:11], v[128:131], v[210:213], v[8:11]
	v_mfma_f32_16x16x32_bf16 v[60:63], v[124:127], v[190:193], v[60:63]
	v_mfma_f32_16x16x32_bf16 v[56:59], v[132:135], v[190:193], v[56:59]
	v_mfma_f32_16x16x32_bf16 v[44:47], v[124:127], v[198:201], v[44:47]
	v_mfma_f32_16x16x32_bf16 v[40:43], v[132:135], v[198:201], v[40:43]
	v_mfma_f32_16x16x32_bf16 v[28:31], v[124:127], v[206:209], v[28:31]
	v_mfma_f32_16x16x32_bf16 v[24:27], v[132:135], v[206:209], v[24:27]
	v_mfma_f32_16x16x32_bf16 v[12:15], v[124:127], v[214:217], v[12:15]
	v_mfma_f32_16x16x32_bf16 v[8:11], v[132:135], v[214:217], v[8:11]
	s_setprio 0
	s_setprio 1
	v_mfma_f32_16x16x32_bf16 v[52:55], v[160:163], v[186:189], v[52:55]
	v_mfma_f32_16x16x32_bf16 v[48:51], v[178:181], v[186:189], v[48:51]
	v_mfma_f32_16x16x32_bf16 v[36:39], v[160:163], v[194:197], v[36:39]
	v_mfma_f32_16x16x32_bf16 v[32:35], v[178:181], v[194:197], v[32:35]
	v_mfma_f32_16x16x32_bf16 v[20:23], v[160:163], v[202:205], v[20:23]
	v_mfma_f32_16x16x32_bf16 v[16:19], v[178:181], v[202:205], v[16:19]
	v_mfma_f32_16x16x32_bf16 v[4:7], v[160:163], v[210:213], v[4:7]
	v_mfma_f32_16x16x32_bf16 v[0:3], v[178:181], v[210:213], v[0:3]
	v_mfma_f32_16x16x32_bf16 v[52:55], v[164:167], v[190:193], v[52:55]
	v_mfma_f32_16x16x32_bf16 v[48:51], v[182:185], v[190:193], v[48:51]
	v_mfma_f32_16x16x32_bf16 v[36:39], v[164:167], v[198:201], v[36:39]
	v_mfma_f32_16x16x32_bf16 v[32:35], v[182:185], v[198:201], v[32:35]
	v_mfma_f32_16x16x32_bf16 v[20:23], v[164:167], v[206:209], v[20:23]
	v_mfma_f32_16x16x32_bf16 v[16:19], v[182:185], v[206:209], v[16:19]
	v_mfma_f32_16x16x32_bf16 v[4:7], v[164:167], v[214:217], v[4:7]
	v_mfma_f32_16x16x32_bf16 v[0:3], v[182:185], v[214:217], v[0:3]
	s_setprio 0
	s_barrier
	s_add_i32 s80, 0, 0x18000
	s_add_i32 s81, 0, 0x1c000
	v_add_u32_e32 v132, s80, v171
	v_add_u32_e32 v177, s81, v171
	ds_read_b128 v[116:119], v132
	ds_read_b128 v[124:127], v132 offset:1024
	ds_read_b128 v[128:131], v132 offset:2048
	ds_read_b128 v[132:135], v132 offset:3072
	ds_read_b128 v[160:163], v177
	ds_read_b128 v[164:167], v177 offset:1024
	ds_read_b128 v[178:181], v177 offset:2048
	ds_read_b128 v[182:185], v177 offset:3072
	s_add_u32 s78, s94, 0x40000
	s_addc_u32 s79, s95, 0
	s_mov_b32 m0, s53
	v_lshl_add_u64 v[224:225], s[78:79], 0, v[150:151]
	ds_read_b128 v[186:189], v175 offset:32768
	ds_read_b128 v[190:193], v175 offset:33792
	ds_read_b128 v[194:197], v175 offset:34816
	ds_read_b128 v[198:201], v175 offset:35840
	ds_read_b128 v[202:205], v175 offset:36864
	ds_read_b128 v[206:209], v175 offset:37888
	ds_read_b128 v[210:213], v175 offset:38912
	ds_read_b128 v[214:217], v175 offset:39936
	global_load_lds_dwordx4 v[224:225], off
	v_lshl_add_u64 v[224:225], s[78:79], 0, v[146:147]
	s_mov_b32 m0, s58
	s_nop 0
	global_load_lds_dwordx4 v[224:225], off
	s_waitcnt vmcnt(8)
	s_waitcnt lgkmcnt(0)
	s_barrier
	s_setprio 1
	s_waitcnt lgkmcnt(0)
	v_mfma_f32_16x16x32_bf16 v[140:143], v[116:119], v[186:189], v[140:143]
	v_mfma_f32_16x16x32_bf16 v[136:139], v[128:131], v[186:189], v[136:139]
	v_mfma_f32_16x16x32_bf16 v[108:111], v[116:119], v[194:197], v[108:111]
	v_mfma_f32_16x16x32_bf16 v[104:107], v[128:131], v[194:197], v[104:107]
	v_mfma_f32_16x16x32_bf16 v[92:95], v[116:119], v[202:205], v[92:95]
	v_mfma_f32_16x16x32_bf16 v[88:91], v[128:131], v[202:205], v[88:91]
	v_mfma_f32_16x16x32_bf16 v[76:79], v[116:119], v[210:213], v[76:79]
	v_mfma_f32_16x16x32_bf16 v[72:75], v[128:131], v[210:213], v[72:75]
	v_mfma_f32_16x16x32_bf16 v[140:143], v[124:127], v[190:193], v[140:143]
	v_mfma_f32_16x16x32_bf16 v[136:139], v[132:135], v[190:193], v[136:139]
	v_mfma_f32_16x16x32_bf16 v[108:111], v[124:127], v[198:201], v[108:111]
	v_mfma_f32_16x16x32_bf16 v[104:107], v[132:135], v[198:201], v[104:107]
	v_mfma_f32_16x16x32_bf16 v[92:95], v[124:127], v[206:209], v[92:95]
	v_mfma_f32_16x16x32_bf16 v[88:91], v[132:135], v[206:209], v[88:91]
	v_mfma_f32_16x16x32_bf16 v[76:79], v[124:127], v[214:217], v[76:79]
	v_mfma_f32_16x16x32_bf16 v[72:75], v[132:135], v[214:217], v[72:75]
	s_setprio 0
	s_setprio 1
	v_mfma_f32_16x16x32_bf16 v[120:123], v[160:163], v[186:189], v[120:123]
	v_mfma_f32_16x16x32_bf16 v[112:115], v[178:181], v[186:189], v[112:115]
	v_mfma_f32_16x16x32_bf16 v[100:103], v[160:163], v[194:197], v[100:103]
	v_mfma_f32_16x16x32_bf16 v[96:99], v[178:181], v[194:197], v[96:99]
	v_mfma_f32_16x16x32_bf16 v[84:87], v[160:163], v[202:205], v[84:87]
	v_mfma_f32_16x16x32_bf16 v[80:83], v[178:181], v[202:205], v[80:83]
	v_mfma_f32_16x16x32_bf16 v[68:71], v[160:163], v[210:213], v[68:71]
	v_mfma_f32_16x16x32_bf16 v[64:67], v[178:181], v[210:213], v[64:67]
	v_mfma_f32_16x16x32_bf16 v[120:123], v[164:167], v[190:193], v[120:123]
	v_mfma_f32_16x16x32_bf16 v[112:115], v[182:185], v[190:193], v[112:115]
	v_mfma_f32_16x16x32_bf16 v[100:103], v[164:167], v[198:201], v[100:103]
	v_mfma_f32_16x16x32_bf16 v[96:99], v[182:185], v[198:201], v[96:99]
	v_mfma_f32_16x16x32_bf16 v[84:87], v[164:167], v[206:209], v[84:87]
	v_mfma_f32_16x16x32_bf16 v[80:83], v[182:185], v[206:209], v[80:83]
	v_mfma_f32_16x16x32_bf16 v[68:71], v[164:167], v[214:217], v[68:71]
	v_mfma_f32_16x16x32_bf16 v[64:67], v[182:185], v[214:217], v[64:67]
	s_setprio 0
	s_barrier
	s_add_i32 s78, s80, s21
	v_lshl_add_u64 v[168:169], v[168:169], 0, s[16:17]
	s_mov_b32 m0, s78
	ds_read_b128 v[186:189], v175 offset:49152
	ds_read_b128 v[190:193], v175 offset:50176
	ds_read_b128 v[194:197], v175 offset:51200
	ds_read_b128 v[198:201], v175 offset:52224
	ds_read_b128 v[202:205], v175 offset:53248
	ds_read_b128 v[206:209], v175 offset:54272
	ds_read_b128 v[210:213], v175 offset:55296
	ds_read_b128 v[214:217], v175 offset:56320
	global_load_lds_dwordx4 v[168:169], off
	s_add_i32 m0, s78, 0x2000
	s_add_u32 s78, s92, 0x580080
	v_lshl_add_u64 v[168:169], v[218:219], 0, s[16:17]
	s_addc_u32 s79, s93, 0
	s_add_i32 s80, s81, s21
	global_load_lds_dwordx4 v[168:169], off
	v_lshl_add_u64 v[168:169], s[78:79], 0, v[148:149]
	s_mov_b32 m0, s80
	s_nop 0
	global_load_lds_dwordx4 v[168:169], off
	v_lshl_add_u64 v[168:169], s[78:79], 0, v[144:145]
	s_add_i32 m0, s80, 0x2000
	s_nop 0
	global_load_lds_dwordx4 v[168:169], off
	v_lshl_add_u64 v[168:169], v[220:221], 0, s[16:17]
	s_mov_b32 m0, s60
	s_nop 0
	global_load_lds_dwordx4 v[168:169], off
	v_lshl_add_u64 v[168:169], v[222:223], 0, s[16:17]
	s_mov_b32 m0, s61
	s_nop 0
	global_load_lds_dwordx4 v[168:169], off
	s_waitcnt vmcnt(8)
	s_waitcnt lgkmcnt(0)
	s_barrier
	s_setprio 1
	s_waitcnt lgkmcnt(0)
	v_mfma_f32_16x16x32_bf16 v[60:63], v[116:119], v[186:189], v[60:63]
	v_mfma_f32_16x16x32_bf16 v[56:59], v[128:131], v[186:189], v[56:59]
	v_mfma_f32_16x16x32_bf16 v[44:47], v[116:119], v[194:197], v[44:47]
	v_mfma_f32_16x16x32_bf16 v[40:43], v[128:131], v[194:197], v[40:43]
	v_mfma_f32_16x16x32_bf16 v[28:31], v[116:119], v[202:205], v[28:31]
	v_mfma_f32_16x16x32_bf16 v[24:27], v[128:131], v[202:205], v[24:27]
	v_mfma_f32_16x16x32_bf16 v[12:15], v[116:119], v[210:213], v[12:15]
	v_mfma_f32_16x16x32_bf16 v[8:11], v[128:131], v[210:213], v[8:11]
	v_mfma_f32_16x16x32_bf16 v[60:63], v[124:127], v[190:193], v[60:63]
	v_mfma_f32_16x16x32_bf16 v[56:59], v[132:135], v[190:193], v[56:59]
	v_mfma_f32_16x16x32_bf16 v[44:47], v[124:127], v[198:201], v[44:47]
	v_mfma_f32_16x16x32_bf16 v[40:43], v[132:135], v[198:201], v[40:43]
	v_mfma_f32_16x16x32_bf16 v[28:31], v[124:127], v[206:209], v[28:31]
	v_mfma_f32_16x16x32_bf16 v[24:27], v[132:135], v[206:209], v[24:27]
	v_mfma_f32_16x16x32_bf16 v[12:15], v[124:127], v[214:217], v[12:15]
	v_mfma_f32_16x16x32_bf16 v[8:11], v[132:135], v[214:217], v[8:11]
	s_setprio 0
	s_setprio 1
	v_mfma_f32_16x16x32_bf16 v[52:55], v[160:163], v[186:189], v[52:55]
	v_mfma_f32_16x16x32_bf16 v[48:51], v[178:181], v[186:189], v[48:51]
	v_mfma_f32_16x16x32_bf16 v[36:39], v[160:163], v[194:197], v[36:39]
	v_mfma_f32_16x16x32_bf16 v[32:35], v[178:181], v[194:197], v[32:35]
	v_mfma_f32_16x16x32_bf16 v[20:23], v[160:163], v[202:205], v[20:23]
	v_mfma_f32_16x16x32_bf16 v[16:19], v[178:181], v[202:205], v[16:19]
	v_mfma_f32_16x16x32_bf16 v[4:7], v[160:163], v[210:213], v[4:7]
	v_mfma_f32_16x16x32_bf16 v[0:3], v[178:181], v[210:213], v[0:3]
	v_mfma_f32_16x16x32_bf16 v[52:55], v[164:167], v[190:193], v[52:55]
	v_mfma_f32_16x16x32_bf16 v[48:51], v[182:185], v[190:193], v[48:51]
	v_mfma_f32_16x16x32_bf16 v[36:39], v[164:167], v[198:201], v[36:39]
	v_mfma_f32_16x16x32_bf16 v[32:35], v[182:185], v[198:201], v[32:35]
	v_mfma_f32_16x16x32_bf16 v[20:23], v[164:167], v[206:209], v[20:23]
	v_mfma_f32_16x16x32_bf16 v[16:19], v[182:185], v[206:209], v[16:19]
	v_mfma_f32_16x16x32_bf16 v[4:7], v[164:167], v[214:217], v[4:7]
	v_mfma_f32_16x16x32_bf16 v[0:3], v[182:185], v[214:217], v[0:3]
	s_setprio 0
	s_barrier
	s_add_i32 s77, s77, 2
	s_add_u32 s90, s90, 0x100
	s_addc_u32 s91, s91, 0
	s_add_u32 s67, s67, 0x100
	s_addc_u32 s76, s76, 0
	s_cmp_gt_u32 s77, 13
	s_cbranch_scc0 .LBB0_828
	s_and_b64 vcc, exec, s[34:35]
	s_cbranch_vccz .LBB0_831
	s_barrier
.LBB0_831:
	s_and_b32 s32, s12, 1
	v_readlane_b32 s92, v254, 49
	v_readlane_b32 s93, v254, 50
	s_nop 0
	s_sub_i32 s4, s88, 32
	s_ashr_i32 s4, s4, 2
	s_add_i32 s4, s4, 1
	s_cmp_gt_i32 s88, 31
	s_cselect_b32 s4, s4, 0
	s_mul_hi_i32 s5, s4, 0x5800
	s_mulk_i32 s4, 0x5800
	s_add_u32 s4, s92, s4
	s_addc_u32 s5, s93, s5
	v_lshl_add_u32 v236, s88, 8, v170
	v_lshlrev_b32_e32 v236, 2, v236
	v_lshl_or_b32 v177, s66, 7, v172
	v_lshlrev_b32_e32 v177, 2, v177
	global_load_dword v210, v236, s[10:11] offset:0
	global_load_dword v211, v236, s[10:11] offset:64
	global_load_dword v212, v236, s[10:11] offset:128
	global_load_dword v213, v236, s[10:11] offset:192
	global_load_dword v214, v236, s[10:11] offset:512
	global_load_dword v215, v236, s[10:11] offset:576
	global_load_dword v216, v236, s[10:11] offset:640
	global_load_dword v217, v236, s[10:11] offset:704
	global_load_dwordx4 v[202:205], v177, s[4:5]
	global_load_dwordx4 v[206:209], v177, s[4:5] offset:16
	v_add_u32_e32 v226, 0x2c00, v177
	global_load_dwordx4 v[218:221], v226, s[4:5]
	global_load_dwordx4 v[222:225], v226, s[4:5] offset:16
	v_readlane_b32 s2, v254, 5
	v_readlane_b32 s3, v254, 6
	v_readlane_b32 s28, v254, 7
	v_readlane_b32 s29, v254, 8
	s_mul_i32 s76, s88, 0x160000
	s_lshl_b32 s67, s66, 8
	s_add_i32 s76, s76, s67
	s_add_i32 s76, s76, 0x9300000
	s_add_u32 s76, s76, s70
	s_addc_u32 s77, s71, 0
	v_mul_u32_u24_e32 v168, 0x1600, v170
	v_lshl_add_u32 v168, v172, 1, v168
	s_mov_b32 s57, 0x20800
	v_lshl_add_u32 v169, v172, 2, s57
	v_and_b32_e32 v237, 15, v170
	v_cmp_eq_u32_e64 s[78:79], 0, v237
	v_cmp_eq_u32_e64 s[80:81], 15, v237
	v_and_b32_e32 v231, 8, v237
	v_lshlrev_b32_e32 v231, 9, v231
	s_lshl_b32 s67, s32, 10
	v_add3_u32 v231, v231, v169, s67
	s_waitcnt vmcnt(4)
	v_fmamk_f32 v210, v210, 0x3a800000, v176
	v_fmamk_f32 v211, v211, 0x3a800000, v176
	v_fmamk_f32 v212, v212, 0x3a800000, v176
	v_fmamk_f32 v213, v213, 0x3a800000, v176
	v_fmamk_f32 v214, v214, 0x3a800000, v176
	v_fmamk_f32 v215, v215, 0x3a800000, v176
	v_fmamk_f32 v216, v216, 0x3a800000, v176
	v_fmamk_f32 v217, v217, 0x3a800000, v176
	s_mov_b32 s67, 0x800000
	v_mul_f32_e32 v226, 0x4b800000, v210
	v_mul_f32_e32 v227, 0x4b800000, v211
	v_mul_f32_e32 v228, 0x4b800000, v212
	v_mul_f32_e32 v229, 0x4b800000, v213
	v_mul_f32_e32 v232, 0x4b800000, v214
	v_mul_f32_e32 v233, 0x4b800000, v215
	v_mul_f32_e32 v234, 0x4b800000, v216
	v_mul_f32_e32 v235, 0x4b800000, v217
	v_cmp_gt_f32_e32 vcc, s67, v210
	s_nop 1
	v_cndmask_b32_e32 v210, v210, v226, vcc
	v_rsq_f32_e32 v210, v210
	s_nop 0
	v_mul_f32_e32 v226, 0x45800000, v210
	v_cndmask_b32_e32 v210, v210, v226, vcc
	v_cmp_gt_f32_e32 vcc, s67, v211
	s_nop 1
	v_cndmask_b32_e32 v211, v211, v227, vcc
	v_rsq_f32_e32 v211, v211
	s_nop 0
	v_mul_f32_e32 v227, 0x45800000, v211
	v_cndmask_b32_e32 v211, v211, v227, vcc
	v_cmp_gt_f32_e32 vcc, s67, v212
	s_nop 1
	v_cndmask_b32_e32 v212, v212, v228, vcc
	v_rsq_f32_e32 v212, v212
	s_nop 0
	v_mul_f32_e32 v228, 0x45800000, v212
	v_cndmask_b32_e32 v212, v212, v228, vcc
	v_cmp_gt_f32_e32 vcc, s67, v213
	s_nop 1
	v_cndmask_b32_e32 v213, v213, v229, vcc
	v_rsq_f32_e32 v213, v213
	s_nop 0
	v_mul_f32_e32 v229, 0x45800000, v213
	v_cndmask_b32_e32 v213, v213, v229, vcc
	v_cmp_gt_f32_e32 vcc, s67, v214
	s_nop 1
	v_cndmask_b32_e32 v214, v214, v232, vcc
	v_rsq_f32_e32 v214, v214
	s_nop 0
	v_mul_f32_e32 v232, 0x45800000, v214
	v_cndmask_b32_e32 v214, v214, v232, vcc
	v_cmp_gt_f32_e32 vcc, s67, v215
	s_nop 1
	v_cndmask_b32_e32 v215, v215, v233, vcc
	v_rsq_f32_e32 v215, v215
	s_nop 0
	v_mul_f32_e32 v233, 0x45800000, v215
	v_cndmask_b32_e32 v215, v215, v233, vcc
	v_cmp_gt_f32_e32 vcc, s67, v216
	s_nop 1
	v_cndmask_b32_e32 v216, v216, v234, vcc
	v_rsq_f32_e32 v216, v216
	s_nop 0
	v_mul_f32_e32 v234, 0x45800000, v216
	v_cndmask_b32_e32 v216, v216, v234, vcc
	v_cmp_gt_f32_e32 vcc, s67, v217
	s_nop 1
	v_cndmask_b32_e32 v217, v217, v235, vcc
	v_rsq_f32_e32 v217, v217
	s_nop 0
	v_mul_f32_e32 v235, 0x45800000, v217
	v_cndmask_b32_e32 v217, v217, v235, vcc
	s_waitcnt vmcnt(0)
	v_fma_f32 v140, v140, v210, v202
	v_fma_f32 v141, v141, v210, v203
	v_fma_f32 v142, v142, v210, v204
	v_fma_f32 v143, v143, v210, v205
	v_fma_f32 v136, v136, v210, v206
	v_fma_f32 v137, v137, v210, v207
	v_fma_f32 v138, v138, v210, v208
	v_fma_f32 v139, v139, v210, v209
	v_fma_f32 v120, v120, v210, v218
	v_fma_f32 v121, v121, v210, v219
	v_fma_f32 v122, v122, v210, v220
	v_fma_f32 v123, v123, v210, v221
	v_fma_f32 v112, v112, v210, v222
	v_fma_f32 v113, v113, v210, v223
	v_fma_f32 v114, v114, v210, v224
	v_fma_f32 v115, v115, v210, v225
	v_fma_f32 v108, v108, v211, v202
	v_fma_f32 v109, v109, v211, v203
	v_fma_f32 v110, v110, v211, v204
	v_fma_f32 v111, v111, v211, v205
	v_fma_f32 v104, v104, v211, v206
	v_fma_f32 v105, v105, v211, v207
	v_fma_f32 v106, v106, v211, v208
	v_fma_f32 v107, v107, v211, v209
	v_fma_f32 v100, v100, v211, v218
	v_fma_f32 v101, v101, v211, v219
	v_fma_f32 v102, v102, v211, v220
	v_fma_f32 v103, v103, v211, v221
	v_fma_f32 v96, v96, v211, v222
	v_fma_f32 v97, v97, v211, v223
	v_fma_f32 v98, v98, v211, v224
	v_fma_f32 v99, v99, v211, v225
	v_fma_f32 v92, v92, v212, v202
	v_fma_f32 v93, v93, v212, v203
	v_fma_f32 v94, v94, v212, v204
	v_fma_f32 v95, v95, v212, v205
	v_fma_f32 v88, v88, v212, v206
	v_fma_f32 v89, v89, v212, v207
	v_fma_f32 v90, v90, v212, v208
	v_fma_f32 v91, v91, v212, v209
	v_fma_f32 v84, v84, v212, v218
	v_fma_f32 v85, v85, v212, v219
	v_fma_f32 v86, v86, v212, v220
	v_fma_f32 v87, v87, v212, v221
	v_fma_f32 v80, v80, v212, v222
	v_fma_f32 v81, v81, v212, v223
	v_fma_f32 v82, v82, v212, v224
	v_fma_f32 v83, v83, v212, v225
	v_fma_f32 v76, v76, v213, v202
	v_fma_f32 v77, v77, v213, v203
	v_fma_f32 v78, v78, v213, v204
	v_fma_f32 v79, v79, v213, v205
	v_fma_f32 v72, v72, v213, v206
	v_fma_f32 v73, v73, v213, v207
	v_fma_f32 v74, v74, v213, v208
	v_fma_f32 v75, v75, v213, v209
	v_fma_f32 v68, v68, v213, v218
	v_fma_f32 v69, v69, v213, v219
	v_fma_f32 v70, v70, v213, v220
	v_fma_f32 v71, v71, v213, v221
	v_fma_f32 v64, v64, v213, v222
	v_fma_f32 v65, v65, v213, v223
	v_fma_f32 v66, v66, v213, v224
	v_fma_f32 v67, v67, v213, v225
	v_fma_f32 v60, v60, v214, v202
	v_fma_f32 v61, v61, v214, v203
	v_fma_f32 v62, v62, v214, v204
	v_fma_f32 v63, v63, v214, v205
	v_fma_f32 v56, v56, v214, v206
	v_fma_f32 v57, v57, v214, v207
	v_fma_f32 v58, v58, v214, v208
	v_fma_f32 v59, v59, v214, v209
	v_fma_f32 v52, v52, v214, v218
	v_fma_f32 v53, v53, v214, v219
	v_fma_f32 v54, v54, v214, v220
	v_fma_f32 v55, v55, v214, v221
	v_fma_f32 v48, v48, v214, v222
	v_fma_f32 v49, v49, v214, v223
	v_fma_f32 v50, v50, v214, v224
	v_fma_f32 v51, v51, v214, v225
	v_fma_f32 v44, v44, v215, v202
	v_fma_f32 v45, v45, v215, v203
	v_fma_f32 v46, v46, v215, v204
	v_fma_f32 v47, v47, v215, v205
	v_fma_f32 v40, v40, v215, v206
	v_fma_f32 v41, v41, v215, v207
	v_fma_f32 v42, v42, v215, v208
	v_fma_f32 v43, v43, v215, v209
	v_fma_f32 v36, v36, v215, v218
	v_fma_f32 v37, v37, v215, v219
	v_fma_f32 v38, v38, v215, v220
	v_fma_f32 v39, v39, v215, v221
	v_fma_f32 v32, v32, v215, v222
	v_fma_f32 v33, v33, v215, v223
	v_fma_f32 v34, v34, v215, v224
	v_fma_f32 v35, v35, v215, v225
	v_fma_f32 v28, v28, v216, v202
	v_fma_f32 v29, v29, v216, v203
	v_fma_f32 v30, v30, v216, v204
	v_fma_f32 v31, v31, v216, v205
	v_fma_f32 v24, v24, v216, v206
	v_fma_f32 v25, v25, v216, v207
	v_fma_f32 v26, v26, v216, v208
	v_fma_f32 v27, v27, v216, v209
	v_fma_f32 v20, v20, v216, v218
	v_fma_f32 v21, v21, v216, v219
	v_fma_f32 v22, v22, v216, v220
	v_fma_f32 v23, v23, v216, v221
	v_fma_f32 v16, v16, v216, v222
	v_fma_f32 v17, v17, v216, v223
	v_fma_f32 v18, v18, v216, v224
	v_fma_f32 v19, v19, v216, v225
	v_fma_f32 v12, v12, v217, v202
	v_fma_f32 v13, v13, v217, v203
	v_fma_f32 v14, v14, v217, v204
	v_fma_f32 v15, v15, v217, v205
	v_fma_f32 v8, v8, v217, v206
	v_fma_f32 v9, v9, v217, v207
	v_fma_f32 v10, v10, v217, v208
	v_fma_f32 v11, v11, v217, v209
	v_fma_f32 v4, v4, v217, v218
	v_fma_f32 v5, v5, v217, v219
	v_fma_f32 v6, v6, v217, v220
	v_fma_f32 v7, v7, v217, v221
	v_fma_f32 v0, v0, v217, v222
	v_fma_f32 v1, v1, v217, v223
	v_fma_f32 v2, v2, v217, v224
	v_fma_f32 v3, v3, v217, v225
	global_load_dwordx4 v[116:119], v177, s[2:3]
	v_add_u32_e32 v213, 0x5800, v177
	global_load_dwordx4 v[124:127], v213, s[2:3]
	v_add_u32_e32 v212, 0xb000, v177
	global_load_dwordx4 v[128:131], v212, s[2:3]
	global_load_dwordx4 v[132:135], v177, s[28:29]
	v_add_u32_e32 v212, 0x2c00, v177
	global_load_dwordx4 v[160:163], v212, s[2:3]
	v_add_u32_e32 v213, 0x8400, v177
	global_load_dwordx4 v[164:167], v213, s[2:3]
	v_add_u32_e32 v212, 0xdc00, v177
	global_load_dwordx4 v[178:181], v212, s[2:3]
	v_add_u32_e32 v213, 0x2c00, v177
	global_load_dwordx4 v[182:185], v213, s[28:29]
	v_mov_b32_e32 v214, 0
	v_mov_b32_e32 v215, 0
	v_mov_b32_e32 v216, 0
	v_mov_b32_e32 v217, 0
	s_lshl_b32 s100, s32, 12
	s_sub_i32 s100, 0x2000, s100
	s_mul_i32 s101, s32, 0x1400
	s_add_i32 s101, s101, 0xc00
	s_lshl_b32 s67, s32, 10
	s_add_i32 s98, s67, 5120
	s_add_i32 s99, s67, 1024
	s_mov_b64 s[90:91], exec
	s_mov_b64 exec, s[78:79]
	v_add_u32_e32 v250, s100, v169
	ds_write_b128 v250, v[140:143] offset:0
	ds_write_b128 v250, v[136:139] offset:16
	ds_write_b128 v250, v[120:123] offset:512
	ds_write_b128 v250, v[112:115] offset:528
	v_add_u32_e32 v250, s98, v169
	ds_write_b128 v250, v[60:63] offset:0
	ds_write_b128 v250, v[56:59] offset:16
	ds_write_b128 v250, v[52:55] offset:512
	ds_write_b128 v250, v[48:51] offset:528
	ds_write_b128 v169, v[214:217] offset:0
	ds_write_b128 v169, v[214:217] offset:16
	ds_write_b128 v169, v[214:217] offset:512
	ds_write_b128 v169, v[214:217] offset:528
	s_mov_b64 exec, s[80:81]
	v_add_u32_e32 v251, s99, v169
	ds_write_b128 v251, v[76:79] offset:0
	ds_write_b128 v251, v[72:75] offset:16
	ds_write_b128 v251, v[68:71] offset:512
	ds_write_b128 v251, v[64:67] offset:528
	v_add_u32_e32 v251, s101, v169
	ds_write_b128 v251, v[12:15] offset:0
	ds_write_b128 v251, v[8:11] offset:16
	ds_write_b128 v251, v[4:7] offset:512
	ds_write_b128 v251, v[0:3] offset:528
	ds_write_b128 v169, v[214:217] offset:7168
	ds_write_b128 v169, v[214:217] offset:7184
	ds_write_b128 v169, v[214:217] offset:7680
	ds_write_b128 v169, v[214:217] offset:7696
	s_mov_b64 exec, s[90:91]
	s_waitcnt lgkmcnt(0)
	s_barrier
	ds_read_b128 v[186:189], v231 offset:0
	ds_read_b128 v[190:193], v231 offset:512
	ds_read_b128 v[194:197], v231 offset:2048
	ds_read_b128 v[198:201], v231 offset:2560
	s_waitcnt vmcnt(0)
	v_cndmask_b32_e64 v218, 0, v116, s[78:79]
	v_cndmask_b32_e64 v222, 0, v128, s[80:81]
	v_cndmask_b32_e64 v219, 0, v117, s[78:79]
	v_cndmask_b32_e64 v223, 0, v129, s[80:81]
	v_cndmask_b32_e64 v220, 0, v118, s[78:79]
	v_cndmask_b32_e64 v224, 0, v130, s[80:81]
	v_cndmask_b32_e64 v221, 0, v119, s[78:79]
	v_cndmask_b32_e64 v225, 0, v131, s[80:81]
	v_cndmask_b32_e64 v226, 0, v160, s[78:79]
	v_cndmask_b32_e64 v232, 0, v178, s[80:81]
	v_cndmask_b32_e64 v227, 0, v161, s[78:79]
	v_cndmask_b32_e64 v233, 0, v179, s[80:81]
	v_cndmask_b32_e64 v228, 0, v162, s[78:79]
	v_cndmask_b32_e64 v234, 0, v180, s[80:81]
	v_cndmask_b32_e64 v229, 0, v163, s[78:79]
	v_cndmask_b32_e64 v235, 0, v181, s[80:81]
	s_waitcnt lgkmcnt(0)
	s_nop 1
	v_fma_f32 v202, v124, v140, v132
	v_fma_f32 v203, v125, v141, v133
	v_fma_f32 v204, v126, v142, v134
	v_fma_f32 v205, v127, v143, v135
	v_fmac_f32_dpp v202, v140, v116 row_shr:1 row_mask:0xf bank_mask:0xf
	v_fmac_f32_dpp v203, v141, v117 row_shr:1 row_mask:0xf bank_mask:0xf
	v_fmac_f32_dpp v204, v142, v118 row_shr:1 row_mask:0xf bank_mask:0xf
	v_fmac_f32_dpp v205, v143, v119 row_shr:1 row_mask:0xf bank_mask:0xf
	v_fmac_f32_e32 v202, v186, v218
	v_fmac_f32_e32 v203, v187, v219
	v_fmac_f32_e32 v204, v188, v220
	v_fmac_f32_e32 v205, v189, v221
	v_fmac_f32_dpp v202, v140, v128 row_shl:1 row_mask:0xf bank_mask:0xf
	v_fmac_f32_dpp v203, v141, v129 row_shl:1 row_mask:0xf bank_mask:0xf
	v_fmac_f32_dpp v204, v142, v130 row_shl:1 row_mask:0xf bank_mask:0xf
	v_fmac_f32_dpp v205, v143, v131 row_shl:1 row_mask:0xf bank_mask:0xf
	v_fmac_f32_dpp v202, v108, v222 row_ror:15 row_mask:0xf bank_mask:0xf
	v_fmac_f32_dpp v203, v109, v223 row_ror:15 row_mask:0xf bank_mask:0xf
	v_fmac_f32_dpp v204, v110, v224 row_ror:15 row_mask:0xf bank_mask:0xf
	v_fmac_f32_dpp v205, v111, v225 row_ror:15 row_mask:0xf bank_mask:0xf
	v_fma_f32 v206, v164, v120, v182
	v_fma_f32 v207, v165, v121, v183
	v_fma_f32 v208, v166, v122, v184
	v_fma_f32 v209, v167, v123, v185
	v_fmac_f32_dpp v206, v120, v160 row_shr:1 row_mask:0xf bank_mask:0xf
	v_fmac_f32_dpp v207, v121, v161 row_shr:1 row_mask:0xf bank_mask:0xf
	v_fmac_f32_dpp v208, v122, v162 row_shr:1 row_mask:0xf bank_mask:0xf
	v_fmac_f32_dpp v209, v123, v163 row_shr:1 row_mask:0xf bank_mask:0xf
	v_fmac_f32_e32 v206, v190, v226
	v_fmac_f32_e32 v207, v191, v227
	v_fmac_f32_e32 v208, v192, v228
	v_fmac_f32_e32 v209, v193, v229
	v_fmac_f32_dpp v206, v120, v178 row_shl:1 row_mask:0xf bank_mask:0xf
	v_fmac_f32_dpp v207, v121, v179 row_shl:1 row_mask:0xf bank_mask:0xf
	v_fmac_f32_dpp v208, v122, v180 row_shl:1 row_mask:0xf bank_mask:0xf
	v_fmac_f32_dpp v209, v123, v181 row_shl:1 row_mask:0xf bank_mask:0xf
	v_fmac_f32_dpp v206, v100, v232 row_ror:15 row_mask:0xf bank_mask:0xf
	v_fmac_f32_dpp v207, v101, v233 row_ror:15 row_mask:0xf bank_mask:0xf
	v_fmac_f32_dpp v208, v102, v234 row_ror:15 row_mask:0xf bank_mask:0xf
	v_fmac_f32_dpp v209, v103, v235 row_ror:15 row_mask:0xf bank_mask:0xf
	v_mul_f32_e32 v210, 0xbfb8aa3b, v202
	v_mul_f32_e32 v211, 0xbfb8aa3b, v203
	v_mul_f32_e32 v212, 0xbfb8aa3b, v204
	v_mul_f32_e32 v213, 0xbfb8aa3b, v205
	v_exp_f32_e32 v210, v210
	v_exp_f32_e32 v211, v211
	v_exp_f32_e32 v212, v212
	v_exp_f32_e32 v213, v213
	v_add_f32_e32 v210, 1.0, v210
	v_add_f32_e32 v211, 1.0, v211
	v_add_f32_e32 v212, 1.0, v212
	v_add_f32_e32 v213, 1.0, v213
	v_rcp_f32_e32 v210, v210
	v_rcp_f32_e32 v211, v211
	v_rcp_f32_e32 v212, v212
	v_rcp_f32_e32 v213, v213
	v_mul_f32_e32 v202, v202, v210
	v_mul_f32_e32 v203, v203, v211
	v_mul_f32_e32 v204, v204, v212
	v_mul_f32_e32 v205, v205, v213
	v_mul_f32_e32 v202, v202, v206
	v_mul_f32_e32 v203, v203, v207
	v_mul_f32_e32 v204, v204, v208
	v_mul_f32_e32 v205, v205, v209
	v_cvt_pk_bf16_f32 v236, v202, v203
	v_cvt_pk_bf16_f32 v237, v204, v205
	v_fma_f32 v202, v124, v108, v132
	v_fma_f32 v203, v125, v109, v133
	v_fma_f32 v204, v126, v110, v134
	v_fma_f32 v205, v127, v111, v135
	v_fmac_f32_dpp v202, v108, v116 row_shr:1 row_mask:0xf bank_mask:0xf
	v_fmac_f32_dpp v203, v109, v117 row_shr:1 row_mask:0xf bank_mask:0xf
	v_fmac_f32_dpp v204, v110, v118 row_shr:1 row_mask:0xf bank_mask:0xf
	v_fmac_f32_dpp v205, v111, v119 row_shr:1 row_mask:0xf bank_mask:0xf
	v_fmac_f32_dpp v202, v140, v218 row_ror:1 row_mask:0xf bank_mask:0xf
	v_fmac_f32_dpp v203, v141, v219 row_ror:1 row_mask:0xf bank_mask:0xf
	v_fmac_f32_dpp v204, v142, v220 row_ror:1 row_mask:0xf bank_mask:0xf
	v_fmac_f32_dpp v205, v143, v221 row_ror:1 row_mask:0xf bank_mask:0xf
	v_fmac_f32_dpp v202, v108, v128 row_shl:1 row_mask:0xf bank_mask:0xf
	v_fmac_f32_dpp v203, v109, v129 row_shl:1 row_mask:0xf bank_mask:0xf
	v_fmac_f32_dpp v204, v110, v130 row_shl:1 row_mask:0xf bank_mask:0xf
	v_fmac_f32_dpp v205, v111, v131 row_shl:1 row_mask:0xf bank_mask:0xf
	v_fmac_f32_dpp v202, v92, v222 row_ror:15 row_mask:0xf bank_mask:0xf
	v_fmac_f32_dpp v203, v93, v223 row_ror:15 row_mask:0xf bank_mask:0xf
	v_fmac_f32_dpp v204, v94, v224 row_ror:15 row_mask:0xf bank_mask:0xf
	v_fmac_f32_dpp v205, v95, v225 row_ror:15 row_mask:0xf bank_mask:0xf
	v_fma_f32 v206, v164, v100, v182
	v_fma_f32 v207, v165, v101, v183
	v_fma_f32 v208, v166, v102, v184
	v_fma_f32 v209, v167, v103, v185
	v_fmac_f32_dpp v206, v100, v160 row_shr:1 row_mask:0xf bank_mask:0xf
	v_fmac_f32_dpp v207, v101, v161 row_shr:1 row_mask:0xf bank_mask:0xf
	v_fmac_f32_dpp v208, v102, v162 row_shr:1 row_mask:0xf bank_mask:0xf
	v_fmac_f32_dpp v209, v103, v163 row_shr:1 row_mask:0xf bank_mask:0xf
	v_fmac_f32_dpp v206, v120, v226 row_ror:1 row_mask:0xf bank_mask:0xf
	v_fmac_f32_dpp v207, v121, v227 row_ror:1 row_mask:0xf bank_mask:0xf
	v_fmac_f32_dpp v208, v122, v228 row_ror:1 row_mask:0xf bank_mask:0xf
	v_fmac_f32_dpp v209, v123, v229 row_ror:1 row_mask:0xf bank_mask:0xf
	v_fmac_f32_dpp v206, v100, v178 row_shl:1 row_mask:0xf bank_mask:0xf
	v_fmac_f32_dpp v207, v101, v179 row_shl:1 row_mask:0xf bank_mask:0xf
	v_fmac_f32_dpp v208, v102, v180 row_shl:1 row_mask:0xf bank_mask:0xf
	v_fmac_f32_dpp v209, v103, v181 row_shl:1 row_mask:0xf bank_mask:0xf
	v_fmac_f32_dpp v206, v84, v232 row_ror:15 row_mask:0xf bank_mask:0xf
	v_fmac_f32_dpp v207, v85, v233 row_ror:15 row_mask:0xf bank_mask:0xf
	v_fmac_f32_dpp v208, v86, v234 row_ror:15 row_mask:0xf bank_mask:0xf
	v_fmac_f32_dpp v209, v87, v235 row_ror:15 row_mask:0xf bank_mask:0xf
	v_mul_f32_e32 v210, 0xbfb8aa3b, v202
	v_mul_f32_e32 v211, 0xbfb8aa3b, v203
	v_mul_f32_e32 v212, 0xbfb8aa3b, v204
	v_mul_f32_e32 v213, 0xbfb8aa3b, v205
	v_exp_f32_e32 v210, v210
	v_exp_f32_e32 v211, v211
	v_exp_f32_e32 v212, v212
	v_exp_f32_e32 v213, v213
	v_add_f32_e32 v210, 1.0, v210
	v_add_f32_e32 v211, 1.0, v211
	v_add_f32_e32 v212, 1.0, v212
	v_add_f32_e32 v213, 1.0, v213
	v_rcp_f32_e32 v210, v210
	v_rcp_f32_e32 v211, v211
	v_rcp_f32_e32 v212, v212
	v_rcp_f32_e32 v213, v213
	v_mul_f32_e32 v202, v202, v210
	v_mul_f32_e32 v203, v203, v211
	v_mul_f32_e32 v204, v204, v212
	v_mul_f32_e32 v205, v205, v213
	v_mul_f32_e32 v202, v202, v206
	v_mul_f32_e32 v203, v203, v207
	v_mul_f32_e32 v204, v204, v208
	v_mul_f32_e32 v205, v205, v209
	v_cvt_pk_bf16_f32 v238, v202, v203
	v_cvt_pk_bf16_f32 v239, v204, v205
	v_fma_f32 v202, v124, v92, v132
	v_fma_f32 v203, v125, v93, v133
	v_fma_f32 v204, v126, v94, v134
	v_fma_f32 v205, v127, v95, v135
	v_fmac_f32_dpp v202, v92, v116 row_shr:1 row_mask:0xf bank_mask:0xf
	v_fmac_f32_dpp v203, v93, v117 row_shr:1 row_mask:0xf bank_mask:0xf
	v_fmac_f32_dpp v204, v94, v118 row_shr:1 row_mask:0xf bank_mask:0xf
	v_fmac_f32_dpp v205, v95, v119 row_shr:1 row_mask:0xf bank_mask:0xf
	v_fmac_f32_dpp v202, v108, v218 row_ror:1 row_mask:0xf bank_mask:0xf
	v_fmac_f32_dpp v203, v109, v219 row_ror:1 row_mask:0xf bank_mask:0xf
	v_fmac_f32_dpp v204, v110, v220 row_ror:1 row_mask:0xf bank_mask:0xf
	v_fmac_f32_dpp v205, v111, v221 row_ror:1 row_mask:0xf bank_mask:0xf
	v_fmac_f32_dpp v202, v92, v128 row_shl:1 row_mask:0xf bank_mask:0xf
	v_fmac_f32_dpp v203, v93, v129 row_shl:1 row_mask:0xf bank_mask:0xf
	v_fmac_f32_dpp v204, v94, v130 row_shl:1 row_mask:0xf bank_mask:0xf
	v_fmac_f32_dpp v205, v95, v131 row_shl:1 row_mask:0xf bank_mask:0xf
	v_fmac_f32_dpp v202, v76, v222 row_ror:15 row_mask:0xf bank_mask:0xf
	v_fmac_f32_dpp v203, v77, v223 row_ror:15 row_mask:0xf bank_mask:0xf
	v_fmac_f32_dpp v204, v78, v224 row_ror:15 row_mask:0xf bank_mask:0xf
	v_fmac_f32_dpp v205, v79, v225 row_ror:15 row_mask:0xf bank_mask:0xf
	v_fma_f32 v206, v164, v84, v182
	v_fma_f32 v207, v165, v85, v183
	v_fma_f32 v208, v166, v86, v184
	v_fma_f32 v209, v167, v87, v185
	v_fmac_f32_dpp v206, v84, v160 row_shr:1 row_mask:0xf bank_mask:0xf
	v_fmac_f32_dpp v207, v85, v161 row_shr:1 row_mask:0xf bank_mask:0xf
	v_fmac_f32_dpp v208, v86, v162 row_shr:1 row_mask:0xf bank_mask:0xf
	v_fmac_f32_dpp v209, v87, v163 row_shr:1 row_mask:0xf bank_mask:0xf
	v_fmac_f32_dpp v206, v100, v226 row_ror:1 row_mask:0xf bank_mask:0xf
	v_fmac_f32_dpp v207, v101, v227 row_ror:1 row_mask:0xf bank_mask:0xf
	v_fmac_f32_dpp v208, v102, v228 row_ror:1 row_mask:0xf bank_mask:0xf
	v_fmac_f32_dpp v209, v103, v229 row_ror:1 row_mask:0xf bank_mask:0xf
	v_fmac_f32_dpp v206, v84, v178 row_shl:1 row_mask:0xf bank_mask:0xf
	v_fmac_f32_dpp v207, v85, v179 row_shl:1 row_mask:0xf bank_mask:0xf
	v_fmac_f32_dpp v208, v86, v180 row_shl:1 row_mask:0xf bank_mask:0xf
	v_fmac_f32_dpp v209, v87, v181 row_shl:1 row_mask:0xf bank_mask:0xf
	v_fmac_f32_dpp v206, v68, v232 row_ror:15 row_mask:0xf bank_mask:0xf
	v_fmac_f32_dpp v207, v69, v233 row_ror:15 row_mask:0xf bank_mask:0xf
	v_fmac_f32_dpp v208, v70, v234 row_ror:15 row_mask:0xf bank_mask:0xf
	v_fmac_f32_dpp v209, v71, v235 row_ror:15 row_mask:0xf bank_mask:0xf
	v_mul_f32_e32 v210, 0xbfb8aa3b, v202
	v_mul_f32_e32 v211, 0xbfb8aa3b, v203
	v_mul_f32_e32 v212, 0xbfb8aa3b, v204
	v_mul_f32_e32 v213, 0xbfb8aa3b, v205
	v_exp_f32_e32 v210, v210
	v_exp_f32_e32 v211, v211
	v_exp_f32_e32 v212, v212
	v_exp_f32_e32 v213, v213
	v_add_f32_e32 v210, 1.0, v210
	v_add_f32_e32 v211, 1.0, v211
	v_add_f32_e32 v212, 1.0, v212
	v_add_f32_e32 v213, 1.0, v213
	v_rcp_f32_e32 v210, v210
	v_rcp_f32_e32 v211, v211
	v_rcp_f32_e32 v212, v212
	v_rcp_f32_e32 v213, v213
	v_mul_f32_e32 v202, v202, v210
	v_mul_f32_e32 v203, v203, v211
	v_mul_f32_e32 v204, v204, v212
	v_mul_f32_e32 v205, v205, v213
	v_mul_f32_e32 v202, v202, v206
	v_mul_f32_e32 v203, v203, v207
	v_mul_f32_e32 v204, v204, v208
	v_mul_f32_e32 v205, v205, v209
	v_cvt_pk_bf16_f32 v240, v202, v203
	v_cvt_pk_bf16_f32 v241, v204, v205
	v_fma_f32 v202, v124, v76, v132
	v_fma_f32 v203, v125, v77, v133
	v_fma_f32 v204, v126, v78, v134
	v_fma_f32 v205, v127, v79, v135
	v_fmac_f32_dpp v202, v76, v116 row_shr:1 row_mask:0xf bank_mask:0xf
	v_fmac_f32_dpp v203, v77, v117 row_shr:1 row_mask:0xf bank_mask:0xf
	v_fmac_f32_dpp v204, v78, v118 row_shr:1 row_mask:0xf bank_mask:0xf
	v_fmac_f32_dpp v205, v79, v119 row_shr:1 row_mask:0xf bank_mask:0xf
	v_fmac_f32_dpp v202, v92, v218 row_ror:1 row_mask:0xf bank_mask:0xf
	v_fmac_f32_dpp v203, v93, v219 row_ror:1 row_mask:0xf bank_mask:0xf
	v_fmac_f32_dpp v204, v94, v220 row_ror:1 row_mask:0xf bank_mask:0xf
	v_fmac_f32_dpp v205, v95, v221 row_ror:1 row_mask:0xf bank_mask:0xf
	v_fmac_f32_dpp v202, v76, v128 row_shl:1 row_mask:0xf bank_mask:0xf
	v_fmac_f32_dpp v203, v77, v129 row_shl:1 row_mask:0xf bank_mask:0xf
	v_fmac_f32_dpp v204, v78, v130 row_shl:1 row_mask:0xf bank_mask:0xf
	v_fmac_f32_dpp v205, v79, v131 row_shl:1 row_mask:0xf bank_mask:0xf
	v_fmac_f32_e32 v202, v186, v222
	v_fmac_f32_e32 v203, v187, v223
	v_fmac_f32_e32 v204, v188, v224
	v_fmac_f32_e32 v205, v189, v225
	v_fma_f32 v206, v164, v68, v182
	v_fma_f32 v207, v165, v69, v183
	v_fma_f32 v208, v166, v70, v184
	v_fma_f32 v209, v167, v71, v185
	v_fmac_f32_dpp v206, v68, v160 row_shr:1 row_mask:0xf bank_mask:0xf
	v_fmac_f32_dpp v207, v69, v161 row_shr:1 row_mask:0xf bank_mask:0xf
	v_fmac_f32_dpp v208, v70, v162 row_shr:1 row_mask:0xf bank_mask:0xf
	v_fmac_f32_dpp v209, v71, v163 row_shr:1 row_mask:0xf bank_mask:0xf
	v_fmac_f32_dpp v206, v84, v226 row_ror:1 row_mask:0xf bank_mask:0xf
	v_fmac_f32_dpp v207, v85, v227 row_ror:1 row_mask:0xf bank_mask:0xf
	v_fmac_f32_dpp v208, v86, v228 row_ror:1 row_mask:0xf bank_mask:0xf
	v_fmac_f32_dpp v209, v87, v229 row_ror:1 row_mask:0xf bank_mask:0xf
	v_fmac_f32_dpp v206, v68, v178 row_shl:1 row_mask:0xf bank_mask:0xf
	v_fmac_f32_dpp v207, v69, v179 row_shl:1 row_mask:0xf bank_mask:0xf
	v_fmac_f32_dpp v208, v70, v180 row_shl:1 row_mask:0xf bank_mask:0xf
	v_fmac_f32_dpp v209, v71, v181 row_shl:1 row_mask:0xf bank_mask:0xf
	v_fmac_f32_e32 v206, v190, v232
	v_fmac_f32_e32 v207, v191, v233
	v_fmac_f32_e32 v208, v192, v234
	v_fmac_f32_e32 v209, v193, v235
	v_mul_f32_e32 v210, 0xbfb8aa3b, v202
	v_mul_f32_e32 v211, 0xbfb8aa3b, v203
	v_mul_f32_e32 v212, 0xbfb8aa3b, v204
	v_mul_f32_e32 v213, 0xbfb8aa3b, v205
	v_exp_f32_e32 v210, v210
	v_exp_f32_e32 v211, v211
	v_exp_f32_e32 v212, v212
	v_exp_f32_e32 v213, v213
	v_add_f32_e32 v210, 1.0, v210
	v_add_f32_e32 v211, 1.0, v211
	v_add_f32_e32 v212, 1.0, v212
	v_add_f32_e32 v213, 1.0, v213
	v_rcp_f32_e32 v210, v210
	v_rcp_f32_e32 v211, v211
	v_rcp_f32_e32 v212, v212
	v_rcp_f32_e32 v213, v213
	v_mul_f32_e32 v202, v202, v210
	v_mul_f32_e32 v203, v203, v211
	v_mul_f32_e32 v204, v204, v212
	v_mul_f32_e32 v205, v205, v213
	v_mul_f32_e32 v202, v202, v206
	v_mul_f32_e32 v203, v203, v207
	v_mul_f32_e32 v204, v204, v208
	v_mul_f32_e32 v205, v205, v209
	v_cvt_pk_bf16_f32 v242, v202, v203
	v_cvt_pk_bf16_f32 v243, v204, v205
	v_fma_f32 v202, v124, v60, v132
	v_fma_f32 v203, v125, v61, v133
	v_fma_f32 v204, v126, v62, v134
	v_fma_f32 v205, v127, v63, v135
	v_fmac_f32_dpp v202, v60, v116 row_shr:1 row_mask:0xf bank_mask:0xf
	v_fmac_f32_dpp v203, v61, v117 row_shr:1 row_mask:0xf bank_mask:0xf
	v_fmac_f32_dpp v204, v62, v118 row_shr:1 row_mask:0xf bank_mask:0xf
	v_fmac_f32_dpp v205, v63, v119 row_shr:1 row_mask:0xf bank_mask:0xf
	v_fmac_f32_e32 v202, v194, v218
	v_fmac_f32_e32 v203, v195, v219
	v_fmac_f32_e32 v204, v196, v220
	v_fmac_f32_e32 v205, v197, v221
	v_fmac_f32_dpp v202, v60, v128 row_shl:1 row_mask:0xf bank_mask:0xf
	v_fmac_f32_dpp v203, v61, v129 row_shl:1 row_mask:0xf bank_mask:0xf
	v_fmac_f32_dpp v204, v62, v130 row_shl:1 row_mask:0xf bank_mask:0xf
	v_fmac_f32_dpp v205, v63, v131 row_shl:1 row_mask:0xf bank_mask:0xf
	v_fmac_f32_dpp v202, v44, v222 row_ror:15 row_mask:0xf bank_mask:0xf
	v_fmac_f32_dpp v203, v45, v223 row_ror:15 row_mask:0xf bank_mask:0xf
	v_fmac_f32_dpp v204, v46, v224 row_ror:15 row_mask:0xf bank_mask:0xf
	v_fmac_f32_dpp v205, v47, v225 row_ror:15 row_mask:0xf bank_mask:0xf
	v_fma_f32 v206, v164, v52, v182
	v_fma_f32 v207, v165, v53, v183
	v_fma_f32 v208, v166, v54, v184
	v_fma_f32 v209, v167, v55, v185
	v_fmac_f32_dpp v206, v52, v160 row_shr:1 row_mask:0xf bank_mask:0xf
	v_fmac_f32_dpp v207, v53, v161 row_shr:1 row_mask:0xf bank_mask:0xf
	v_fmac_f32_dpp v208, v54, v162 row_shr:1 row_mask:0xf bank_mask:0xf
	v_fmac_f32_dpp v209, v55, v163 row_shr:1 row_mask:0xf bank_mask:0xf
	v_fmac_f32_e32 v206, v198, v226
	v_fmac_f32_e32 v207, v199, v227
	v_fmac_f32_e32 v208, v200, v228
	v_fmac_f32_e32 v209, v201, v229
	v_fmac_f32_dpp v206, v52, v178 row_shl:1 row_mask:0xf bank_mask:0xf
	v_fmac_f32_dpp v207, v53, v179 row_shl:1 row_mask:0xf bank_mask:0xf
	v_fmac_f32_dpp v208, v54, v180 row_shl:1 row_mask:0xf bank_mask:0xf
	v_fmac_f32_dpp v209, v55, v181 row_shl:1 row_mask:0xf bank_mask:0xf
	v_fmac_f32_dpp v206, v36, v232 row_ror:15 row_mask:0xf bank_mask:0xf
	v_fmac_f32_dpp v207, v37, v233 row_ror:15 row_mask:0xf bank_mask:0xf
	v_fmac_f32_dpp v208, v38, v234 row_ror:15 row_mask:0xf bank_mask:0xf
	v_fmac_f32_dpp v209, v39, v235 row_ror:15 row_mask:0xf bank_mask:0xf
	v_mul_f32_e32 v210, 0xbfb8aa3b, v202
	v_mul_f32_e32 v211, 0xbfb8aa3b, v203
	v_mul_f32_e32 v212, 0xbfb8aa3b, v204
	v_mul_f32_e32 v213, 0xbfb8aa3b, v205
	v_exp_f32_e32 v210, v210
	v_exp_f32_e32 v211, v211
	v_exp_f32_e32 v212, v212
	v_exp_f32_e32 v213, v213
	v_add_f32_e32 v210, 1.0, v210
	v_add_f32_e32 v211, 1.0, v211
	v_add_f32_e32 v212, 1.0, v212
	v_add_f32_e32 v213, 1.0, v213
	v_rcp_f32_e32 v210, v210
	v_rcp_f32_e32 v211, v211
	v_rcp_f32_e32 v212, v212
	v_rcp_f32_e32 v213, v213
	v_mul_f32_e32 v202, v202, v210
	v_mul_f32_e32 v203, v203, v211
	v_mul_f32_e32 v204, v204, v212
	v_mul_f32_e32 v205, v205, v213
	v_mul_f32_e32 v202, v202, v206
	v_mul_f32_e32 v203, v203, v207
	v_mul_f32_e32 v204, v204, v208
	v_mul_f32_e32 v205, v205, v209
	v_cvt_pk_bf16_f32 v244, v202, v203
	v_cvt_pk_bf16_f32 v245, v204, v205
	v_fma_f32 v202, v124, v44, v132
	v_fma_f32 v203, v125, v45, v133
	v_fma_f32 v204, v126, v46, v134
	v_fma_f32 v205, v127, v47, v135
	v_fmac_f32_dpp v202, v44, v116 row_shr:1 row_mask:0xf bank_mask:0xf
	v_fmac_f32_dpp v203, v45, v117 row_shr:1 row_mask:0xf bank_mask:0xf
	v_fmac_f32_dpp v204, v46, v118 row_shr:1 row_mask:0xf bank_mask:0xf
	v_fmac_f32_dpp v205, v47, v119 row_shr:1 row_mask:0xf bank_mask:0xf
	v_fmac_f32_dpp v202, v60, v218 row_ror:1 row_mask:0xf bank_mask:0xf
	v_fmac_f32_dpp v203, v61, v219 row_ror:1 row_mask:0xf bank_mask:0xf
	v_fmac_f32_dpp v204, v62, v220 row_ror:1 row_mask:0xf bank_mask:0xf
	v_fmac_f32_dpp v205, v63, v221 row_ror:1 row_mask:0xf bank_mask:0xf
	v_fmac_f32_dpp v202, v44, v128 row_shl:1 row_mask:0xf bank_mask:0xf
	v_fmac_f32_dpp v203, v45, v129 row_shl:1 row_mask:0xf bank_mask:0xf
	v_fmac_f32_dpp v204, v46, v130 row_shl:1 row_mask:0xf bank_mask:0xf
	v_fmac_f32_dpp v205, v47, v131 row_shl:1 row_mask:0xf bank_mask:0xf
	v_fmac_f32_dpp v202, v28, v222 row_ror:15 row_mask:0xf bank_mask:0xf
	v_fmac_f32_dpp v203, v29, v223 row_ror:15 row_mask:0xf bank_mask:0xf
	v_fmac_f32_dpp v204, v30, v224 row_ror:15 row_mask:0xf bank_mask:0xf
	v_fmac_f32_dpp v205, v31, v225 row_ror:15 row_mask:0xf bank_mask:0xf
	v_fma_f32 v206, v164, v36, v182
	v_fma_f32 v207, v165, v37, v183
	v_fma_f32 v208, v166, v38, v184
	v_fma_f32 v209, v167, v39, v185
	v_fmac_f32_dpp v206, v36, v160 row_shr:1 row_mask:0xf bank_mask:0xf
	v_fmac_f32_dpp v207, v37, v161 row_shr:1 row_mask:0xf bank_mask:0xf
	v_fmac_f32_dpp v208, v38, v162 row_shr:1 row_mask:0xf bank_mask:0xf
	v_fmac_f32_dpp v209, v39, v163 row_shr:1 row_mask:0xf bank_mask:0xf
	v_fmac_f32_dpp v206, v52, v226 row_ror:1 row_mask:0xf bank_mask:0xf
	v_fmac_f32_dpp v207, v53, v227 row_ror:1 row_mask:0xf bank_mask:0xf
	v_fmac_f32_dpp v208, v54, v228 row_ror:1 row_mask:0xf bank_mask:0xf
	v_fmac_f32_dpp v209, v55, v229 row_ror:1 row_mask:0xf bank_mask:0xf
	v_fmac_f32_dpp v206, v36, v178 row_shl:1 row_mask:0xf bank_mask:0xf
	v_fmac_f32_dpp v207, v37, v179 row_shl:1 row_mask:0xf bank_mask:0xf
	v_fmac_f32_dpp v208, v38, v180 row_shl:1 row_mask:0xf bank_mask:0xf
	v_fmac_f32_dpp v209, v39, v181 row_shl:1 row_mask:0xf bank_mask:0xf
	v_fmac_f32_dpp v206, v20, v232 row_ror:15 row_mask:0xf bank_mask:0xf
	v_fmac_f32_dpp v207, v21, v233 row_ror:15 row_mask:0xf bank_mask:0xf
	v_fmac_f32_dpp v208, v22, v234 row_ror:15 row_mask:0xf bank_mask:0xf
	v_fmac_f32_dpp v209, v23, v235 row_ror:15 row_mask:0xf bank_mask:0xf
	v_mul_f32_e32 v210, 0xbfb8aa3b, v202
	v_mul_f32_e32 v211, 0xbfb8aa3b, v203
	v_mul_f32_e32 v212, 0xbfb8aa3b, v204
	v_mul_f32_e32 v213, 0xbfb8aa3b, v205
	v_exp_f32_e32 v210, v210
	v_exp_f32_e32 v211, v211
	v_exp_f32_e32 v212, v212
	v_exp_f32_e32 v213, v213
	v_add_f32_e32 v210, 1.0, v210
	v_add_f32_e32 v211, 1.0, v211
	v_add_f32_e32 v212, 1.0, v212
	v_add_f32_e32 v213, 1.0, v213
	v_rcp_f32_e32 v210, v210
	v_rcp_f32_e32 v211, v211
	v_rcp_f32_e32 v212, v212
	v_rcp_f32_e32 v213, v213
	v_mul_f32_e32 v202, v202, v210
	v_mul_f32_e32 v203, v203, v211
	v_mul_f32_e32 v204, v204, v212
	v_mul_f32_e32 v205, v205, v213
	v_mul_f32_e32 v202, v202, v206
	v_mul_f32_e32 v203, v203, v207
	v_mul_f32_e32 v204, v204, v208
	v_mul_f32_e32 v205, v205, v209
	v_cvt_pk_bf16_f32 v246, v202, v203
	v_cvt_pk_bf16_f32 v247, v204, v205
	v_fma_f32 v202, v124, v28, v132
	v_fma_f32 v203, v125, v29, v133
	v_fma_f32 v204, v126, v30, v134
	v_fma_f32 v205, v127, v31, v135
	v_fmac_f32_dpp v202, v28, v116 row_shr:1 row_mask:0xf bank_mask:0xf
	v_fmac_f32_dpp v203, v29, v117 row_shr:1 row_mask:0xf bank_mask:0xf
	v_fmac_f32_dpp v204, v30, v118 row_shr:1 row_mask:0xf bank_mask:0xf
	v_fmac_f32_dpp v205, v31, v119 row_shr:1 row_mask:0xf bank_mask:0xf
	v_fmac_f32_dpp v202, v44, v218 row_ror:1 row_mask:0xf bank_mask:0xf
	v_fmac_f32_dpp v203, v45, v219 row_ror:1 row_mask:0xf bank_mask:0xf
	v_fmac_f32_dpp v204, v46, v220 row_ror:1 row_mask:0xf bank_mask:0xf
	v_fmac_f32_dpp v205, v47, v221 row_ror:1 row_mask:0xf bank_mask:0xf
	v_fmac_f32_dpp v202, v28, v128 row_shl:1 row_mask:0xf bank_mask:0xf
	v_fmac_f32_dpp v203, v29, v129 row_shl:1 row_mask:0xf bank_mask:0xf
	v_fmac_f32_dpp v204, v30, v130 row_shl:1 row_mask:0xf bank_mask:0xf
	v_fmac_f32_dpp v205, v31, v131 row_shl:1 row_mask:0xf bank_mask:0xf
	v_fmac_f32_dpp v202, v12, v222 row_ror:15 row_mask:0xf bank_mask:0xf
	v_fmac_f32_dpp v203, v13, v223 row_ror:15 row_mask:0xf bank_mask:0xf
	v_fmac_f32_dpp v204, v14, v224 row_ror:15 row_mask:0xf bank_mask:0xf
	v_fmac_f32_dpp v205, v15, v225 row_ror:15 row_mask:0xf bank_mask:0xf
	v_fma_f32 v206, v164, v20, v182
	v_fma_f32 v207, v165, v21, v183
	v_fma_f32 v208, v166, v22, v184
	v_fma_f32 v209, v167, v23, v185
	v_fmac_f32_dpp v206, v20, v160 row_shr:1 row_mask:0xf bank_mask:0xf
	v_fmac_f32_dpp v207, v21, v161 row_shr:1 row_mask:0xf bank_mask:0xf
	v_fmac_f32_dpp v208, v22, v162 row_shr:1 row_mask:0xf bank_mask:0xf
	v_fmac_f32_dpp v209, v23, v163 row_shr:1 row_mask:0xf bank_mask:0xf
	v_fmac_f32_dpp v206, v36, v226 row_ror:1 row_mask:0xf bank_mask:0xf
	v_fmac_f32_dpp v207, v37, v227 row_ror:1 row_mask:0xf bank_mask:0xf
	v_fmac_f32_dpp v208, v38, v228 row_ror:1 row_mask:0xf bank_mask:0xf
	v_fmac_f32_dpp v209, v39, v229 row_ror:1 row_mask:0xf bank_mask:0xf
	v_fmac_f32_dpp v206, v20, v178 row_shl:1 row_mask:0xf bank_mask:0xf
	v_fmac_f32_dpp v207, v21, v179 row_shl:1 row_mask:0xf bank_mask:0xf
	v_fmac_f32_dpp v208, v22, v180 row_shl:1 row_mask:0xf bank_mask:0xf
	v_fmac_f32_dpp v209, v23, v181 row_shl:1 row_mask:0xf bank_mask:0xf
	v_fmac_f32_dpp v206, v4, v232 row_ror:15 row_mask:0xf bank_mask:0xf
	v_fmac_f32_dpp v207, v5, v233 row_ror:15 row_mask:0xf bank_mask:0xf
	v_fmac_f32_dpp v208, v6, v234 row_ror:15 row_mask:0xf bank_mask:0xf
	v_fmac_f32_dpp v209, v7, v235 row_ror:15 row_mask:0xf bank_mask:0xf
	v_mul_f32_e32 v210, 0xbfb8aa3b, v202
	v_mul_f32_e32 v211, 0xbfb8aa3b, v203
	v_mul_f32_e32 v212, 0xbfb8aa3b, v204
	v_mul_f32_e32 v213, 0xbfb8aa3b, v205
	v_exp_f32_e32 v210, v210
	v_exp_f32_e32 v211, v211
	v_exp_f32_e32 v212, v212
	v_exp_f32_e32 v213, v213
	v_add_f32_e32 v210, 1.0, v210
	v_add_f32_e32 v211, 1.0, v211
	v_add_f32_e32 v212, 1.0, v212
	v_add_f32_e32 v213, 1.0, v213
	v_rcp_f32_e32 v210, v210
	v_rcp_f32_e32 v211, v211
	v_rcp_f32_e32 v212, v212
	v_rcp_f32_e32 v213, v213
	v_mul_f32_e32 v202, v202, v210
	v_mul_f32_e32 v203, v203, v211
	v_mul_f32_e32 v204, v204, v212
	v_mul_f32_e32 v205, v205, v213
	v_mul_f32_e32 v202, v202, v206
	v_mul_f32_e32 v203, v203, v207
	v_mul_f32_e32 v204, v204, v208
	v_mul_f32_e32 v205, v205, v209
	v_cvt_pk_bf16_f32 v248, v202, v203
	v_cvt_pk_bf16_f32 v249, v204, v205
	v_fma_f32 v202, v124, v12, v132
	v_fma_f32 v203, v125, v13, v133
	v_fma_f32 v204, v126, v14, v134
	v_fma_f32 v205, v127, v15, v135
	v_fmac_f32_dpp v202, v12, v116 row_shr:1 row_mask:0xf bank_mask:0xf
	v_fmac_f32_dpp v203, v13, v117 row_shr:1 row_mask:0xf bank_mask:0xf
	v_fmac_f32_dpp v204, v14, v118 row_shr:1 row_mask:0xf bank_mask:0xf
	v_fmac_f32_dpp v205, v15, v119 row_shr:1 row_mask:0xf bank_mask:0xf
	v_fmac_f32_dpp v202, v28, v218 row_ror:1 row_mask:0xf bank_mask:0xf
	v_fmac_f32_dpp v203, v29, v219 row_ror:1 row_mask:0xf bank_mask:0xf
	v_fmac_f32_dpp v204, v30, v220 row_ror:1 row_mask:0xf bank_mask:0xf
	v_fmac_f32_dpp v205, v31, v221 row_ror:1 row_mask:0xf bank_mask:0xf
	v_fmac_f32_dpp v202, v12, v128 row_shl:1 row_mask:0xf bank_mask:0xf
	v_fmac_f32_dpp v203, v13, v129 row_shl:1 row_mask:0xf bank_mask:0xf
	v_fmac_f32_dpp v204, v14, v130 row_shl:1 row_mask:0xf bank_mask:0xf
	v_fmac_f32_dpp v205, v15, v131 row_shl:1 row_mask:0xf bank_mask:0xf
	v_fmac_f32_e32 v202, v194, v222
	v_fmac_f32_e32 v203, v195, v223
	v_fmac_f32_e32 v204, v196, v224
	v_fmac_f32_e32 v205, v197, v225
	v_fma_f32 v206, v164, v4, v182
	v_fma_f32 v207, v165, v5, v183
	v_fma_f32 v208, v166, v6, v184
	v_fma_f32 v209, v167, v7, v185
	v_fmac_f32_dpp v206, v4, v160 row_shr:1 row_mask:0xf bank_mask:0xf
	v_fmac_f32_dpp v207, v5, v161 row_shr:1 row_mask:0xf bank_mask:0xf
	v_fmac_f32_dpp v208, v6, v162 row_shr:1 row_mask:0xf bank_mask:0xf
	v_fmac_f32_dpp v209, v7, v163 row_shr:1 row_mask:0xf bank_mask:0xf
	v_fmac_f32_dpp v206, v20, v226 row_ror:1 row_mask:0xf bank_mask:0xf
	v_fmac_f32_dpp v207, v21, v227 row_ror:1 row_mask:0xf bank_mask:0xf
	v_fmac_f32_dpp v208, v22, v228 row_ror:1 row_mask:0xf bank_mask:0xf
	v_fmac_f32_dpp v209, v23, v229 row_ror:1 row_mask:0xf bank_mask:0xf
	v_fmac_f32_dpp v206, v4, v178 row_shl:1 row_mask:0xf bank_mask:0xf
	v_fmac_f32_dpp v207, v5, v179 row_shl:1 row_mask:0xf bank_mask:0xf
	v_fmac_f32_dpp v208, v6, v180 row_shl:1 row_mask:0xf bank_mask:0xf
	v_fmac_f32_dpp v209, v7, v181 row_shl:1 row_mask:0xf bank_mask:0xf
	v_fmac_f32_e32 v206, v198, v232
	v_fmac_f32_e32 v207, v199, v233
	v_fmac_f32_e32 v208, v200, v234
	v_fmac_f32_e32 v209, v201, v235
	v_mul_f32_e32 v210, 0xbfb8aa3b, v202
	v_mul_f32_e32 v211, 0xbfb8aa3b, v203
	v_mul_f32_e32 v212, 0xbfb8aa3b, v204
	v_mul_f32_e32 v213, 0xbfb8aa3b, v205
	v_exp_f32_e32 v210, v210
	v_exp_f32_e32 v211, v211
	v_exp_f32_e32 v212, v212
	v_exp_f32_e32 v213, v213
	v_add_f32_e32 v210, 1.0, v210
	v_add_f32_e32 v211, 1.0, v211
	v_add_f32_e32 v212, 1.0, v212
	v_add_f32_e32 v213, 1.0, v213
	v_rcp_f32_e32 v210, v210
	v_rcp_f32_e32 v211, v211
	v_rcp_f32_e32 v212, v212
	v_rcp_f32_e32 v213, v213
	v_mul_f32_e32 v202, v202, v210
	v_mul_f32_e32 v203, v203, v211
	v_mul_f32_e32 v204, v204, v212
	v_mul_f32_e32 v205, v205, v213
	v_mul_f32_e32 v202, v202, v206
	v_mul_f32_e32 v203, v203, v207
	v_mul_f32_e32 v204, v204, v208
	v_mul_f32_e32 v205, v205, v209
	v_cvt_pk_bf16_f32 v250, v202, v203
	v_cvt_pk_bf16_f32 v251, v204, v205
	global_load_dwordx4 v[116:119], v177, s[2:3] offset:16
	v_add_u32_e32 v213, 0x5800, v177
	global_load_dwordx4 v[124:127], v213, s[2:3] offset:16
	v_add_u32_e32 v212, 0xb000, v177
	global_load_dwordx4 v[128:131], v212, s[2:3] offset:16
	global_load_dwordx4 v[132:135], v177, s[28:29] offset:16
	v_add_u32_e32 v212, 0x2c00, v177
	global_load_dwordx4 v[160:163], v212, s[2:3] offset:16
	v_add_u32_e32 v213, 0x8400, v177
	global_load_dwordx4 v[164:167], v213, s[2:3] offset:16
	v_add_u32_e32 v212, 0xdc00, v177
	global_load_dwordx4 v[178:181], v212, s[2:3] offset:16
	v_add_u32_e32 v213, 0x2c00, v177
	global_load_dwordx4 v[182:185], v213, s[28:29] offset:16
	v_mov_b32_e32 v140, v236
	v_mov_b32_e32 v141, v237
	v_mov_b32_e32 v108, v238
	v_mov_b32_e32 v109, v239
	v_mov_b32_e32 v92, v240
	v_mov_b32_e32 v93, v241
	v_mov_b32_e32 v76, v242
	v_mov_b32_e32 v77, v243
	v_mov_b32_e32 v60, v244
	v_mov_b32_e32 v61, v245
	v_mov_b32_e32 v44, v246
	v_mov_b32_e32 v45, v247
	v_mov_b32_e32 v28, v248
	v_mov_b32_e32 v29, v249
	v_mov_b32_e32 v12, v250
	v_mov_b32_e32 v13, v251
	ds_read_b128 v[186:189], v231 offset:16
	ds_read_b128 v[190:193], v231 offset:528
	ds_read_b128 v[194:197], v231 offset:2064
	ds_read_b128 v[198:201], v231 offset:2576
	s_waitcnt vmcnt(0)
	v_cndmask_b32_e64 v218, 0, v116, s[78:79]
	v_cndmask_b32_e64 v222, 0, v128, s[80:81]
	v_cndmask_b32_e64 v219, 0, v117, s[78:79]
	v_cndmask_b32_e64 v223, 0, v129, s[80:81]
	v_cndmask_b32_e64 v220, 0, v118, s[78:79]
	v_cndmask_b32_e64 v224, 0, v130, s[80:81]
	v_cndmask_b32_e64 v221, 0, v119, s[78:79]
	v_cndmask_b32_e64 v225, 0, v131, s[80:81]
	v_cndmask_b32_e64 v226, 0, v160, s[78:79]
	v_cndmask_b32_e64 v232, 0, v178, s[80:81]
	v_cndmask_b32_e64 v227, 0, v161, s[78:79]
	v_cndmask_b32_e64 v233, 0, v179, s[80:81]
	v_cndmask_b32_e64 v228, 0, v162, s[78:79]
	v_cndmask_b32_e64 v234, 0, v180, s[80:81]
	v_cndmask_b32_e64 v229, 0, v163, s[78:79]
	v_cndmask_b32_e64 v235, 0, v181, s[80:81]
	s_waitcnt lgkmcnt(0)
	s_nop 1
	v_fma_f32 v202, v124, v136, v132
	v_fma_f32 v203, v125, v137, v133
	v_fma_f32 v204, v126, v138, v134
	v_fma_f32 v205, v127, v139, v135
	v_fmac_f32_dpp v202, v136, v116 row_shr:1 row_mask:0xf bank_mask:0xf
	v_fmac_f32_dpp v203, v137, v117 row_shr:1 row_mask:0xf bank_mask:0xf
	v_fmac_f32_dpp v204, v138, v118 row_shr:1 row_mask:0xf bank_mask:0xf
	v_fmac_f32_dpp v205, v139, v119 row_shr:1 row_mask:0xf bank_mask:0xf
	v_fmac_f32_e32 v202, v186, v218
	v_fmac_f32_e32 v203, v187, v219
	v_fmac_f32_e32 v204, v188, v220
	v_fmac_f32_e32 v205, v189, v221
	v_fmac_f32_dpp v202, v136, v128 row_shl:1 row_mask:0xf bank_mask:0xf
	v_fmac_f32_dpp v203, v137, v129 row_shl:1 row_mask:0xf bank_mask:0xf
	v_fmac_f32_dpp v204, v138, v130 row_shl:1 row_mask:0xf bank_mask:0xf
	v_fmac_f32_dpp v205, v139, v131 row_shl:1 row_mask:0xf bank_mask:0xf
	v_fmac_f32_dpp v202, v104, v222 row_ror:15 row_mask:0xf bank_mask:0xf
	v_fmac_f32_dpp v203, v105, v223 row_ror:15 row_mask:0xf bank_mask:0xf
	v_fmac_f32_dpp v204, v106, v224 row_ror:15 row_mask:0xf bank_mask:0xf
	v_fmac_f32_dpp v205, v107, v225 row_ror:15 row_mask:0xf bank_mask:0xf
	v_fma_f32 v206, v164, v112, v182
	v_fma_f32 v207, v165, v113, v183
	v_fma_f32 v208, v166, v114, v184
	v_fma_f32 v209, v167, v115, v185
	v_fmac_f32_dpp v206, v112, v160 row_shr:1 row_mask:0xf bank_mask:0xf
	v_fmac_f32_dpp v207, v113, v161 row_shr:1 row_mask:0xf bank_mask:0xf
	v_fmac_f32_dpp v208, v114, v162 row_shr:1 row_mask:0xf bank_mask:0xf
	v_fmac_f32_dpp v209, v115, v163 row_shr:1 row_mask:0xf bank_mask:0xf
	v_fmac_f32_e32 v206, v190, v226
	v_fmac_f32_e32 v207, v191, v227
	v_fmac_f32_e32 v208, v192, v228
	v_fmac_f32_e32 v209, v193, v229
	v_fmac_f32_dpp v206, v112, v178 row_shl:1 row_mask:0xf bank_mask:0xf
	v_fmac_f32_dpp v207, v113, v179 row_shl:1 row_mask:0xf bank_mask:0xf
	v_fmac_f32_dpp v208, v114, v180 row_shl:1 row_mask:0xf bank_mask:0xf
	v_fmac_f32_dpp v209, v115, v181 row_shl:1 row_mask:0xf bank_mask:0xf
	v_fmac_f32_dpp v206, v96, v232 row_ror:15 row_mask:0xf bank_mask:0xf
	v_fmac_f32_dpp v207, v97, v233 row_ror:15 row_mask:0xf bank_mask:0xf
	v_fmac_f32_dpp v208, v98, v234 row_ror:15 row_mask:0xf bank_mask:0xf
	v_fmac_f32_dpp v209, v99, v235 row_ror:15 row_mask:0xf bank_mask:0xf
	v_mul_f32_e32 v210, 0xbfb8aa3b, v202
	v_mul_f32_e32 v211, 0xbfb8aa3b, v203
	v_mul_f32_e32 v212, 0xbfb8aa3b, v204
	v_mul_f32_e32 v213, 0xbfb8aa3b, v205
	v_exp_f32_e32 v210, v210
	v_exp_f32_e32 v211, v211
	v_exp_f32_e32 v212, v212
	v_exp_f32_e32 v213, v213
	v_add_f32_e32 v210, 1.0, v210
	v_add_f32_e32 v211, 1.0, v211
	v_add_f32_e32 v212, 1.0, v212
	v_add_f32_e32 v213, 1.0, v213
	v_rcp_f32_e32 v210, v210
	v_rcp_f32_e32 v211, v211
	v_rcp_f32_e32 v212, v212
	v_rcp_f32_e32 v213, v213
	v_mul_f32_e32 v202, v202, v210
	v_mul_f32_e32 v203, v203, v211
	v_mul_f32_e32 v204, v204, v212
	v_mul_f32_e32 v205, v205, v213
	v_mul_f32_e32 v202, v202, v206
	v_mul_f32_e32 v203, v203, v207
	v_mul_f32_e32 v204, v204, v208
	v_mul_f32_e32 v205, v205, v209
	v_cvt_pk_bf16_f32 v142, v202, v203
	v_cvt_pk_bf16_f32 v143, v204, v205
	v_fma_f32 v202, v124, v104, v132
	v_fma_f32 v203, v125, v105, v133
	v_fma_f32 v204, v126, v106, v134
	v_fma_f32 v205, v127, v107, v135
	v_fmac_f32_dpp v202, v104, v116 row_shr:1 row_mask:0xf bank_mask:0xf
	v_fmac_f32_dpp v203, v105, v117 row_shr:1 row_mask:0xf bank_mask:0xf
	v_fmac_f32_dpp v204, v106, v118 row_shr:1 row_mask:0xf bank_mask:0xf
	v_fmac_f32_dpp v205, v107, v119 row_shr:1 row_mask:0xf bank_mask:0xf
	v_fmac_f32_dpp v202, v136, v218 row_ror:1 row_mask:0xf bank_mask:0xf
	v_fmac_f32_dpp v203, v137, v219 row_ror:1 row_mask:0xf bank_mask:0xf
	v_fmac_f32_dpp v204, v138, v220 row_ror:1 row_mask:0xf bank_mask:0xf
	v_fmac_f32_dpp v205, v139, v221 row_ror:1 row_mask:0xf bank_mask:0xf
	v_fmac_f32_dpp v202, v104, v128 row_shl:1 row_mask:0xf bank_mask:0xf
	v_fmac_f32_dpp v203, v105, v129 row_shl:1 row_mask:0xf bank_mask:0xf
	v_fmac_f32_dpp v204, v106, v130 row_shl:1 row_mask:0xf bank_mask:0xf
	v_fmac_f32_dpp v205, v107, v131 row_shl:1 row_mask:0xf bank_mask:0xf
	v_fmac_f32_dpp v202, v88, v222 row_ror:15 row_mask:0xf bank_mask:0xf
	v_fmac_f32_dpp v203, v89, v223 row_ror:15 row_mask:0xf bank_mask:0xf
	v_fmac_f32_dpp v204, v90, v224 row_ror:15 row_mask:0xf bank_mask:0xf
	v_fmac_f32_dpp v205, v91, v225 row_ror:15 row_mask:0xf bank_mask:0xf
	v_fma_f32 v206, v164, v96, v182
	v_fma_f32 v207, v165, v97, v183
	v_fma_f32 v208, v166, v98, v184
	v_fma_f32 v209, v167, v99, v185
	v_fmac_f32_dpp v206, v96, v160 row_shr:1 row_mask:0xf bank_mask:0xf
	v_fmac_f32_dpp v207, v97, v161 row_shr:1 row_mask:0xf bank_mask:0xf
	v_fmac_f32_dpp v208, v98, v162 row_shr:1 row_mask:0xf bank_mask:0xf
	v_fmac_f32_dpp v209, v99, v163 row_shr:1 row_mask:0xf bank_mask:0xf
	v_fmac_f32_dpp v206, v112, v226 row_ror:1 row_mask:0xf bank_mask:0xf
	v_fmac_f32_dpp v207, v113, v227 row_ror:1 row_mask:0xf bank_mask:0xf
	v_fmac_f32_dpp v208, v114, v228 row_ror:1 row_mask:0xf bank_mask:0xf
	v_fmac_f32_dpp v209, v115, v229 row_ror:1 row_mask:0xf bank_mask:0xf
	v_fmac_f32_dpp v206, v96, v178 row_shl:1 row_mask:0xf bank_mask:0xf
	v_fmac_f32_dpp v207, v97, v179 row_shl:1 row_mask:0xf bank_mask:0xf
	v_fmac_f32_dpp v208, v98, v180 row_shl:1 row_mask:0xf bank_mask:0xf
	v_fmac_f32_dpp v209, v99, v181 row_shl:1 row_mask:0xf bank_mask:0xf
	v_fmac_f32_dpp v206, v80, v232 row_ror:15 row_mask:0xf bank_mask:0xf
	v_fmac_f32_dpp v207, v81, v233 row_ror:15 row_mask:0xf bank_mask:0xf
	v_fmac_f32_dpp v208, v82, v234 row_ror:15 row_mask:0xf bank_mask:0xf
	v_fmac_f32_dpp v209, v83, v235 row_ror:15 row_mask:0xf bank_mask:0xf
	v_mul_f32_e32 v210, 0xbfb8aa3b, v202
	v_mul_f32_e32 v211, 0xbfb8aa3b, v203
	v_mul_f32_e32 v212, 0xbfb8aa3b, v204
	v_mul_f32_e32 v213, 0xbfb8aa3b, v205
	v_exp_f32_e32 v210, v210
	v_exp_f32_e32 v211, v211
	v_exp_f32_e32 v212, v212
	v_exp_f32_e32 v213, v213
	v_add_f32_e32 v210, 1.0, v210
	v_add_f32_e32 v211, 1.0, v211
	v_add_f32_e32 v212, 1.0, v212
	v_add_f32_e32 v213, 1.0, v213
	v_rcp_f32_e32 v210, v210
	v_rcp_f32_e32 v211, v211
	v_rcp_f32_e32 v212, v212
	v_rcp_f32_e32 v213, v213
	v_mul_f32_e32 v202, v202, v210
	v_mul_f32_e32 v203, v203, v211
	v_mul_f32_e32 v204, v204, v212
	v_mul_f32_e32 v205, v205, v213
	v_mul_f32_e32 v202, v202, v206
	v_mul_f32_e32 v203, v203, v207
	v_mul_f32_e32 v204, v204, v208
	v_mul_f32_e32 v205, v205, v209
	v_cvt_pk_bf16_f32 v110, v202, v203
	v_cvt_pk_bf16_f32 v111, v204, v205
	v_fma_f32 v202, v124, v88, v132
	v_fma_f32 v203, v125, v89, v133
	v_fma_f32 v204, v126, v90, v134
	v_fma_f32 v205, v127, v91, v135
	v_fmac_f32_dpp v202, v88, v116 row_shr:1 row_mask:0xf bank_mask:0xf
	v_fmac_f32_dpp v203, v89, v117 row_shr:1 row_mask:0xf bank_mask:0xf
	v_fmac_f32_dpp v204, v90, v118 row_shr:1 row_mask:0xf bank_mask:0xf
	v_fmac_f32_dpp v205, v91, v119 row_shr:1 row_mask:0xf bank_mask:0xf
	v_fmac_f32_dpp v202, v104, v218 row_ror:1 row_mask:0xf bank_mask:0xf
	v_fmac_f32_dpp v203, v105, v219 row_ror:1 row_mask:0xf bank_mask:0xf
	v_fmac_f32_dpp v204, v106, v220 row_ror:1 row_mask:0xf bank_mask:0xf
	v_fmac_f32_dpp v205, v107, v221 row_ror:1 row_mask:0xf bank_mask:0xf
	v_fmac_f32_dpp v202, v88, v128 row_shl:1 row_mask:0xf bank_mask:0xf
	v_fmac_f32_dpp v203, v89, v129 row_shl:1 row_mask:0xf bank_mask:0xf
	v_fmac_f32_dpp v204, v90, v130 row_shl:1 row_mask:0xf bank_mask:0xf
	v_fmac_f32_dpp v205, v91, v131 row_shl:1 row_mask:0xf bank_mask:0xf
	v_fmac_f32_dpp v202, v72, v222 row_ror:15 row_mask:0xf bank_mask:0xf
	v_fmac_f32_dpp v203, v73, v223 row_ror:15 row_mask:0xf bank_mask:0xf
	v_fmac_f32_dpp v204, v74, v224 row_ror:15 row_mask:0xf bank_mask:0xf
	v_fmac_f32_dpp v205, v75, v225 row_ror:15 row_mask:0xf bank_mask:0xf
	v_fma_f32 v206, v164, v80, v182
	v_fma_f32 v207, v165, v81, v183
	v_fma_f32 v208, v166, v82, v184
	v_fma_f32 v209, v167, v83, v185
	v_fmac_f32_dpp v206, v80, v160 row_shr:1 row_mask:0xf bank_mask:0xf
	v_fmac_f32_dpp v207, v81, v161 row_shr:1 row_mask:0xf bank_mask:0xf
	v_fmac_f32_dpp v208, v82, v162 row_shr:1 row_mask:0xf bank_mask:0xf
	v_fmac_f32_dpp v209, v83, v163 row_shr:1 row_mask:0xf bank_mask:0xf
	v_fmac_f32_dpp v206, v96, v226 row_ror:1 row_mask:0xf bank_mask:0xf
	v_fmac_f32_dpp v207, v97, v227 row_ror:1 row_mask:0xf bank_mask:0xf
	v_fmac_f32_dpp v208, v98, v228 row_ror:1 row_mask:0xf bank_mask:0xf
	v_fmac_f32_dpp v209, v99, v229 row_ror:1 row_mask:0xf bank_mask:0xf
	v_fmac_f32_dpp v206, v80, v178 row_shl:1 row_mask:0xf bank_mask:0xf
	v_fmac_f32_dpp v207, v81, v179 row_shl:1 row_mask:0xf bank_mask:0xf
	v_fmac_f32_dpp v208, v82, v180 row_shl:1 row_mask:0xf bank_mask:0xf
	v_fmac_f32_dpp v209, v83, v181 row_shl:1 row_mask:0xf bank_mask:0xf
	v_fmac_f32_dpp v206, v64, v232 row_ror:15 row_mask:0xf bank_mask:0xf
	v_fmac_f32_dpp v207, v65, v233 row_ror:15 row_mask:0xf bank_mask:0xf
	v_fmac_f32_dpp v208, v66, v234 row_ror:15 row_mask:0xf bank_mask:0xf
	v_fmac_f32_dpp v209, v67, v235 row_ror:15 row_mask:0xf bank_mask:0xf
	v_mul_f32_e32 v210, 0xbfb8aa3b, v202
	v_mul_f32_e32 v211, 0xbfb8aa3b, v203
	v_mul_f32_e32 v212, 0xbfb8aa3b, v204
	v_mul_f32_e32 v213, 0xbfb8aa3b, v205
	v_exp_f32_e32 v210, v210
	v_exp_f32_e32 v211, v211
	v_exp_f32_e32 v212, v212
	v_exp_f32_e32 v213, v213
	v_add_f32_e32 v210, 1.0, v210
	v_add_f32_e32 v211, 1.0, v211
	v_add_f32_e32 v212, 1.0, v212
	v_add_f32_e32 v213, 1.0, v213
	v_rcp_f32_e32 v210, v210
	v_rcp_f32_e32 v211, v211
	v_rcp_f32_e32 v212, v212
	v_rcp_f32_e32 v213, v213
	v_mul_f32_e32 v202, v202, v210
	v_mul_f32_e32 v203, v203, v211
	v_mul_f32_e32 v204, v204, v212
	v_mul_f32_e32 v205, v205, v213
	v_mul_f32_e32 v202, v202, v206
	v_mul_f32_e32 v203, v203, v207
	v_mul_f32_e32 v204, v204, v208
	v_mul_f32_e32 v205, v205, v209
	v_cvt_pk_bf16_f32 v94, v202, v203
	v_cvt_pk_bf16_f32 v95, v204, v205
	v_fma_f32 v202, v124, v72, v132
	v_fma_f32 v203, v125, v73, v133
	v_fma_f32 v204, v126, v74, v134
	v_fma_f32 v205, v127, v75, v135
	v_fmac_f32_dpp v202, v72, v116 row_shr:1 row_mask:0xf bank_mask:0xf
	v_fmac_f32_dpp v203, v73, v117 row_shr:1 row_mask:0xf bank_mask:0xf
	v_fmac_f32_dpp v204, v74, v118 row_shr:1 row_mask:0xf bank_mask:0xf
	v_fmac_f32_dpp v205, v75, v119 row_shr:1 row_mask:0xf bank_mask:0xf
	v_fmac_f32_dpp v202, v88, v218 row_ror:1 row_mask:0xf bank_mask:0xf
	v_fmac_f32_dpp v203, v89, v219 row_ror:1 row_mask:0xf bank_mask:0xf
	v_fmac_f32_dpp v204, v90, v220 row_ror:1 row_mask:0xf bank_mask:0xf
	v_fmac_f32_dpp v205, v91, v221 row_ror:1 row_mask:0xf bank_mask:0xf
	v_fmac_f32_dpp v202, v72, v128 row_shl:1 row_mask:0xf bank_mask:0xf
	v_fmac_f32_dpp v203, v73, v129 row_shl:1 row_mask:0xf bank_mask:0xf
	v_fmac_f32_dpp v204, v74, v130 row_shl:1 row_mask:0xf bank_mask:0xf
	v_fmac_f32_dpp v205, v75, v131 row_shl:1 row_mask:0xf bank_mask:0xf
	v_fmac_f32_e32 v202, v186, v222
	v_fmac_f32_e32 v203, v187, v223
	v_fmac_f32_e32 v204, v188, v224
	v_fmac_f32_e32 v205, v189, v225
	v_fma_f32 v206, v164, v64, v182
	v_fma_f32 v207, v165, v65, v183
	v_fma_f32 v208, v166, v66, v184
	v_fma_f32 v209, v167, v67, v185
	v_fmac_f32_dpp v206, v64, v160 row_shr:1 row_mask:0xf bank_mask:0xf
	v_fmac_f32_dpp v207, v65, v161 row_shr:1 row_mask:0xf bank_mask:0xf
	v_fmac_f32_dpp v208, v66, v162 row_shr:1 row_mask:0xf bank_mask:0xf
	v_fmac_f32_dpp v209, v67, v163 row_shr:1 row_mask:0xf bank_mask:0xf
	v_fmac_f32_dpp v206, v80, v226 row_ror:1 row_mask:0xf bank_mask:0xf
	v_fmac_f32_dpp v207, v81, v227 row_ror:1 row_mask:0xf bank_mask:0xf
	v_fmac_f32_dpp v208, v82, v228 row_ror:1 row_mask:0xf bank_mask:0xf
	v_fmac_f32_dpp v209, v83, v229 row_ror:1 row_mask:0xf bank_mask:0xf
	v_fmac_f32_dpp v206, v64, v178 row_shl:1 row_mask:0xf bank_mask:0xf
	v_fmac_f32_dpp v207, v65, v179 row_shl:1 row_mask:0xf bank_mask:0xf
	v_fmac_f32_dpp v208, v66, v180 row_shl:1 row_mask:0xf bank_mask:0xf
	v_fmac_f32_dpp v209, v67, v181 row_shl:1 row_mask:0xf bank_mask:0xf
	v_fmac_f32_e32 v206, v190, v232
	v_fmac_f32_e32 v207, v191, v233
	v_fmac_f32_e32 v208, v192, v234
	v_fmac_f32_e32 v209, v193, v235
	v_mul_f32_e32 v210, 0xbfb8aa3b, v202
	v_mul_f32_e32 v211, 0xbfb8aa3b, v203
	v_mul_f32_e32 v212, 0xbfb8aa3b, v204
	v_mul_f32_e32 v213, 0xbfb8aa3b, v205
	v_exp_f32_e32 v210, v210
	v_exp_f32_e32 v211, v211
	v_exp_f32_e32 v212, v212
	v_exp_f32_e32 v213, v213
	v_add_f32_e32 v210, 1.0, v210
	v_add_f32_e32 v211, 1.0, v211
	v_add_f32_e32 v212, 1.0, v212
	v_add_f32_e32 v213, 1.0, v213
	v_rcp_f32_e32 v210, v210
	v_rcp_f32_e32 v211, v211
	v_rcp_f32_e32 v212, v212
	v_rcp_f32_e32 v213, v213
	v_mul_f32_e32 v202, v202, v210
	v_mul_f32_e32 v203, v203, v211
	v_mul_f32_e32 v204, v204, v212
	v_mul_f32_e32 v205, v205, v213
	v_mul_f32_e32 v202, v202, v206
	v_mul_f32_e32 v203, v203, v207
	v_mul_f32_e32 v204, v204, v208
	v_mul_f32_e32 v205, v205, v209
	v_cvt_pk_bf16_f32 v78, v202, v203
	v_cvt_pk_bf16_f32 v79, v204, v205
	v_fma_f32 v202, v124, v56, v132
	v_fma_f32 v203, v125, v57, v133
	v_fma_f32 v204, v126, v58, v134
	v_fma_f32 v205, v127, v59, v135
	v_fmac_f32_dpp v202, v56, v116 row_shr:1 row_mask:0xf bank_mask:0xf
	v_fmac_f32_dpp v203, v57, v117 row_shr:1 row_mask:0xf bank_mask:0xf
	v_fmac_f32_dpp v204, v58, v118 row_shr:1 row_mask:0xf bank_mask:0xf
	v_fmac_f32_dpp v205, v59, v119 row_shr:1 row_mask:0xf bank_mask:0xf
	v_fmac_f32_e32 v202, v194, v218
	v_fmac_f32_e32 v203, v195, v219
	v_fmac_f32_e32 v204, v196, v220
	v_fmac_f32_e32 v205, v197, v221
	v_fmac_f32_dpp v202, v56, v128 row_shl:1 row_mask:0xf bank_mask:0xf
	v_fmac_f32_dpp v203, v57, v129 row_shl:1 row_mask:0xf bank_mask:0xf
	v_fmac_f32_dpp v204, v58, v130 row_shl:1 row_mask:0xf bank_mask:0xf
	v_fmac_f32_dpp v205, v59, v131 row_shl:1 row_mask:0xf bank_mask:0xf
	v_fmac_f32_dpp v202, v40, v222 row_ror:15 row_mask:0xf bank_mask:0xf
	v_fmac_f32_dpp v203, v41, v223 row_ror:15 row_mask:0xf bank_mask:0xf
	v_fmac_f32_dpp v204, v42, v224 row_ror:15 row_mask:0xf bank_mask:0xf
	v_fmac_f32_dpp v205, v43, v225 row_ror:15 row_mask:0xf bank_mask:0xf
	v_fma_f32 v206, v164, v48, v182
	v_fma_f32 v207, v165, v49, v183
	v_fma_f32 v208, v166, v50, v184
	v_fma_f32 v209, v167, v51, v185
	v_fmac_f32_dpp v206, v48, v160 row_shr:1 row_mask:0xf bank_mask:0xf
	v_fmac_f32_dpp v207, v49, v161 row_shr:1 row_mask:0xf bank_mask:0xf
	v_fmac_f32_dpp v208, v50, v162 row_shr:1 row_mask:0xf bank_mask:0xf
	v_fmac_f32_dpp v209, v51, v163 row_shr:1 row_mask:0xf bank_mask:0xf
	v_fmac_f32_e32 v206, v198, v226
	v_fmac_f32_e32 v207, v199, v227
	v_fmac_f32_e32 v208, v200, v228
	v_fmac_f32_e32 v209, v201, v229
	v_fmac_f32_dpp v206, v48, v178 row_shl:1 row_mask:0xf bank_mask:0xf
	v_fmac_f32_dpp v207, v49, v179 row_shl:1 row_mask:0xf bank_mask:0xf
	v_fmac_f32_dpp v208, v50, v180 row_shl:1 row_mask:0xf bank_mask:0xf
	v_fmac_f32_dpp v209, v51, v181 row_shl:1 row_mask:0xf bank_mask:0xf
	v_fmac_f32_dpp v206, v32, v232 row_ror:15 row_mask:0xf bank_mask:0xf
	v_fmac_f32_dpp v207, v33, v233 row_ror:15 row_mask:0xf bank_mask:0xf
	v_fmac_f32_dpp v208, v34, v234 row_ror:15 row_mask:0xf bank_mask:0xf
	v_fmac_f32_dpp v209, v35, v235 row_ror:15 row_mask:0xf bank_mask:0xf
	v_mul_f32_e32 v210, 0xbfb8aa3b, v202
	v_mul_f32_e32 v211, 0xbfb8aa3b, v203
	v_mul_f32_e32 v212, 0xbfb8aa3b, v204
	v_mul_f32_e32 v213, 0xbfb8aa3b, v205
	v_exp_f32_e32 v210, v210
	v_exp_f32_e32 v211, v211
	v_exp_f32_e32 v212, v212
	v_exp_f32_e32 v213, v213
	v_add_f32_e32 v210, 1.0, v210
	v_add_f32_e32 v211, 1.0, v211
	v_add_f32_e32 v212, 1.0, v212
	v_add_f32_e32 v213, 1.0, v213
	v_rcp_f32_e32 v210, v210
	v_rcp_f32_e32 v211, v211
	v_rcp_f32_e32 v212, v212
	v_rcp_f32_e32 v213, v213
	v_mul_f32_e32 v202, v202, v210
	v_mul_f32_e32 v203, v203, v211
	v_mul_f32_e32 v204, v204, v212
	v_mul_f32_e32 v205, v205, v213
	v_mul_f32_e32 v202, v202, v206
	v_mul_f32_e32 v203, v203, v207
	v_mul_f32_e32 v204, v204, v208
	v_mul_f32_e32 v205, v205, v209
	v_cvt_pk_bf16_f32 v62, v202, v203
	v_cvt_pk_bf16_f32 v63, v204, v205
	v_fma_f32 v202, v124, v40, v132
	v_fma_f32 v203, v125, v41, v133
	v_fma_f32 v204, v126, v42, v134
	v_fma_f32 v205, v127, v43, v135
	v_fmac_f32_dpp v202, v40, v116 row_shr:1 row_mask:0xf bank_mask:0xf
	v_fmac_f32_dpp v203, v41, v117 row_shr:1 row_mask:0xf bank_mask:0xf
	v_fmac_f32_dpp v204, v42, v118 row_shr:1 row_mask:0xf bank_mask:0xf
	v_fmac_f32_dpp v205, v43, v119 row_shr:1 row_mask:0xf bank_mask:0xf
	v_fmac_f32_dpp v202, v56, v218 row_ror:1 row_mask:0xf bank_mask:0xf
	v_fmac_f32_dpp v203, v57, v219 row_ror:1 row_mask:0xf bank_mask:0xf
	v_fmac_f32_dpp v204, v58, v220 row_ror:1 row_mask:0xf bank_mask:0xf
	v_fmac_f32_dpp v205, v59, v221 row_ror:1 row_mask:0xf bank_mask:0xf
	v_fmac_f32_dpp v202, v40, v128 row_shl:1 row_mask:0xf bank_mask:0xf
	v_fmac_f32_dpp v203, v41, v129 row_shl:1 row_mask:0xf bank_mask:0xf
	v_fmac_f32_dpp v204, v42, v130 row_shl:1 row_mask:0xf bank_mask:0xf
	v_fmac_f32_dpp v205, v43, v131 row_shl:1 row_mask:0xf bank_mask:0xf
	v_fmac_f32_dpp v202, v24, v222 row_ror:15 row_mask:0xf bank_mask:0xf
	v_fmac_f32_dpp v203, v25, v223 row_ror:15 row_mask:0xf bank_mask:0xf
	v_fmac_f32_dpp v204, v26, v224 row_ror:15 row_mask:0xf bank_mask:0xf
	v_fmac_f32_dpp v205, v27, v225 row_ror:15 row_mask:0xf bank_mask:0xf
	v_fma_f32 v206, v164, v32, v182
	v_fma_f32 v207, v165, v33, v183
	v_fma_f32 v208, v166, v34, v184
	v_fma_f32 v209, v167, v35, v185
	v_fmac_f32_dpp v206, v32, v160 row_shr:1 row_mask:0xf bank_mask:0xf
	v_fmac_f32_dpp v207, v33, v161 row_shr:1 row_mask:0xf bank_mask:0xf
	v_fmac_f32_dpp v208, v34, v162 row_shr:1 row_mask:0xf bank_mask:0xf
	v_fmac_f32_dpp v209, v35, v163 row_shr:1 row_mask:0xf bank_mask:0xf
	v_fmac_f32_dpp v206, v48, v226 row_ror:1 row_mask:0xf bank_mask:0xf
	v_fmac_f32_dpp v207, v49, v227 row_ror:1 row_mask:0xf bank_mask:0xf
	v_fmac_f32_dpp v208, v50, v228 row_ror:1 row_mask:0xf bank_mask:0xf
	v_fmac_f32_dpp v209, v51, v229 row_ror:1 row_mask:0xf bank_mask:0xf
	v_fmac_f32_dpp v206, v32, v178 row_shl:1 row_mask:0xf bank_mask:0xf
	v_fmac_f32_dpp v207, v33, v179 row_shl:1 row_mask:0xf bank_mask:0xf
	v_fmac_f32_dpp v208, v34, v180 row_shl:1 row_mask:0xf bank_mask:0xf
	v_fmac_f32_dpp v209, v35, v181 row_shl:1 row_mask:0xf bank_mask:0xf
	v_fmac_f32_dpp v206, v16, v232 row_ror:15 row_mask:0xf bank_mask:0xf
	v_fmac_f32_dpp v207, v17, v233 row_ror:15 row_mask:0xf bank_mask:0xf
	v_fmac_f32_dpp v208, v18, v234 row_ror:15 row_mask:0xf bank_mask:0xf
	v_fmac_f32_dpp v209, v19, v235 row_ror:15 row_mask:0xf bank_mask:0xf
	v_mul_f32_e32 v210, 0xbfb8aa3b, v202
	v_mul_f32_e32 v211, 0xbfb8aa3b, v203
	v_mul_f32_e32 v212, 0xbfb8aa3b, v204
	v_mul_f32_e32 v213, 0xbfb8aa3b, v205
	v_exp_f32_e32 v210, v210
	v_exp_f32_e32 v211, v211
	v_exp_f32_e32 v212, v212
	v_exp_f32_e32 v213, v213
	v_add_f32_e32 v210, 1.0, v210
	v_add_f32_e32 v211, 1.0, v211
	v_add_f32_e32 v212, 1.0, v212
	v_add_f32_e32 v213, 1.0, v213
	v_rcp_f32_e32 v210, v210
	v_rcp_f32_e32 v211, v211
	v_rcp_f32_e32 v212, v212
	v_rcp_f32_e32 v213, v213
	v_mul_f32_e32 v202, v202, v210
	v_mul_f32_e32 v203, v203, v211
	v_mul_f32_e32 v204, v204, v212
	v_mul_f32_e32 v205, v205, v213
	v_mul_f32_e32 v202, v202, v206
	v_mul_f32_e32 v203, v203, v207
	v_mul_f32_e32 v204, v204, v208
	v_mul_f32_e32 v205, v205, v209
	v_cvt_pk_bf16_f32 v46, v202, v203
	v_cvt_pk_bf16_f32 v47, v204, v205
	v_fma_f32 v202, v124, v24, v132
	v_fma_f32 v203, v125, v25, v133
	v_fma_f32 v204, v126, v26, v134
	v_fma_f32 v205, v127, v27, v135
	v_fmac_f32_dpp v202, v24, v116 row_shr:1 row_mask:0xf bank_mask:0xf
	v_fmac_f32_dpp v203, v25, v117 row_shr:1 row_mask:0xf bank_mask:0xf
	v_fmac_f32_dpp v204, v26, v118 row_shr:1 row_mask:0xf bank_mask:0xf
	v_fmac_f32_dpp v205, v27, v119 row_shr:1 row_mask:0xf bank_mask:0xf
	v_fmac_f32_dpp v202, v40, v218 row_ror:1 row_mask:0xf bank_mask:0xf
	v_fmac_f32_dpp v203, v41, v219 row_ror:1 row_mask:0xf bank_mask:0xf
	v_fmac_f32_dpp v204, v42, v220 row_ror:1 row_mask:0xf bank_mask:0xf
	v_fmac_f32_dpp v205, v43, v221 row_ror:1 row_mask:0xf bank_mask:0xf
	v_fmac_f32_dpp v202, v24, v128 row_shl:1 row_mask:0xf bank_mask:0xf
	v_fmac_f32_dpp v203, v25, v129 row_shl:1 row_mask:0xf bank_mask:0xf
	v_fmac_f32_dpp v204, v26, v130 row_shl:1 row_mask:0xf bank_mask:0xf
	v_fmac_f32_dpp v205, v27, v131 row_shl:1 row_mask:0xf bank_mask:0xf
	v_fmac_f32_dpp v202, v8, v222 row_ror:15 row_mask:0xf bank_mask:0xf
	v_fmac_f32_dpp v203, v9, v223 row_ror:15 row_mask:0xf bank_mask:0xf
	v_fmac_f32_dpp v204, v10, v224 row_ror:15 row_mask:0xf bank_mask:0xf
	v_fmac_f32_dpp v205, v11, v225 row_ror:15 row_mask:0xf bank_mask:0xf
	v_fma_f32 v206, v164, v16, v182
	v_fma_f32 v207, v165, v17, v183
	v_fma_f32 v208, v166, v18, v184
	v_fma_f32 v209, v167, v19, v185
	v_fmac_f32_dpp v206, v16, v160 row_shr:1 row_mask:0xf bank_mask:0xf
	v_fmac_f32_dpp v207, v17, v161 row_shr:1 row_mask:0xf bank_mask:0xf
	v_fmac_f32_dpp v208, v18, v162 row_shr:1 row_mask:0xf bank_mask:0xf
	v_fmac_f32_dpp v209, v19, v163 row_shr:1 row_mask:0xf bank_mask:0xf
	v_fmac_f32_dpp v206, v32, v226 row_ror:1 row_mask:0xf bank_mask:0xf
	v_fmac_f32_dpp v207, v33, v227 row_ror:1 row_mask:0xf bank_mask:0xf
	v_fmac_f32_dpp v208, v34, v228 row_ror:1 row_mask:0xf bank_mask:0xf
	v_fmac_f32_dpp v209, v35, v229 row_ror:1 row_mask:0xf bank_mask:0xf
	v_fmac_f32_dpp v206, v16, v178 row_shl:1 row_mask:0xf bank_mask:0xf
	v_fmac_f32_dpp v207, v17, v179 row_shl:1 row_mask:0xf bank_mask:0xf
	v_fmac_f32_dpp v208, v18, v180 row_shl:1 row_mask:0xf bank_mask:0xf
	v_fmac_f32_dpp v209, v19, v181 row_shl:1 row_mask:0xf bank_mask:0xf
	v_fmac_f32_dpp v206, v0, v232 row_ror:15 row_mask:0xf bank_mask:0xf
	v_fmac_f32_dpp v207, v1, v233 row_ror:15 row_mask:0xf bank_mask:0xf
	v_fmac_f32_dpp v208, v2, v234 row_ror:15 row_mask:0xf bank_mask:0xf
	v_fmac_f32_dpp v209, v3, v235 row_ror:15 row_mask:0xf bank_mask:0xf
	v_mul_f32_e32 v210, 0xbfb8aa3b, v202
	v_mul_f32_e32 v211, 0xbfb8aa3b, v203
	v_mul_f32_e32 v212, 0xbfb8aa3b, v204
	v_mul_f32_e32 v213, 0xbfb8aa3b, v205
	v_exp_f32_e32 v210, v210
	v_exp_f32_e32 v211, v211
	v_exp_f32_e32 v212, v212
	v_exp_f32_e32 v213, v213
	v_add_f32_e32 v210, 1.0, v210
	v_add_f32_e32 v211, 1.0, v211
	v_add_f32_e32 v212, 1.0, v212
	v_add_f32_e32 v213, 1.0, v213
	v_rcp_f32_e32 v210, v210
	v_rcp_f32_e32 v211, v211
	v_rcp_f32_e32 v212, v212
	v_rcp_f32_e32 v213, v213
	v_mul_f32_e32 v202, v202, v210
	v_mul_f32_e32 v203, v203, v211
	v_mul_f32_e32 v204, v204, v212
	v_mul_f32_e32 v205, v205, v213
	v_mul_f32_e32 v202, v202, v206
	v_mul_f32_e32 v203, v203, v207
	v_mul_f32_e32 v204, v204, v208
	v_mul_f32_e32 v205, v205, v209
	v_cvt_pk_bf16_f32 v30, v202, v203
	v_cvt_pk_bf16_f32 v31, v204, v205
	v_fma_f32 v202, v124, v8, v132
	v_fma_f32 v203, v125, v9, v133
	v_fma_f32 v204, v126, v10, v134
	v_fma_f32 v205, v127, v11, v135
	v_fmac_f32_dpp v202, v8, v116 row_shr:1 row_mask:0xf bank_mask:0xf
	v_fmac_f32_dpp v203, v9, v117 row_shr:1 row_mask:0xf bank_mask:0xf
	v_fmac_f32_dpp v204, v10, v118 row_shr:1 row_mask:0xf bank_mask:0xf
	v_fmac_f32_dpp v205, v11, v119 row_shr:1 row_mask:0xf bank_mask:0xf
	v_fmac_f32_dpp v202, v24, v218 row_ror:1 row_mask:0xf bank_mask:0xf
	v_fmac_f32_dpp v203, v25, v219 row_ror:1 row_mask:0xf bank_mask:0xf
	v_fmac_f32_dpp v204, v26, v220 row_ror:1 row_mask:0xf bank_mask:0xf
	v_fmac_f32_dpp v205, v27, v221 row_ror:1 row_mask:0xf bank_mask:0xf
	v_fmac_f32_dpp v202, v8, v128 row_shl:1 row_mask:0xf bank_mask:0xf
	v_fmac_f32_dpp v203, v9, v129 row_shl:1 row_mask:0xf bank_mask:0xf
	v_fmac_f32_dpp v204, v10, v130 row_shl:1 row_mask:0xf bank_mask:0xf
	v_fmac_f32_dpp v205, v11, v131 row_shl:1 row_mask:0xf bank_mask:0xf
	v_fmac_f32_e32 v202, v194, v222
	v_fmac_f32_e32 v203, v195, v223
	v_fmac_f32_e32 v204, v196, v224
	v_fmac_f32_e32 v205, v197, v225
	v_fma_f32 v206, v164, v0, v182
	v_fma_f32 v207, v165, v1, v183
	v_fma_f32 v208, v166, v2, v184
	v_fma_f32 v209, v167, v3, v185
	v_fmac_f32_dpp v206, v0, v160 row_shr:1 row_mask:0xf bank_mask:0xf
	v_fmac_f32_dpp v207, v1, v161 row_shr:1 row_mask:0xf bank_mask:0xf
	v_fmac_f32_dpp v208, v2, v162 row_shr:1 row_mask:0xf bank_mask:0xf
	v_fmac_f32_dpp v209, v3, v163 row_shr:1 row_mask:0xf bank_mask:0xf
	v_fmac_f32_dpp v206, v16, v226 row_ror:1 row_mask:0xf bank_mask:0xf
	v_fmac_f32_dpp v207, v17, v227 row_ror:1 row_mask:0xf bank_mask:0xf
	v_fmac_f32_dpp v208, v18, v228 row_ror:1 row_mask:0xf bank_mask:0xf
	v_fmac_f32_dpp v209, v19, v229 row_ror:1 row_mask:0xf bank_mask:0xf
	v_fmac_f32_dpp v206, v0, v178 row_shl:1 row_mask:0xf bank_mask:0xf
	v_fmac_f32_dpp v207, v1, v179 row_shl:1 row_mask:0xf bank_mask:0xf
	v_fmac_f32_dpp v208, v2, v180 row_shl:1 row_mask:0xf bank_mask:0xf
	v_fmac_f32_dpp v209, v3, v181 row_shl:1 row_mask:0xf bank_mask:0xf
	v_fmac_f32_e32 v206, v198, v232
	v_fmac_f32_e32 v207, v199, v233
	v_fmac_f32_e32 v208, v200, v234
	v_fmac_f32_e32 v209, v201, v235
	v_mul_f32_e32 v210, 0xbfb8aa3b, v202
	v_mul_f32_e32 v211, 0xbfb8aa3b, v203
	v_mul_f32_e32 v212, 0xbfb8aa3b, v204
	v_mul_f32_e32 v213, 0xbfb8aa3b, v205
	v_exp_f32_e32 v210, v210
	v_exp_f32_e32 v211, v211
	v_exp_f32_e32 v212, v212
	v_exp_f32_e32 v213, v213
	v_add_f32_e32 v210, 1.0, v210
	v_add_f32_e32 v211, 1.0, v211
	v_add_f32_e32 v212, 1.0, v212
	v_add_f32_e32 v213, 1.0, v213
	v_rcp_f32_e32 v210, v210
	v_rcp_f32_e32 v211, v211
	v_rcp_f32_e32 v212, v212
	v_rcp_f32_e32 v213, v213
	v_mul_f32_e32 v202, v202, v210
	v_mul_f32_e32 v203, v203, v211
	v_mul_f32_e32 v204, v204, v212
	v_mul_f32_e32 v205, v205, v213
	v_mul_f32_e32 v202, v202, v206
	v_mul_f32_e32 v203, v203, v207
	v_mul_f32_e32 v204, v204, v208
	v_mul_f32_e32 v205, v205, v209
	v_cvt_pk_bf16_f32 v14, v202, v203
	v_cvt_pk_bf16_f32 v15, v204, v205
	global_store_dwordx4 v168, v[140:143], s[76:77]
	v_add_u32_e32 v250, 0x16000, v168
	global_store_dwordx4 v250, v[108:111], s[76:77]
	s_nop 0
	v_add_u32_e32 v250, 0x2c000, v168
	global_store_dwordx4 v250, v[92:95], s[76:77]
	s_nop 0
	v_add_u32_e32 v250, 0x42000, v168
	global_store_dwordx4 v250, v[76:79], s[76:77]
	s_nop 0
	v_add_u32_e32 v250, 0xb0000, v168
	global_store_dwordx4 v250, v[60:63], s[76:77]
	s_nop 0
	v_add_u32_e32 v250, 0xc6000, v168
	global_store_dwordx4 v250, v[44:47], s[76:77]
	s_nop 0
	v_add_u32_e32 v250, 0xdc000, v168
	global_store_dwordx4 v250, v[28:31], s[76:77]
	s_nop 0
	v_add_u32_e32 v250, 0xf2000, v168
	global_store_dwordx4 v250, v[12:15], s[76:77]
	s_nop 0
	s_andn2_b64 vcc, exec, s[6:7]
	s_mov_b64 s[4:5], -1
	s_cbranch_vccnz .LBB0_824
	s_andn2_b64 vcc, exec, s[12:13]
	s_cbranch_vccnz .LBB0_823
	s_barrier
	s_branch .LBB0_823

.LBB0_850:
	s_waitcnt vmcnt(0) lgkmcnt(0)
	s_barrier
	s_branch .LBB0_899
	s_waitcnt vmcnt(0)
	v_readlane_b32 s2, v254, 59
	v_readlane_b32 s3, v254, 60
	s_waitcnt vmcnt(0) lgkmcnt(0)
	s_barrier
	s_and_saveexec_b64 s[6:7], s[2:3]
	s_cbranch_execz .LBB0_898
	v_mov_b32_e32 v0, s78
	s_waitcnt vmcnt(0) expcnt(0) lgkmcnt(0)
	ds_read_b32 v2, v0
	ds_read_b32 v0, v0 offset:4
	s_waitcnt lgkmcnt(1)
	v_cmp_ne_u32_e32 vcc, 0, v2
	s_cbranch_vccnz .LBB0_866
	v_readlane_b32 s4, v254, 0
	v_readlane_b32 s5, v254, 1
	s_load_dword s4, s[4:5], 0x14
	v_readlane_b32 s2, v254, 47
	v_readlane_b32 s3, v254, 48
	s_mov_b32 s22, s78
	s_mov_b32 s0, 1
	s_waitcnt lgkmcnt(0)
	s_lshr_b32 s10, s4, 16
	s_and_b32 s4, s4, 0xffff
	s_cmp_lg_u32 s4, 0
	s_cselect_b64 s[4:5], -1, 0
	s_cmp_lg_u64 s[4:5], 0
	s_addc_u32 s4, s3, 0
	s_cmp_lg_u32 s10, 0
	s_mul_i32 s52, s4, s2
	s_cselect_b64 s[4:5], -1, 0
	s_cmp_lg_u64 s[4:5], 0
	v_readlane_b32 s4, v254, 2
	s_addc_u32 s4, s4, 0
	s_add_u32 s10, s70, 0x4200
	s_addc_u32 s11, s71, 0
	s_add_u32 s12, s70, 0x4400
	s_addc_u32 s13, s71, 0
	s_add_u32 s14, s70, 0x4500
	s_addc_u32 s15, s71, 0
	s_add_u32 s16, s70, 0x4600
	s_addc_u32 s17, s71, 0
	s_add_u32 s34, s70, 0x4700
	s_addc_u32 s35, s71, 0
	s_add_u32 s54, s70, 0x4800
	s_addc_u32 s55, s71, 0
	s_add_u32 s56, s70, 0x4900
	s_addc_u32 s57, s71, 0
	s_add_u32 s74, s70, 0x4a00
	s_addc_u32 s75, s71, 0
	s_add_u32 s86, s70, 0x4b00
	s_addc_u32 s87, s71, 0
	s_add_u32 s88, s70, 0x4c00
	s_addc_u32 s89, s71, 0
	s_add_u32 s90, s70, 0x4d00
	s_addc_u32 s91, s71, 0
	s_add_u32 s92, s70, 0x4e00
	s_addc_u32 s93, s71, 0
	s_add_u32 s94, s70, 0x4f00
	s_addc_u32 s95, s71, 0
	s_add_u32 s96, s70, 0x5000
	s_addc_u32 s97, s71, 0
	s_add_u32 s20, s70, 0x5100
	s_addc_u32 s21, s71, 0
	s_add_u32 s30, s70, 0x5200
	s_addc_u32 s31, s71, 0
	s_mul_i32 s52, s52, s4
	s_add_u32 s4, s70, 0x5300
	s_addc_u32 s5, s71, 0
	v_mov_b32_e32 v16, 0
	s_branch .LBB0_854

.LBB0_899:
	s_lshl_b32 s0, s84, 9
	v_writelane_b32 v254, s0, 55
	s_nop 0
	v_readlane_b32 s2, v254, 47
	s_lshl_b32 s97, s2, 9
	s_cmp_gt_i32 s72, 8
	s_cselect_b64 s[4:5], -1, 0
	s_cmp_lt_i32 s73, 9
	s_cselect_b64 s[6:7], -1, 0
	s_or_b64 s[4:5], s[4:5], s[6:7]
	v_readlane_b32 s3, v254, 48
	s_and_b64 vcc, exec, s[4:5]
	v_writelane_b32 v254, s97, 53
	s_branch .LBB0_957
	v_mov_b32_e32 v0, v230
	v_readlane_b32 s0, v254, 55
	s_nop 1
	v_add_u32_e32 v172, s0, v0
	s_mov_b32 s0, 0x58000
	v_cmp_gt_i32_e32 vcc, s0, v172
	s_and_saveexec_b64 s[6:7], vcc
	s_cbranch_execz .LBB0_907
	s_add_u32 s10, s70, 0x3b00000
	s_addc_u32 s11, s71, 0
	s_add_u32 s12, s70, 0x9300000
	v_readlane_b32 s56, v254, 3
	s_addc_u32 s13, s71, 0
	v_readlane_b32 s60, v254, 7
	v_readlane_b32 s61, v254, 8
	s_add_u32 s14, s60, 0x2c00
	v_readlane_b32 s58, v254, 5
	s_addc_u32 s15, s61, 0
	v_readlane_b32 s59, v254, 6
	s_add_u32 s16, s58, 0x2c00
	s_addc_u32 s17, s59, 0
	s_add_u32 s34, s58, 0x5800
	s_addc_u32 s35, s59, 0
	s_add_u32 s54, s58, 0x8400
	s_addc_u32 s55, s59, 0
	v_readlane_b32 s57, v254, 4
	s_add_u32 s56, s58, 0xb000
	s_addc_u32 s57, s59, 0
	s_add_u32 s74, s58, 0xdc00
	v_lshlrev_b32_e32 v0, 3, v0
	s_addc_u32 s75, s59, 0
	v_lshl_add_u32 v173, s84, 12, v0
	s_lshl_b32 s0, s97, 3
	s_mov_b64 s[86:87], 0
	s_movk_i32 s20, 0x2c00
	v_mov_b64_e32 v[144:145], s[10:11]
	s_mov_b32 s88, 0xbfb8aa3b
	s_movk_i32 s21, 0x1600
	v_readlane_b32 s62, v254, 9
	v_readlane_b32 s63, v254, 10
	s_branch .LBB0_903

.LBB0_1755:
	s_and_b32 s27, s12, 1
	s_sub_i32 s4, s8, 32
	s_ashr_i32 s4, s4, 2
	s_add_i32 s4, s4, 1
	s_cmp_gt_i32 s8, 31
	s_cselect_b32 s4, s4, 0
	s_mul_hi_i32 s5, s4, 0x5800
	s_mulk_i32 s4, 0x5800
	s_add_u32 s4, s33, s4
	s_addc_u32 s5, s50, s5
	v_lshl_add_u32 v236, s8, 8, v164
	v_lshlrev_b32_e32 v236, 2, v236
	v_lshl_or_b32 v229, s9, 7, v166
	v_lshlrev_b32_e32 v229, 2, v229
	global_load_dword v208, v236, s[10:11] offset:0
	global_load_dword v209, v236, s[10:11] offset:64
	global_load_dword v210, v236, s[10:11] offset:128
	global_load_dword v211, v236, s[10:11] offset:192
	global_load_dword v212, v236, s[10:11] offset:512
	global_load_dword v213, v236, s[10:11] offset:576
	global_load_dword v214, v236, s[10:11] offset:640
	global_load_dword v215, v236, s[10:11] offset:704
	global_load_dwordx4 v[200:203], v229, s[4:5]
	global_load_dwordx4 v[204:207], v229, s[4:5] offset:16
	v_add_u32_e32 v224, 0x2c00, v229
	global_load_dwordx4 v[216:219], v224, s[4:5]
	global_load_dwordx4 v[220:223], v224, s[4:5] offset:16
	v_readlane_b32 s36, v254, 5
	v_readlane_b32 s37, v254, 6
	v_readlane_b32 s38, v254, 7
	v_readlane_b32 s39, v254, 8
	s_add_u32 s36, s36, 0x10800
	s_addc_u32 s37, s37, 0
	s_add_u32 s38, s38, 0x5800
	s_addc_u32 s39, s39, 0
	s_mul_i32 s40, s8, 0x160000
	s_lshl_b32 s79, s9, 8
	s_add_i32 s40, s40, s79
	s_add_i32 s40, s40, 0x9300000
	s_add_u32 s40, s40, s70
	s_addc_u32 s41, s71, 0
	v_mul_u32_u24_e32 v171, 0x1600, v164
	v_lshl_add_u32 v171, v166, 1, v171
	s_mov_b32 s32, 0x20800
	v_lshl_add_u32 v228, v166, 2, s32
	v_and_b32_e32 v237, 15, v164
	v_cmp_eq_u32_e64 s[54:55], 0, v237
	v_cmp_eq_u32_e64 s[56:57], 15, v237
	v_and_b32_e32 v231, 8, v237
	v_lshlrev_b32_e32 v231, 9, v231
	s_lshl_b32 s79, s27, 10
	v_add3_u32 v231, v231, v228, s79
	s_waitcnt vmcnt(4)
	v_fmamk_f32 v208, v208, 0x3a800000, v170
	v_fmamk_f32 v209, v209, 0x3a800000, v170
	v_fmamk_f32 v210, v210, 0x3a800000, v170
	v_fmamk_f32 v211, v211, 0x3a800000, v170
	v_fmamk_f32 v212, v212, 0x3a800000, v170
	v_fmamk_f32 v213, v213, 0x3a800000, v170
	v_fmamk_f32 v214, v214, 0x3a800000, v170
	v_fmamk_f32 v215, v215, 0x3a800000, v170
	s_mov_b32 s79, 0x800000
	v_mul_f32_e32 v224, 0x4b800000, v208
	v_mul_f32_e32 v225, 0x4b800000, v209
	v_mul_f32_e32 v226, 0x4b800000, v210
	v_mul_f32_e32 v227, 0x4b800000, v211
	v_mul_f32_e32 v232, 0x4b800000, v212
	v_mul_f32_e32 v233, 0x4b800000, v213
	v_mul_f32_e32 v234, 0x4b800000, v214
	v_mul_f32_e32 v235, 0x4b800000, v215
	v_cmp_gt_f32_e32 vcc, s79, v208
	s_nop 1
	v_cndmask_b32_e32 v208, v208, v224, vcc
	v_rsq_f32_e32 v208, v208
	s_nop 0
	v_mul_f32_e32 v224, 0x45800000, v208
	v_cndmask_b32_e32 v208, v208, v224, vcc
	v_cmp_gt_f32_e32 vcc, s79, v209
	s_nop 1
	v_cndmask_b32_e32 v209, v209, v225, vcc
	v_rsq_f32_e32 v209, v209
	s_nop 0
	v_mul_f32_e32 v225, 0x45800000, v209
	v_cndmask_b32_e32 v209, v209, v225, vcc
	v_cmp_gt_f32_e32 vcc, s79, v210
	s_nop 1
	v_cndmask_b32_e32 v210, v210, v226, vcc
	v_rsq_f32_e32 v210, v210
	s_nop 0
	v_mul_f32_e32 v226, 0x45800000, v210
	v_cndmask_b32_e32 v210, v210, v226, vcc
	v_cmp_gt_f32_e32 vcc, s79, v211
	s_nop 1
	v_cndmask_b32_e32 v211, v211, v227, vcc
	v_rsq_f32_e32 v211, v211
	s_nop 0
	v_mul_f32_e32 v227, 0x45800000, v211
	v_cndmask_b32_e32 v211, v211, v227, vcc
	v_cmp_gt_f32_e32 vcc, s79, v212
	s_nop 1
	v_cndmask_b32_e32 v212, v212, v232, vcc
	v_rsq_f32_e32 v212, v212
	s_nop 0
	v_mul_f32_e32 v232, 0x45800000, v212
	v_cndmask_b32_e32 v212, v212, v232, vcc
	v_cmp_gt_f32_e32 vcc, s79, v213
	s_nop 1
	v_cndmask_b32_e32 v213, v213, v233, vcc
	v_rsq_f32_e32 v213, v213
	s_nop 0
	v_mul_f32_e32 v233, 0x45800000, v213
	v_cndmask_b32_e32 v213, v213, v233, vcc
	v_cmp_gt_f32_e32 vcc, s79, v214
	s_nop 1
	v_cndmask_b32_e32 v214, v214, v234, vcc
	v_rsq_f32_e32 v214, v214
	s_nop 0
	v_mul_f32_e32 v234, 0x45800000, v214
	v_cndmask_b32_e32 v214, v214, v234, vcc
	v_cmp_gt_f32_e32 vcc, s79, v215
	s_nop 1
	v_cndmask_b32_e32 v215, v215, v235, vcc
	v_rsq_f32_e32 v215, v215
	s_nop 0
	v_mul_f32_e32 v235, 0x45800000, v215
	v_cndmask_b32_e32 v215, v215, v235, vcc
	s_waitcnt vmcnt(0)
	v_fma_f32 v124, v124, v208, v200
	v_fma_f32 v125, v125, v208, v201
	v_fma_f32 v126, v126, v208, v202
	v_fma_f32 v127, v127, v208, v203
	v_fma_f32 v120, v120, v208, v204
	v_fma_f32 v121, v121, v208, v205
	v_fma_f32 v122, v122, v208, v206
	v_fma_f32 v123, v123, v208, v207
	v_fma_f32 v108, v108, v208, v216
	v_fma_f32 v109, v109, v208, v217
	v_fma_f32 v110, v110, v208, v218
	v_fma_f32 v111, v111, v208, v219
	v_fma_f32 v104, v104, v208, v220
	v_fma_f32 v105, v105, v208, v221
	v_fma_f32 v106, v106, v208, v222
	v_fma_f32 v107, v107, v208, v223
	v_fma_f32 v116, v116, v209, v200
	v_fma_f32 v117, v117, v209, v201
	v_fma_f32 v118, v118, v209, v202
	v_fma_f32 v119, v119, v209, v203
	v_fma_f32 v112, v112, v209, v204
	v_fma_f32 v113, v113, v209, v205
	v_fma_f32 v114, v114, v209, v206
	v_fma_f32 v115, v115, v209, v207
	v_fma_f32 v100, v100, v209, v216
	v_fma_f32 v101, v101, v209, v217
	v_fma_f32 v102, v102, v209, v218
	v_fma_f32 v103, v103, v209, v219
	v_fma_f32 v92, v92, v209, v220
	v_fma_f32 v93, v93, v209, v221
	v_fma_f32 v94, v94, v209, v222
	v_fma_f32 v95, v95, v209, v223
	v_fma_f32 v96, v96, v210, v200
	v_fma_f32 v97, v97, v210, v201
	v_fma_f32 v98, v98, v210, v202
	v_fma_f32 v99, v99, v210, v203
	v_fma_f32 v88, v88, v210, v204
	v_fma_f32 v89, v89, v210, v205
	v_fma_f32 v90, v90, v210, v206
	v_fma_f32 v91, v91, v210, v207
	v_fma_f32 v84, v84, v210, v216
	v_fma_f32 v85, v85, v210, v217
	v_fma_f32 v86, v86, v210, v218
	v_fma_f32 v87, v87, v210, v219
	v_fma_f32 v76, v76, v210, v220
	v_fma_f32 v77, v77, v210, v221
	v_fma_f32 v78, v78, v210, v222
	v_fma_f32 v79, v79, v210, v223
	v_fma_f32 v80, v80, v211, v200
	v_fma_f32 v81, v81, v211, v201
	v_fma_f32 v82, v82, v211, v202
	v_fma_f32 v83, v83, v211, v203
	v_fma_f32 v72, v72, v211, v204
	v_fma_f32 v73, v73, v211, v205
	v_fma_f32 v74, v74, v211, v206
	v_fma_f32 v75, v75, v211, v207
	v_fma_f32 v68, v68, v211, v216
	v_fma_f32 v69, v69, v211, v217
	v_fma_f32 v70, v70, v211, v218
	v_fma_f32 v71, v71, v211, v219
	v_fma_f32 v64, v64, v211, v220
	v_fma_f32 v65, v65, v211, v221
	v_fma_f32 v66, v66, v211, v222
	v_fma_f32 v67, v67, v211, v223
	v_fma_f32 v60, v60, v212, v200
	v_fma_f32 v61, v61, v212, v201
	v_fma_f32 v62, v62, v212, v202
	v_fma_f32 v63, v63, v212, v203
	v_fma_f32 v56, v56, v212, v204
	v_fma_f32 v57, v57, v212, v205
	v_fma_f32 v58, v58, v212, v206
	v_fma_f32 v59, v59, v212, v207
	v_fma_f32 v52, v52, v212, v216
	v_fma_f32 v53, v53, v212, v217
	v_fma_f32 v54, v54, v212, v218
	v_fma_f32 v55, v55, v212, v219
	v_fma_f32 v44, v44, v212, v220
	v_fma_f32 v45, v45, v212, v221
	v_fma_f32 v46, v46, v212, v222
	v_fma_f32 v47, v47, v212, v223
	v_fma_f32 v48, v48, v213, v200
	v_fma_f32 v49, v49, v213, v201
	v_fma_f32 v50, v50, v213, v202
	v_fma_f32 v51, v51, v213, v203
	v_fma_f32 v40, v40, v213, v204
	v_fma_f32 v41, v41, v213, v205
	v_fma_f32 v42, v42, v213, v206
	v_fma_f32 v43, v43, v213, v207
	v_fma_f32 v36, v36, v213, v216
	v_fma_f32 v37, v37, v213, v217
	v_fma_f32 v38, v38, v213, v218
	v_fma_f32 v39, v39, v213, v219
	v_fma_f32 v28, v28, v213, v220
	v_fma_f32 v29, v29, v213, v221
	v_fma_f32 v30, v30, v213, v222
	v_fma_f32 v31, v31, v213, v223
	v_fma_f32 v32, v32, v214, v200
	v_fma_f32 v33, v33, v214, v201
	v_fma_f32 v34, v34, v214, v202
	v_fma_f32 v35, v35, v214, v203
	v_fma_f32 v24, v24, v214, v204
	v_fma_f32 v25, v25, v214, v205
	v_fma_f32 v26, v26, v214, v206
	v_fma_f32 v27, v27, v214, v207
	v_fma_f32 v20, v20, v214, v216
	v_fma_f32 v21, v21, v214, v217
	v_fma_f32 v22, v22, v214, v218
	v_fma_f32 v23, v23, v214, v219
	v_fma_f32 v12, v12, v214, v220
	v_fma_f32 v13, v13, v214, v221
	v_fma_f32 v14, v14, v214, v222
	v_fma_f32 v15, v15, v214, v223
	v_fma_f32 v16, v16, v215, v200
	v_fma_f32 v17, v17, v215, v201
	v_fma_f32 v18, v18, v215, v202
	v_fma_f32 v19, v19, v215, v203
	v_fma_f32 v8, v8, v215, v204
	v_fma_f32 v9, v9, v215, v205
	v_fma_f32 v10, v10, v215, v206
	v_fma_f32 v11, v11, v215, v207
	v_fma_f32 v4, v4, v215, v216
	v_fma_f32 v5, v5, v215, v217
	v_fma_f32 v6, v6, v215, v218
	v_fma_f32 v7, v7, v215, v219
	v_fma_f32 v0, v0, v215, v220
	v_fma_f32 v1, v1, v215, v221
	v_fma_f32 v2, v2, v215, v222
	v_fma_f32 v3, v3, v215, v223
	global_load_dwordx4 v[128:131], v229, s[36:37]
	v_add_u32_e32 v211, 0x5800, v229
	global_load_dwordx4 v[132:135], v211, s[36:37]
	v_add_u32_e32 v210, 0xb000, v229
	global_load_dwordx4 v[136:139], v210, s[36:37]
	global_load_dwordx4 v[140:143], v229, s[38:39]
	v_add_u32_e32 v210, 0x2c00, v229
	global_load_dwordx4 v[160:163], v210, s[36:37]
	v_add_u32_e32 v211, 0x8400, v229
	global_load_dwordx4 v[172:175], v211, s[36:37]
	v_add_u32_e32 v210, 0xdc00, v229
	global_load_dwordx4 v[176:179], v210, s[36:37]
	v_add_u32_e32 v211, 0x2c00, v229
	global_load_dwordx4 v[180:183], v211, s[38:39]
	v_mov_b32_e32 v212, 0
	v_mov_b32_e32 v213, 0
	v_mov_b32_e32 v214, 0
	v_mov_b32_e32 v215, 0
	s_lshl_b32 s96, s27, 12
	s_sub_i32 s96, 0x2000, s96
	s_mul_i32 s94, s27, 0x1400
	s_add_i32 s94, s94, 0xc00
	s_lshl_b32 s79, s27, 10
	s_add_i32 s95, s79, 5120
	s_add_i32 s92, s79, 1024
	s_mov_b64 s[58:59], exec
	s_mov_b64 exec, s[54:55]
	v_add_u32_e32 v250, s96, v228
	ds_write_b128 v250, v[124:127] offset:0
	ds_write_b128 v250, v[120:123] offset:16
	ds_write_b128 v250, v[108:111] offset:512
	ds_write_b128 v250, v[104:107] offset:528
	v_add_u32_e32 v250, s95, v228
	ds_write_b128 v250, v[60:63] offset:0
	ds_write_b128 v250, v[56:59] offset:16
	ds_write_b128 v250, v[52:55] offset:512
	ds_write_b128 v250, v[44:47] offset:528
	ds_write_b128 v228, v[212:215] offset:0
	ds_write_b128 v228, v[212:215] offset:16
	ds_write_b128 v228, v[212:215] offset:512
	ds_write_b128 v228, v[212:215] offset:528
	s_mov_b64 exec, s[56:57]
	v_add_u32_e32 v251, s92, v228
	ds_write_b128 v251, v[80:83] offset:0
	ds_write_b128 v251, v[72:75] offset:16
	ds_write_b128 v251, v[68:71] offset:512
	ds_write_b128 v251, v[64:67] offset:528
	v_add_u32_e32 v251, s94, v228
	ds_write_b128 v251, v[16:19] offset:0
	ds_write_b128 v251, v[8:11] offset:16
	ds_write_b128 v251, v[4:7] offset:512
	ds_write_b128 v251, v[0:3] offset:528
	ds_write_b128 v228, v[212:215] offset:7168
	ds_write_b128 v228, v[212:215] offset:7184
	ds_write_b128 v228, v[212:215] offset:7680
	ds_write_b128 v228, v[212:215] offset:7696
	s_mov_b64 exec, s[58:59]
	s_waitcnt lgkmcnt(0)
	s_barrier
	ds_read_b128 v[184:187], v231 offset:0
	ds_read_b128 v[188:191], v231 offset:512
	ds_read_b128 v[192:195], v231 offset:2048
	ds_read_b128 v[196:199], v231 offset:2560
	s_waitcnt vmcnt(0)
	v_cndmask_b32_e64 v216, 0, v128, s[54:55]
	v_cndmask_b32_e64 v220, 0, v136, s[56:57]
	v_cndmask_b32_e64 v217, 0, v129, s[54:55]
	v_cndmask_b32_e64 v221, 0, v137, s[56:57]
	v_cndmask_b32_e64 v218, 0, v130, s[54:55]
	v_cndmask_b32_e64 v222, 0, v138, s[56:57]
	v_cndmask_b32_e64 v219, 0, v131, s[54:55]
	v_cndmask_b32_e64 v223, 0, v139, s[56:57]
	v_cndmask_b32_e64 v224, 0, v160, s[54:55]
	v_cndmask_b32_e64 v232, 0, v176, s[56:57]
	v_cndmask_b32_e64 v225, 0, v161, s[54:55]
	v_cndmask_b32_e64 v233, 0, v177, s[56:57]
	v_cndmask_b32_e64 v226, 0, v162, s[54:55]
	v_cndmask_b32_e64 v234, 0, v178, s[56:57]
	v_cndmask_b32_e64 v227, 0, v163, s[54:55]
	v_cndmask_b32_e64 v235, 0, v179, s[56:57]
	s_waitcnt lgkmcnt(0)
	s_nop 1
	v_fma_f32 v200, v132, v124, v140
	v_fma_f32 v201, v133, v125, v141
	v_fma_f32 v202, v134, v126, v142
	v_fma_f32 v203, v135, v127, v143
	v_fmac_f32_dpp v200, v124, v128 row_shr:1 row_mask:0xf bank_mask:0xf
	v_fmac_f32_dpp v201, v125, v129 row_shr:1 row_mask:0xf bank_mask:0xf
	v_fmac_f32_dpp v202, v126, v130 row_shr:1 row_mask:0xf bank_mask:0xf
	v_fmac_f32_dpp v203, v127, v131 row_shr:1 row_mask:0xf bank_mask:0xf
	v_fmac_f32_e32 v200, v184, v216
	v_fmac_f32_e32 v201, v185, v217
	v_fmac_f32_e32 v202, v186, v218
	v_fmac_f32_e32 v203, v187, v219
	v_fmac_f32_dpp v200, v124, v136 row_shl:1 row_mask:0xf bank_mask:0xf
	v_fmac_f32_dpp v201, v125, v137 row_shl:1 row_mask:0xf bank_mask:0xf
	v_fmac_f32_dpp v202, v126, v138 row_shl:1 row_mask:0xf bank_mask:0xf
	v_fmac_f32_dpp v203, v127, v139 row_shl:1 row_mask:0xf bank_mask:0xf
	v_fmac_f32_dpp v200, v116, v220 row_ror:15 row_mask:0xf bank_mask:0xf
	v_fmac_f32_dpp v201, v117, v221 row_ror:15 row_mask:0xf bank_mask:0xf
	v_fmac_f32_dpp v202, v118, v222 row_ror:15 row_mask:0xf bank_mask:0xf
	v_fmac_f32_dpp v203, v119, v223 row_ror:15 row_mask:0xf bank_mask:0xf
	v_fma_f32 v204, v172, v108, v180
	v_fma_f32 v205, v173, v109, v181
	v_fma_f32 v206, v174, v110, v182
	v_fma_f32 v207, v175, v111, v183
	v_fmac_f32_dpp v204, v108, v160 row_shr:1 row_mask:0xf bank_mask:0xf
	v_fmac_f32_dpp v205, v109, v161 row_shr:1 row_mask:0xf bank_mask:0xf
	v_fmac_f32_dpp v206, v110, v162 row_shr:1 row_mask:0xf bank_mask:0xf
	v_fmac_f32_dpp v207, v111, v163 row_shr:1 row_mask:0xf bank_mask:0xf
	v_fmac_f32_e32 v204, v188, v224
	v_fmac_f32_e32 v205, v189, v225
	v_fmac_f32_e32 v206, v190, v226
	v_fmac_f32_e32 v207, v191, v227
	v_fmac_f32_dpp v204, v108, v176 row_shl:1 row_mask:0xf bank_mask:0xf
	v_fmac_f32_dpp v205, v109, v177 row_shl:1 row_mask:0xf bank_mask:0xf
	v_fmac_f32_dpp v206, v110, v178 row_shl:1 row_mask:0xf bank_mask:0xf
	v_fmac_f32_dpp v207, v111, v179 row_shl:1 row_mask:0xf bank_mask:0xf
	v_fmac_f32_dpp v204, v100, v232 row_ror:15 row_mask:0xf bank_mask:0xf
	v_fmac_f32_dpp v205, v101, v233 row_ror:15 row_mask:0xf bank_mask:0xf
	v_fmac_f32_dpp v206, v102, v234 row_ror:15 row_mask:0xf bank_mask:0xf
	v_fmac_f32_dpp v207, v103, v235 row_ror:15 row_mask:0xf bank_mask:0xf
	v_mul_f32_e32 v208, 0xbfb8aa3b, v200
	v_mul_f32_e32 v209, 0xbfb8aa3b, v201
	v_mul_f32_e32 v210, 0xbfb8aa3b, v202
	v_mul_f32_e32 v211, 0xbfb8aa3b, v203
	v_exp_f32_e32 v208, v208
	v_exp_f32_e32 v209, v209
	v_exp_f32_e32 v210, v210
	v_exp_f32_e32 v211, v211
	v_add_f32_e32 v208, 1.0, v208
	v_add_f32_e32 v209, 1.0, v209
	v_add_f32_e32 v210, 1.0, v210
	v_add_f32_e32 v211, 1.0, v211
	v_rcp_f32_e32 v208, v208
	v_rcp_f32_e32 v209, v209
	v_rcp_f32_e32 v210, v210
	v_rcp_f32_e32 v211, v211
	v_mul_f32_e32 v200, v200, v208
	v_mul_f32_e32 v201, v201, v209
	v_mul_f32_e32 v202, v202, v210
	v_mul_f32_e32 v203, v203, v211
	v_mul_f32_e32 v200, v200, v204
	v_mul_f32_e32 v201, v201, v205
	v_mul_f32_e32 v202, v202, v206
	v_mul_f32_e32 v203, v203, v207
	v_cvt_pk_bf16_f32 v236, v200, v201
	v_cvt_pk_bf16_f32 v237, v202, v203
	v_fma_f32 v200, v132, v116, v140
	v_fma_f32 v201, v133, v117, v141
	v_fma_f32 v202, v134, v118, v142
	v_fma_f32 v203, v135, v119, v143
	v_fmac_f32_dpp v200, v116, v128 row_shr:1 row_mask:0xf bank_mask:0xf
	v_fmac_f32_dpp v201, v117, v129 row_shr:1 row_mask:0xf bank_mask:0xf
	v_fmac_f32_dpp v202, v118, v130 row_shr:1 row_mask:0xf bank_mask:0xf
	v_fmac_f32_dpp v203, v119, v131 row_shr:1 row_mask:0xf bank_mask:0xf
	v_fmac_f32_dpp v200, v124, v216 row_ror:1 row_mask:0xf bank_mask:0xf
	v_fmac_f32_dpp v201, v125, v217 row_ror:1 row_mask:0xf bank_mask:0xf
	v_fmac_f32_dpp v202, v126, v218 row_ror:1 row_mask:0xf bank_mask:0xf
	v_fmac_f32_dpp v203, v127, v219 row_ror:1 row_mask:0xf bank_mask:0xf
	v_fmac_f32_dpp v200, v116, v136 row_shl:1 row_mask:0xf bank_mask:0xf
	v_fmac_f32_dpp v201, v117, v137 row_shl:1 row_mask:0xf bank_mask:0xf
	v_fmac_f32_dpp v202, v118, v138 row_shl:1 row_mask:0xf bank_mask:0xf
	v_fmac_f32_dpp v203, v119, v139 row_shl:1 row_mask:0xf bank_mask:0xf
	v_fmac_f32_dpp v200, v96, v220 row_ror:15 row_mask:0xf bank_mask:0xf
	v_fmac_f32_dpp v201, v97, v221 row_ror:15 row_mask:0xf bank_mask:0xf
	v_fmac_f32_dpp v202, v98, v222 row_ror:15 row_mask:0xf bank_mask:0xf
	v_fmac_f32_dpp v203, v99, v223 row_ror:15 row_mask:0xf bank_mask:0xf
	v_fma_f32 v204, v172, v100, v180
	v_fma_f32 v205, v173, v101, v181
	v_fma_f32 v206, v174, v102, v182
	v_fma_f32 v207, v175, v103, v183
	v_fmac_f32_dpp v204, v100, v160 row_shr:1 row_mask:0xf bank_mask:0xf
	v_fmac_f32_dpp v205, v101, v161 row_shr:1 row_mask:0xf bank_mask:0xf
	v_fmac_f32_dpp v206, v102, v162 row_shr:1 row_mask:0xf bank_mask:0xf
	v_fmac_f32_dpp v207, v103, v163 row_shr:1 row_mask:0xf bank_mask:0xf
	v_fmac_f32_dpp v204, v108, v224 row_ror:1 row_mask:0xf bank_mask:0xf
	v_fmac_f32_dpp v205, v109, v225 row_ror:1 row_mask:0xf bank_mask:0xf
	v_fmac_f32_dpp v206, v110, v226 row_ror:1 row_mask:0xf bank_mask:0xf
	v_fmac_f32_dpp v207, v111, v227 row_ror:1 row_mask:0xf bank_mask:0xf
	v_fmac_f32_dpp v204, v100, v176 row_shl:1 row_mask:0xf bank_mask:0xf
	v_fmac_f32_dpp v205, v101, v177 row_shl:1 row_mask:0xf bank_mask:0xf
	v_fmac_f32_dpp v206, v102, v178 row_shl:1 row_mask:0xf bank_mask:0xf
	v_fmac_f32_dpp v207, v103, v179 row_shl:1 row_mask:0xf bank_mask:0xf
	v_fmac_f32_dpp v204, v84, v232 row_ror:15 row_mask:0xf bank_mask:0xf
	v_fmac_f32_dpp v205, v85, v233 row_ror:15 row_mask:0xf bank_mask:0xf
	v_fmac_f32_dpp v206, v86, v234 row_ror:15 row_mask:0xf bank_mask:0xf
	v_fmac_f32_dpp v207, v87, v235 row_ror:15 row_mask:0xf bank_mask:0xf
	v_mul_f32_e32 v208, 0xbfb8aa3b, v200
	v_mul_f32_e32 v209, 0xbfb8aa3b, v201
	v_mul_f32_e32 v210, 0xbfb8aa3b, v202
	v_mul_f32_e32 v211, 0xbfb8aa3b, v203
	v_exp_f32_e32 v208, v208
	v_exp_f32_e32 v209, v209
	v_exp_f32_e32 v210, v210
	v_exp_f32_e32 v211, v211
	v_add_f32_e32 v208, 1.0, v208
	v_add_f32_e32 v209, 1.0, v209
	v_add_f32_e32 v210, 1.0, v210
	v_add_f32_e32 v211, 1.0, v211
	v_rcp_f32_e32 v208, v208
	v_rcp_f32_e32 v209, v209
	v_rcp_f32_e32 v210, v210
	v_rcp_f32_e32 v211, v211
	v_mul_f32_e32 v200, v200, v208
	v_mul_f32_e32 v201, v201, v209
	v_mul_f32_e32 v202, v202, v210
	v_mul_f32_e32 v203, v203, v211
	v_mul_f32_e32 v200, v200, v204
	v_mul_f32_e32 v201, v201, v205
	v_mul_f32_e32 v202, v202, v206
	v_mul_f32_e32 v203, v203, v207
	v_cvt_pk_bf16_f32 v238, v200, v201
	v_cvt_pk_bf16_f32 v239, v202, v203
	v_fma_f32 v200, v132, v96, v140
	v_fma_f32 v201, v133, v97, v141
	v_fma_f32 v202, v134, v98, v142
	v_fma_f32 v203, v135, v99, v143
	v_fmac_f32_dpp v200, v96, v128 row_shr:1 row_mask:0xf bank_mask:0xf
	v_fmac_f32_dpp v201, v97, v129 row_shr:1 row_mask:0xf bank_mask:0xf
	v_fmac_f32_dpp v202, v98, v130 row_shr:1 row_mask:0xf bank_mask:0xf
	v_fmac_f32_dpp v203, v99, v131 row_shr:1 row_mask:0xf bank_mask:0xf
	v_fmac_f32_dpp v200, v116, v216 row_ror:1 row_mask:0xf bank_mask:0xf
	v_fmac_f32_dpp v201, v117, v217 row_ror:1 row_mask:0xf bank_mask:0xf
	v_fmac_f32_dpp v202, v118, v218 row_ror:1 row_mask:0xf bank_mask:0xf
	v_fmac_f32_dpp v203, v119, v219 row_ror:1 row_mask:0xf bank_mask:0xf
	v_fmac_f32_dpp v200, v96, v136 row_shl:1 row_mask:0xf bank_mask:0xf
	v_fmac_f32_dpp v201, v97, v137 row_shl:1 row_mask:0xf bank_mask:0xf
	v_fmac_f32_dpp v202, v98, v138 row_shl:1 row_mask:0xf bank_mask:0xf
	v_fmac_f32_dpp v203, v99, v139 row_shl:1 row_mask:0xf bank_mask:0xf
	v_fmac_f32_dpp v200, v80, v220 row_ror:15 row_mask:0xf bank_mask:0xf
	v_fmac_f32_dpp v201, v81, v221 row_ror:15 row_mask:0xf bank_mask:0xf
	v_fmac_f32_dpp v202, v82, v222 row_ror:15 row_mask:0xf bank_mask:0xf
	v_fmac_f32_dpp v203, v83, v223 row_ror:15 row_mask:0xf bank_mask:0xf
	v_fma_f32 v204, v172, v84, v180
	v_fma_f32 v205, v173, v85, v181
	v_fma_f32 v206, v174, v86, v182
	v_fma_f32 v207, v175, v87, v183
	v_fmac_f32_dpp v204, v84, v160 row_shr:1 row_mask:0xf bank_mask:0xf
	v_fmac_f32_dpp v205, v85, v161 row_shr:1 row_mask:0xf bank_mask:0xf
	v_fmac_f32_dpp v206, v86, v162 row_shr:1 row_mask:0xf bank_mask:0xf
	v_fmac_f32_dpp v207, v87, v163 row_shr:1 row_mask:0xf bank_mask:0xf
	v_fmac_f32_dpp v204, v100, v224 row_ror:1 row_mask:0xf bank_mask:0xf
	v_fmac_f32_dpp v205, v101, v225 row_ror:1 row_mask:0xf bank_mask:0xf
	v_fmac_f32_dpp v206, v102, v226 row_ror:1 row_mask:0xf bank_mask:0xf
	v_fmac_f32_dpp v207, v103, v227 row_ror:1 row_mask:0xf bank_mask:0xf
	v_fmac_f32_dpp v204, v84, v176 row_shl:1 row_mask:0xf bank_mask:0xf
	v_fmac_f32_dpp v205, v85, v177 row_shl:1 row_mask:0xf bank_mask:0xf
	v_fmac_f32_dpp v206, v86, v178 row_shl:1 row_mask:0xf bank_mask:0xf
	v_fmac_f32_dpp v207, v87, v179 row_shl:1 row_mask:0xf bank_mask:0xf
	v_fmac_f32_dpp v204, v68, v232 row_ror:15 row_mask:0xf bank_mask:0xf
	v_fmac_f32_dpp v205, v69, v233 row_ror:15 row_mask:0xf bank_mask:0xf
	v_fmac_f32_dpp v206, v70, v234 row_ror:15 row_mask:0xf bank_mask:0xf
	v_fmac_f32_dpp v207, v71, v235 row_ror:15 row_mask:0xf bank_mask:0xf
	v_mul_f32_e32 v208, 0xbfb8aa3b, v200
	v_mul_f32_e32 v209, 0xbfb8aa3b, v201
	v_mul_f32_e32 v210, 0xbfb8aa3b, v202
	v_mul_f32_e32 v211, 0xbfb8aa3b, v203
	v_exp_f32_e32 v208, v208
	v_exp_f32_e32 v209, v209
	v_exp_f32_e32 v210, v210
	v_exp_f32_e32 v211, v211
	v_add_f32_e32 v208, 1.0, v208
	v_add_f32_e32 v209, 1.0, v209
	v_add_f32_e32 v210, 1.0, v210
	v_add_f32_e32 v211, 1.0, v211
	v_rcp_f32_e32 v208, v208
	v_rcp_f32_e32 v209, v209
	v_rcp_f32_e32 v210, v210
	v_rcp_f32_e32 v211, v211
	v_mul_f32_e32 v200, v200, v208
	v_mul_f32_e32 v201, v201, v209
	v_mul_f32_e32 v202, v202, v210
	v_mul_f32_e32 v203, v203, v211
	v_mul_f32_e32 v200, v200, v204
	v_mul_f32_e32 v201, v201, v205
	v_mul_f32_e32 v202, v202, v206
	v_mul_f32_e32 v203, v203, v207
	v_cvt_pk_bf16_f32 v240, v200, v201
	v_cvt_pk_bf16_f32 v241, v202, v203
	v_fma_f32 v200, v132, v80, v140
	v_fma_f32 v201, v133, v81, v141
	v_fma_f32 v202, v134, v82, v142
	v_fma_f32 v203, v135, v83, v143
	v_fmac_f32_dpp v200, v80, v128 row_shr:1 row_mask:0xf bank_mask:0xf
	v_fmac_f32_dpp v201, v81, v129 row_shr:1 row_mask:0xf bank_mask:0xf
	v_fmac_f32_dpp v202, v82, v130 row_shr:1 row_mask:0xf bank_mask:0xf
	v_fmac_f32_dpp v203, v83, v131 row_shr:1 row_mask:0xf bank_mask:0xf
	v_fmac_f32_dpp v200, v96, v216 row_ror:1 row_mask:0xf bank_mask:0xf
	v_fmac_f32_dpp v201, v97, v217 row_ror:1 row_mask:0xf bank_mask:0xf
	v_fmac_f32_dpp v202, v98, v218 row_ror:1 row_mask:0xf bank_mask:0xf
	v_fmac_f32_dpp v203, v99, v219 row_ror:1 row_mask:0xf bank_mask:0xf
	v_fmac_f32_dpp v200, v80, v136 row_shl:1 row_mask:0xf bank_mask:0xf
	v_fmac_f32_dpp v201, v81, v137 row_shl:1 row_mask:0xf bank_mask:0xf
	v_fmac_f32_dpp v202, v82, v138 row_shl:1 row_mask:0xf bank_mask:0xf
	v_fmac_f32_dpp v203, v83, v139 row_shl:1 row_mask:0xf bank_mask:0xf
	v_fmac_f32_e32 v200, v184, v220
	v_fmac_f32_e32 v201, v185, v221
	v_fmac_f32_e32 v202, v186, v222
	v_fmac_f32_e32 v203, v187, v223
	v_fma_f32 v204, v172, v68, v180
	v_fma_f32 v205, v173, v69, v181
	v_fma_f32 v206, v174, v70, v182
	v_fma_f32 v207, v175, v71, v183
	v_fmac_f32_dpp v204, v68, v160 row_shr:1 row_mask:0xf bank_mask:0xf
	v_fmac_f32_dpp v205, v69, v161 row_shr:1 row_mask:0xf bank_mask:0xf
	v_fmac_f32_dpp v206, v70, v162 row_shr:1 row_mask:0xf bank_mask:0xf
	v_fmac_f32_dpp v207, v71, v163 row_shr:1 row_mask:0xf bank_mask:0xf
	v_fmac_f32_dpp v204, v84, v224 row_ror:1 row_mask:0xf bank_mask:0xf
	v_fmac_f32_dpp v205, v85, v225 row_ror:1 row_mask:0xf bank_mask:0xf
	v_fmac_f32_dpp v206, v86, v226 row_ror:1 row_mask:0xf bank_mask:0xf
	v_fmac_f32_dpp v207, v87, v227 row_ror:1 row_mask:0xf bank_mask:0xf
	v_fmac_f32_dpp v204, v68, v176 row_shl:1 row_mask:0xf bank_mask:0xf
	v_fmac_f32_dpp v205, v69, v177 row_shl:1 row_mask:0xf bank_mask:0xf
	v_fmac_f32_dpp v206, v70, v178 row_shl:1 row_mask:0xf bank_mask:0xf
	v_fmac_f32_dpp v207, v71, v179 row_shl:1 row_mask:0xf bank_mask:0xf
	v_fmac_f32_e32 v204, v188, v232
	v_fmac_f32_e32 v205, v189, v233
	v_fmac_f32_e32 v206, v190, v234
	v_fmac_f32_e32 v207, v191, v235
	v_mul_f32_e32 v208, 0xbfb8aa3b, v200
	v_mul_f32_e32 v209, 0xbfb8aa3b, v201
	v_mul_f32_e32 v210, 0xbfb8aa3b, v202
	v_mul_f32_e32 v211, 0xbfb8aa3b, v203
	v_exp_f32_e32 v208, v208
	v_exp_f32_e32 v209, v209
	v_exp_f32_e32 v210, v210
	v_exp_f32_e32 v211, v211
	v_add_f32_e32 v208, 1.0, v208
	v_add_f32_e32 v209, 1.0, v209
	v_add_f32_e32 v210, 1.0, v210
	v_add_f32_e32 v211, 1.0, v211
	v_rcp_f32_e32 v208, v208
	v_rcp_f32_e32 v209, v209
	v_rcp_f32_e32 v210, v210
	v_rcp_f32_e32 v211, v211
	v_mul_f32_e32 v200, v200, v208
	v_mul_f32_e32 v201, v201, v209
	v_mul_f32_e32 v202, v202, v210
	v_mul_f32_e32 v203, v203, v211
	v_mul_f32_e32 v200, v200, v204
	v_mul_f32_e32 v201, v201, v205
	v_mul_f32_e32 v202, v202, v206
	v_mul_f32_e32 v203, v203, v207
	v_cvt_pk_bf16_f32 v242, v200, v201
	v_cvt_pk_bf16_f32 v243, v202, v203
	v_fma_f32 v200, v132, v60, v140
	v_fma_f32 v201, v133, v61, v141
	v_fma_f32 v202, v134, v62, v142
	v_fma_f32 v203, v135, v63, v143
	v_fmac_f32_dpp v200, v60, v128 row_shr:1 row_mask:0xf bank_mask:0xf
	v_fmac_f32_dpp v201, v61, v129 row_shr:1 row_mask:0xf bank_mask:0xf
	v_fmac_f32_dpp v202, v62, v130 row_shr:1 row_mask:0xf bank_mask:0xf
	v_fmac_f32_dpp v203, v63, v131 row_shr:1 row_mask:0xf bank_mask:0xf
	v_fmac_f32_e32 v200, v192, v216
	v_fmac_f32_e32 v201, v193, v217
	v_fmac_f32_e32 v202, v194, v218
	v_fmac_f32_e32 v203, v195, v219
	v_fmac_f32_dpp v200, v60, v136 row_shl:1 row_mask:0xf bank_mask:0xf
	v_fmac_f32_dpp v201, v61, v137 row_shl:1 row_mask:0xf bank_mask:0xf
	v_fmac_f32_dpp v202, v62, v138 row_shl:1 row_mask:0xf bank_mask:0xf
	v_fmac_f32_dpp v203, v63, v139 row_shl:1 row_mask:0xf bank_mask:0xf
	v_fmac_f32_dpp v200, v48, v220 row_ror:15 row_mask:0xf bank_mask:0xf
	v_fmac_f32_dpp v201, v49, v221 row_ror:15 row_mask:0xf bank_mask:0xf
	v_fmac_f32_dpp v202, v50, v222 row_ror:15 row_mask:0xf bank_mask:0xf
	v_fmac_f32_dpp v203, v51, v223 row_ror:15 row_mask:0xf bank_mask:0xf
	v_fma_f32 v204, v172, v52, v180
	v_fma_f32 v205, v173, v53, v181
	v_fma_f32 v206, v174, v54, v182
	v_fma_f32 v207, v175, v55, v183
	v_fmac_f32_dpp v204, v52, v160 row_shr:1 row_mask:0xf bank_mask:0xf
	v_fmac_f32_dpp v205, v53, v161 row_shr:1 row_mask:0xf bank_mask:0xf
	v_fmac_f32_dpp v206, v54, v162 row_shr:1 row_mask:0xf bank_mask:0xf
	v_fmac_f32_dpp v207, v55, v163 row_shr:1 row_mask:0xf bank_mask:0xf
	v_fmac_f32_e32 v204, v196, v224
	v_fmac_f32_e32 v205, v197, v225
	v_fmac_f32_e32 v206, v198, v226
	v_fmac_f32_e32 v207, v199, v227
	v_fmac_f32_dpp v204, v52, v176 row_shl:1 row_mask:0xf bank_mask:0xf
	v_fmac_f32_dpp v205, v53, v177 row_shl:1 row_mask:0xf bank_mask:0xf
	v_fmac_f32_dpp v206, v54, v178 row_shl:1 row_mask:0xf bank_mask:0xf
	v_fmac_f32_dpp v207, v55, v179 row_shl:1 row_mask:0xf bank_mask:0xf
	v_fmac_f32_dpp v204, v36, v232 row_ror:15 row_mask:0xf bank_mask:0xf
	v_fmac_f32_dpp v205, v37, v233 row_ror:15 row_mask:0xf bank_mask:0xf
	v_fmac_f32_dpp v206, v38, v234 row_ror:15 row_mask:0xf bank_mask:0xf
	v_fmac_f32_dpp v207, v39, v235 row_ror:15 row_mask:0xf bank_mask:0xf
	v_mul_f32_e32 v208, 0xbfb8aa3b, v200
	v_mul_f32_e32 v209, 0xbfb8aa3b, v201
	v_mul_f32_e32 v210, 0xbfb8aa3b, v202
	v_mul_f32_e32 v211, 0xbfb8aa3b, v203
	v_exp_f32_e32 v208, v208
	v_exp_f32_e32 v209, v209
	v_exp_f32_e32 v210, v210
	v_exp_f32_e32 v211, v211
	v_add_f32_e32 v208, 1.0, v208
	v_add_f32_e32 v209, 1.0, v209
	v_add_f32_e32 v210, 1.0, v210
	v_add_f32_e32 v211, 1.0, v211
	v_rcp_f32_e32 v208, v208
	v_rcp_f32_e32 v209, v209
	v_rcp_f32_e32 v210, v210
	v_rcp_f32_e32 v211, v211
	v_mul_f32_e32 v200, v200, v208
	v_mul_f32_e32 v201, v201, v209
	v_mul_f32_e32 v202, v202, v210
	v_mul_f32_e32 v203, v203, v211
	v_mul_f32_e32 v200, v200, v204
	v_mul_f32_e32 v201, v201, v205
	v_mul_f32_e32 v202, v202, v206
	v_mul_f32_e32 v203, v203, v207
	v_cvt_pk_bf16_f32 v244, v200, v201
	v_cvt_pk_bf16_f32 v245, v202, v203
	v_fma_f32 v200, v132, v48, v140
	v_fma_f32 v201, v133, v49, v141
	v_fma_f32 v202, v134, v50, v142
	v_fma_f32 v203, v135, v51, v143
	v_fmac_f32_dpp v200, v48, v128 row_shr:1 row_mask:0xf bank_mask:0xf
	v_fmac_f32_dpp v201, v49, v129 row_shr:1 row_mask:0xf bank_mask:0xf
	v_fmac_f32_dpp v202, v50, v130 row_shr:1 row_mask:0xf bank_mask:0xf
	v_fmac_f32_dpp v203, v51, v131 row_shr:1 row_mask:0xf bank_mask:0xf
	v_fmac_f32_dpp v200, v60, v216 row_ror:1 row_mask:0xf bank_mask:0xf
	v_fmac_f32_dpp v201, v61, v217 row_ror:1 row_mask:0xf bank_mask:0xf
	v_fmac_f32_dpp v202, v62, v218 row_ror:1 row_mask:0xf bank_mask:0xf
	v_fmac_f32_dpp v203, v63, v219 row_ror:1 row_mask:0xf bank_mask:0xf
	v_fmac_f32_dpp v200, v48, v136 row_shl:1 row_mask:0xf bank_mask:0xf
	v_fmac_f32_dpp v201, v49, v137 row_shl:1 row_mask:0xf bank_mask:0xf
	v_fmac_f32_dpp v202, v50, v138 row_shl:1 row_mask:0xf bank_mask:0xf
	v_fmac_f32_dpp v203, v51, v139 row_shl:1 row_mask:0xf bank_mask:0xf
	v_fmac_f32_dpp v200, v32, v220 row_ror:15 row_mask:0xf bank_mask:0xf
	v_fmac_f32_dpp v201, v33, v221 row_ror:15 row_mask:0xf bank_mask:0xf
	v_fmac_f32_dpp v202, v34, v222 row_ror:15 row_mask:0xf bank_mask:0xf
	v_fmac_f32_dpp v203, v35, v223 row_ror:15 row_mask:0xf bank_mask:0xf
	v_fma_f32 v204, v172, v36, v180
	v_fma_f32 v205, v173, v37, v181
	v_fma_f32 v206, v174, v38, v182
	v_fma_f32 v207, v175, v39, v183
	v_fmac_f32_dpp v204, v36, v160 row_shr:1 row_mask:0xf bank_mask:0xf
	v_fmac_f32_dpp v205, v37, v161 row_shr:1 row_mask:0xf bank_mask:0xf
	v_fmac_f32_dpp v206, v38, v162 row_shr:1 row_mask:0xf bank_mask:0xf
	v_fmac_f32_dpp v207, v39, v163 row_shr:1 row_mask:0xf bank_mask:0xf
	v_fmac_f32_dpp v204, v52, v224 row_ror:1 row_mask:0xf bank_mask:0xf
	v_fmac_f32_dpp v205, v53, v225 row_ror:1 row_mask:0xf bank_mask:0xf
	v_fmac_f32_dpp v206, v54, v226 row_ror:1 row_mask:0xf bank_mask:0xf
	v_fmac_f32_dpp v207, v55, v227 row_ror:1 row_mask:0xf bank_mask:0xf
	v_fmac_f32_dpp v204, v36, v176 row_shl:1 row_mask:0xf bank_mask:0xf
	v_fmac_f32_dpp v205, v37, v177 row_shl:1 row_mask:0xf bank_mask:0xf
	v_fmac_f32_dpp v206, v38, v178 row_shl:1 row_mask:0xf bank_mask:0xf
	v_fmac_f32_dpp v207, v39, v179 row_shl:1 row_mask:0xf bank_mask:0xf
	v_fmac_f32_dpp v204, v20, v232 row_ror:15 row_mask:0xf bank_mask:0xf
	v_fmac_f32_dpp v205, v21, v233 row_ror:15 row_mask:0xf bank_mask:0xf
	v_fmac_f32_dpp v206, v22, v234 row_ror:15 row_mask:0xf bank_mask:0xf
	v_fmac_f32_dpp v207, v23, v235 row_ror:15 row_mask:0xf bank_mask:0xf
	v_mul_f32_e32 v208, 0xbfb8aa3b, v200
	v_mul_f32_e32 v209, 0xbfb8aa3b, v201
	v_mul_f32_e32 v210, 0xbfb8aa3b, v202
	v_mul_f32_e32 v211, 0xbfb8aa3b, v203
	v_exp_f32_e32 v208, v208
	v_exp_f32_e32 v209, v209
	v_exp_f32_e32 v210, v210
	v_exp_f32_e32 v211, v211
	v_add_f32_e32 v208, 1.0, v208
	v_add_f32_e32 v209, 1.0, v209
	v_add_f32_e32 v210, 1.0, v210
	v_add_f32_e32 v211, 1.0, v211
	v_rcp_f32_e32 v208, v208
	v_rcp_f32_e32 v209, v209
	v_rcp_f32_e32 v210, v210
	v_rcp_f32_e32 v211, v211
	v_mul_f32_e32 v200, v200, v208
	v_mul_f32_e32 v201, v201, v209
	v_mul_f32_e32 v202, v202, v210
	v_mul_f32_e32 v203, v203, v211
	v_mul_f32_e32 v200, v200, v204
	v_mul_f32_e32 v201, v201, v205
	v_mul_f32_e32 v202, v202, v206
	v_mul_f32_e32 v203, v203, v207
	v_cvt_pk_bf16_f32 v246, v200, v201
	v_cvt_pk_bf16_f32 v247, v202, v203
	v_fma_f32 v200, v132, v32, v140
	v_fma_f32 v201, v133, v33, v141
	v_fma_f32 v202, v134, v34, v142
	v_fma_f32 v203, v135, v35, v143
	v_fmac_f32_dpp v200, v32, v128 row_shr:1 row_mask:0xf bank_mask:0xf
	v_fmac_f32_dpp v201, v33, v129 row_shr:1 row_mask:0xf bank_mask:0xf
	v_fmac_f32_dpp v202, v34, v130 row_shr:1 row_mask:0xf bank_mask:0xf
	v_fmac_f32_dpp v203, v35, v131 row_shr:1 row_mask:0xf bank_mask:0xf
	v_fmac_f32_dpp v200, v48, v216 row_ror:1 row_mask:0xf bank_mask:0xf
	v_fmac_f32_dpp v201, v49, v217 row_ror:1 row_mask:0xf bank_mask:0xf
	v_fmac_f32_dpp v202, v50, v218 row_ror:1 row_mask:0xf bank_mask:0xf
	v_fmac_f32_dpp v203, v51, v219 row_ror:1 row_mask:0xf bank_mask:0xf
	v_fmac_f32_dpp v200, v32, v136 row_shl:1 row_mask:0xf bank_mask:0xf
	v_fmac_f32_dpp v201, v33, v137 row_shl:1 row_mask:0xf bank_mask:0xf
	v_fmac_f32_dpp v202, v34, v138 row_shl:1 row_mask:0xf bank_mask:0xf
	v_fmac_f32_dpp v203, v35, v139 row_shl:1 row_mask:0xf bank_mask:0xf
	v_fmac_f32_dpp v200, v16, v220 row_ror:15 row_mask:0xf bank_mask:0xf
	v_fmac_f32_dpp v201, v17, v221 row_ror:15 row_mask:0xf bank_mask:0xf
	v_fmac_f32_dpp v202, v18, v222 row_ror:15 row_mask:0xf bank_mask:0xf
	v_fmac_f32_dpp v203, v19, v223 row_ror:15 row_mask:0xf bank_mask:0xf
	v_fma_f32 v204, v172, v20, v180
	v_fma_f32 v205, v173, v21, v181
	v_fma_f32 v206, v174, v22, v182
	v_fma_f32 v207, v175, v23, v183
	v_fmac_f32_dpp v204, v20, v160 row_shr:1 row_mask:0xf bank_mask:0xf
	v_fmac_f32_dpp v205, v21, v161 row_shr:1 row_mask:0xf bank_mask:0xf
	v_fmac_f32_dpp v206, v22, v162 row_shr:1 row_mask:0xf bank_mask:0xf
	v_fmac_f32_dpp v207, v23, v163 row_shr:1 row_mask:0xf bank_mask:0xf
	v_fmac_f32_dpp v204, v36, v224 row_ror:1 row_mask:0xf bank_mask:0xf
	v_fmac_f32_dpp v205, v37, v225 row_ror:1 row_mask:0xf bank_mask:0xf
	v_fmac_f32_dpp v206, v38, v226 row_ror:1 row_mask:0xf bank_mask:0xf
	v_fmac_f32_dpp v207, v39, v227 row_ror:1 row_mask:0xf bank_mask:0xf
	v_fmac_f32_dpp v204, v20, v176 row_shl:1 row_mask:0xf bank_mask:0xf
	v_fmac_f32_dpp v205, v21, v177 row_shl:1 row_mask:0xf bank_mask:0xf
	v_fmac_f32_dpp v206, v22, v178 row_shl:1 row_mask:0xf bank_mask:0xf
	v_fmac_f32_dpp v207, v23, v179 row_shl:1 row_mask:0xf bank_mask:0xf
	v_fmac_f32_dpp v204, v4, v232 row_ror:15 row_mask:0xf bank_mask:0xf
	v_fmac_f32_dpp v205, v5, v233 row_ror:15 row_mask:0xf bank_mask:0xf
	v_fmac_f32_dpp v206, v6, v234 row_ror:15 row_mask:0xf bank_mask:0xf
	v_fmac_f32_dpp v207, v7, v235 row_ror:15 row_mask:0xf bank_mask:0xf
	v_mul_f32_e32 v208, 0xbfb8aa3b, v200
	v_mul_f32_e32 v209, 0xbfb8aa3b, v201
	v_mul_f32_e32 v210, 0xbfb8aa3b, v202
	v_mul_f32_e32 v211, 0xbfb8aa3b, v203
	v_exp_f32_e32 v208, v208
	v_exp_f32_e32 v209, v209
	v_exp_f32_e32 v210, v210
	v_exp_f32_e32 v211, v211
	v_add_f32_e32 v208, 1.0, v208
	v_add_f32_e32 v209, 1.0, v209
	v_add_f32_e32 v210, 1.0, v210
	v_add_f32_e32 v211, 1.0, v211
	v_rcp_f32_e32 v208, v208
	v_rcp_f32_e32 v209, v209
	v_rcp_f32_e32 v210, v210
	v_rcp_f32_e32 v211, v211
	v_mul_f32_e32 v200, v200, v208
	v_mul_f32_e32 v201, v201, v209
	v_mul_f32_e32 v202, v202, v210
	v_mul_f32_e32 v203, v203, v211
	v_mul_f32_e32 v200, v200, v204
	v_mul_f32_e32 v201, v201, v205
	v_mul_f32_e32 v202, v202, v206
	v_mul_f32_e32 v203, v203, v207
	v_cvt_pk_bf16_f32 v248, v200, v201
	v_cvt_pk_bf16_f32 v249, v202, v203
	v_fma_f32 v200, v132, v16, v140
	v_fma_f32 v201, v133, v17, v141
	v_fma_f32 v202, v134, v18, v142
	v_fma_f32 v203, v135, v19, v143
	v_fmac_f32_dpp v200, v16, v128 row_shr:1 row_mask:0xf bank_mask:0xf
	v_fmac_f32_dpp v201, v17, v129 row_shr:1 row_mask:0xf bank_mask:0xf
	v_fmac_f32_dpp v202, v18, v130 row_shr:1 row_mask:0xf bank_mask:0xf
	v_fmac_f32_dpp v203, v19, v131 row_shr:1 row_mask:0xf bank_mask:0xf
	v_fmac_f32_dpp v200, v32, v216 row_ror:1 row_mask:0xf bank_mask:0xf
	v_fmac_f32_dpp v201, v33, v217 row_ror:1 row_mask:0xf bank_mask:0xf
	v_fmac_f32_dpp v202, v34, v218 row_ror:1 row_mask:0xf bank_mask:0xf
	v_fmac_f32_dpp v203, v35, v219 row_ror:1 row_mask:0xf bank_mask:0xf
	v_fmac_f32_dpp v200, v16, v136 row_shl:1 row_mask:0xf bank_mask:0xf
	v_fmac_f32_dpp v201, v17, v137 row_shl:1 row_mask:0xf bank_mask:0xf
	v_fmac_f32_dpp v202, v18, v138 row_shl:1 row_mask:0xf bank_mask:0xf
	v_fmac_f32_dpp v203, v19, v139 row_shl:1 row_mask:0xf bank_mask:0xf
	v_fmac_f32_e32 v200, v192, v220
	v_fmac_f32_e32 v201, v193, v221
	v_fmac_f32_e32 v202, v194, v222
	v_fmac_f32_e32 v203, v195, v223
	v_fma_f32 v204, v172, v4, v180
	v_fma_f32 v205, v173, v5, v181
	v_fma_f32 v206, v174, v6, v182
	v_fma_f32 v207, v175, v7, v183
	v_fmac_f32_dpp v204, v4, v160 row_shr:1 row_mask:0xf bank_mask:0xf
	v_fmac_f32_dpp v205, v5, v161 row_shr:1 row_mask:0xf bank_mask:0xf
	v_fmac_f32_dpp v206, v6, v162 row_shr:1 row_mask:0xf bank_mask:0xf
	v_fmac_f32_dpp v207, v7, v163 row_shr:1 row_mask:0xf bank_mask:0xf
	v_fmac_f32_dpp v204, v20, v224 row_ror:1 row_mask:0xf bank_mask:0xf
	v_fmac_f32_dpp v205, v21, v225 row_ror:1 row_mask:0xf bank_mask:0xf
	v_fmac_f32_dpp v206, v22, v226 row_ror:1 row_mask:0xf bank_mask:0xf
	v_fmac_f32_dpp v207, v23, v227 row_ror:1 row_mask:0xf bank_mask:0xf
	v_fmac_f32_dpp v204, v4, v176 row_shl:1 row_mask:0xf bank_mask:0xf
	v_fmac_f32_dpp v205, v5, v177 row_shl:1 row_mask:0xf bank_mask:0xf
	v_fmac_f32_dpp v206, v6, v178 row_shl:1 row_mask:0xf bank_mask:0xf
	v_fmac_f32_dpp v207, v7, v179 row_shl:1 row_mask:0xf bank_mask:0xf
	v_fmac_f32_e32 v204, v196, v232
	v_fmac_f32_e32 v205, v197, v233
	v_fmac_f32_e32 v206, v198, v234
	v_fmac_f32_e32 v207, v199, v235
	v_mul_f32_e32 v208, 0xbfb8aa3b, v200
	v_mul_f32_e32 v209, 0xbfb8aa3b, v201
	v_mul_f32_e32 v210, 0xbfb8aa3b, v202
	v_mul_f32_e32 v211, 0xbfb8aa3b, v203
	v_exp_f32_e32 v208, v208
	v_exp_f32_e32 v209, v209
	v_exp_f32_e32 v210, v210
	v_exp_f32_e32 v211, v211
	v_add_f32_e32 v208, 1.0, v208
	v_add_f32_e32 v209, 1.0, v209
	v_add_f32_e32 v210, 1.0, v210
	v_add_f32_e32 v211, 1.0, v211
	v_rcp_f32_e32 v208, v208
	v_rcp_f32_e32 v209, v209
	v_rcp_f32_e32 v210, v210
	v_rcp_f32_e32 v211, v211
	v_mul_f32_e32 v200, v200, v208
	v_mul_f32_e32 v201, v201, v209
	v_mul_f32_e32 v202, v202, v210
	v_mul_f32_e32 v203, v203, v211
	v_mul_f32_e32 v200, v200, v204
	v_mul_f32_e32 v201, v201, v205
	v_mul_f32_e32 v202, v202, v206
	v_mul_f32_e32 v203, v203, v207
	v_cvt_pk_bf16_f32 v250, v200, v201
	v_cvt_pk_bf16_f32 v251, v202, v203
	global_load_dwordx4 v[128:131], v229, s[36:37] offset:16
	v_add_u32_e32 v211, 0x5800, v229
	global_load_dwordx4 v[132:135], v211, s[36:37] offset:16
	v_add_u32_e32 v210, 0xb000, v229
	global_load_dwordx4 v[136:139], v210, s[36:37] offset:16
	global_load_dwordx4 v[140:143], v229, s[38:39] offset:16
	v_add_u32_e32 v210, 0x2c00, v229
	global_load_dwordx4 v[160:163], v210, s[36:37] offset:16
	v_add_u32_e32 v211, 0x8400, v229
	global_load_dwordx4 v[172:175], v211, s[36:37] offset:16
	v_add_u32_e32 v210, 0xdc00, v229
	global_load_dwordx4 v[176:179], v210, s[36:37] offset:16
	v_add_u32_e32 v211, 0x2c00, v229
	global_load_dwordx4 v[180:183], v211, s[38:39] offset:16
	v_mov_b32_e32 v124, v236
	v_mov_b32_e32 v125, v237
	v_mov_b32_e32 v116, v238
	v_mov_b32_e32 v117, v239
	v_mov_b32_e32 v96, v240
	v_mov_b32_e32 v97, v241
	v_mov_b32_e32 v80, v242
	v_mov_b32_e32 v81, v243
	v_mov_b32_e32 v60, v244
	v_mov_b32_e32 v61, v245
	v_mov_b32_e32 v48, v246
	v_mov_b32_e32 v49, v247
	v_mov_b32_e32 v32, v248
	v_mov_b32_e32 v33, v249
	v_mov_b32_e32 v16, v250
	v_mov_b32_e32 v17, v251
	ds_read_b128 v[184:187], v231 offset:16
	ds_read_b128 v[188:191], v231 offset:528
	ds_read_b128 v[192:195], v231 offset:2064
	ds_read_b128 v[196:199], v231 offset:2576
	s_waitcnt vmcnt(0)
	v_cndmask_b32_e64 v216, 0, v128, s[54:55]
	v_cndmask_b32_e64 v220, 0, v136, s[56:57]
	v_cndmask_b32_e64 v217, 0, v129, s[54:55]
	v_cndmask_b32_e64 v221, 0, v137, s[56:57]
	v_cndmask_b32_e64 v218, 0, v130, s[54:55]
	v_cndmask_b32_e64 v222, 0, v138, s[56:57]
	v_cndmask_b32_e64 v219, 0, v131, s[54:55]
	v_cndmask_b32_e64 v223, 0, v139, s[56:57]
	v_cndmask_b32_e64 v224, 0, v160, s[54:55]
	v_cndmask_b32_e64 v232, 0, v176, s[56:57]
	v_cndmask_b32_e64 v225, 0, v161, s[54:55]
	v_cndmask_b32_e64 v233, 0, v177, s[56:57]
	v_cndmask_b32_e64 v226, 0, v162, s[54:55]
	v_cndmask_b32_e64 v234, 0, v178, s[56:57]
	v_cndmask_b32_e64 v227, 0, v163, s[54:55]
	v_cndmask_b32_e64 v235, 0, v179, s[56:57]
	s_waitcnt lgkmcnt(0)
	s_nop 1
	v_fma_f32 v200, v132, v120, v140
	v_fma_f32 v201, v133, v121, v141
	v_fma_f32 v202, v134, v122, v142
	v_fma_f32 v203, v135, v123, v143
	v_fmac_f32_dpp v200, v120, v128 row_shr:1 row_mask:0xf bank_mask:0xf
	v_fmac_f32_dpp v201, v121, v129 row_shr:1 row_mask:0xf bank_mask:0xf
	v_fmac_f32_dpp v202, v122, v130 row_shr:1 row_mask:0xf bank_mask:0xf
	v_fmac_f32_dpp v203, v123, v131 row_shr:1 row_mask:0xf bank_mask:0xf
	v_fmac_f32_e32 v200, v184, v216
	v_fmac_f32_e32 v201, v185, v217
	v_fmac_f32_e32 v202, v186, v218
	v_fmac_f32_e32 v203, v187, v219
	v_fmac_f32_dpp v200, v120, v136 row_shl:1 row_mask:0xf bank_mask:0xf
	v_fmac_f32_dpp v201, v121, v137 row_shl:1 row_mask:0xf bank_mask:0xf
	v_fmac_f32_dpp v202, v122, v138 row_shl:1 row_mask:0xf bank_mask:0xf
	v_fmac_f32_dpp v203, v123, v139 row_shl:1 row_mask:0xf bank_mask:0xf
	v_fmac_f32_dpp v200, v112, v220 row_ror:15 row_mask:0xf bank_mask:0xf
	v_fmac_f32_dpp v201, v113, v221 row_ror:15 row_mask:0xf bank_mask:0xf
	v_fmac_f32_dpp v202, v114, v222 row_ror:15 row_mask:0xf bank_mask:0xf
	v_fmac_f32_dpp v203, v115, v223 row_ror:15 row_mask:0xf bank_mask:0xf
	v_fma_f32 v204, v172, v104, v180
	v_fma_f32 v205, v173, v105, v181
	v_fma_f32 v206, v174, v106, v182
	v_fma_f32 v207, v175, v107, v183
	v_fmac_f32_dpp v204, v104, v160 row_shr:1 row_mask:0xf bank_mask:0xf
	v_fmac_f32_dpp v205, v105, v161 row_shr:1 row_mask:0xf bank_mask:0xf
	v_fmac_f32_dpp v206, v106, v162 row_shr:1 row_mask:0xf bank_mask:0xf
	v_fmac_f32_dpp v207, v107, v163 row_shr:1 row_mask:0xf bank_mask:0xf
	v_fmac_f32_e32 v204, v188, v224
	v_fmac_f32_e32 v205, v189, v225
	v_fmac_f32_e32 v206, v190, v226
	v_fmac_f32_e32 v207, v191, v227
	v_fmac_f32_dpp v204, v104, v176 row_shl:1 row_mask:0xf bank_mask:0xf
	v_fmac_f32_dpp v205, v105, v177 row_shl:1 row_mask:0xf bank_mask:0xf
	v_fmac_f32_dpp v206, v106, v178 row_shl:1 row_mask:0xf bank_mask:0xf
	v_fmac_f32_dpp v207, v107, v179 row_shl:1 row_mask:0xf bank_mask:0xf
	v_fmac_f32_dpp v204, v92, v232 row_ror:15 row_mask:0xf bank_mask:0xf
	v_fmac_f32_dpp v205, v93, v233 row_ror:15 row_mask:0xf bank_mask:0xf
	v_fmac_f32_dpp v206, v94, v234 row_ror:15 row_mask:0xf bank_mask:0xf
	v_fmac_f32_dpp v207, v95, v235 row_ror:15 row_mask:0xf bank_mask:0xf
	v_mul_f32_e32 v208, 0xbfb8aa3b, v200
	v_mul_f32_e32 v209, 0xbfb8aa3b, v201
	v_mul_f32_e32 v210, 0xbfb8aa3b, v202
	v_mul_f32_e32 v211, 0xbfb8aa3b, v203
	v_exp_f32_e32 v208, v208
	v_exp_f32_e32 v209, v209
	v_exp_f32_e32 v210, v210
	v_exp_f32_e32 v211, v211
	v_add_f32_e32 v208, 1.0, v208
	v_add_f32_e32 v209, 1.0, v209
	v_add_f32_e32 v210, 1.0, v210
	v_add_f32_e32 v211, 1.0, v211
	v_rcp_f32_e32 v208, v208
	v_rcp_f32_e32 v209, v209
	v_rcp_f32_e32 v210, v210
	v_rcp_f32_e32 v211, v211
	v_mul_f32_e32 v200, v200, v208
	v_mul_f32_e32 v201, v201, v209
	v_mul_f32_e32 v202, v202, v210
	v_mul_f32_e32 v203, v203, v211
	v_mul_f32_e32 v200, v200, v204
	v_mul_f32_e32 v201, v201, v205
	v_mul_f32_e32 v202, v202, v206
	v_mul_f32_e32 v203, v203, v207
	v_cvt_pk_bf16_f32 v126, v200, v201
	v_cvt_pk_bf16_f32 v127, v202, v203
	v_fma_f32 v200, v132, v112, v140
	v_fma_f32 v201, v133, v113, v141
	v_fma_f32 v202, v134, v114, v142
	v_fma_f32 v203, v135, v115, v143
	v_fmac_f32_dpp v200, v112, v128 row_shr:1 row_mask:0xf bank_mask:0xf
	v_fmac_f32_dpp v201, v113, v129 row_shr:1 row_mask:0xf bank_mask:0xf
	v_fmac_f32_dpp v202, v114, v130 row_shr:1 row_mask:0xf bank_mask:0xf
	v_fmac_f32_dpp v203, v115, v131 row_shr:1 row_mask:0xf bank_mask:0xf
	v_fmac_f32_dpp v200, v120, v216 row_ror:1 row_mask:0xf bank_mask:0xf
	v_fmac_f32_dpp v201, v121, v217 row_ror:1 row_mask:0xf bank_mask:0xf
	v_fmac_f32_dpp v202, v122, v218 row_ror:1 row_mask:0xf bank_mask:0xf
	v_fmac_f32_dpp v203, v123, v219 row_ror:1 row_mask:0xf bank_mask:0xf
	v_fmac_f32_dpp v200, v112, v136 row_shl:1 row_mask:0xf bank_mask:0xf
	v_fmac_f32_dpp v201, v113, v137 row_shl:1 row_mask:0xf bank_mask:0xf
	v_fmac_f32_dpp v202, v114, v138 row_shl:1 row_mask:0xf bank_mask:0xf
	v_fmac_f32_dpp v203, v115, v139 row_shl:1 row_mask:0xf bank_mask:0xf
	v_fmac_f32_dpp v200, v88, v220 row_ror:15 row_mask:0xf bank_mask:0xf
	v_fmac_f32_dpp v201, v89, v221 row_ror:15 row_mask:0xf bank_mask:0xf
	v_fmac_f32_dpp v202, v90, v222 row_ror:15 row_mask:0xf bank_mask:0xf
	v_fmac_f32_dpp v203, v91, v223 row_ror:15 row_mask:0xf bank_mask:0xf
	v_fma_f32 v204, v172, v92, v180
	v_fma_f32 v205, v173, v93, v181
	v_fma_f32 v206, v174, v94, v182
	v_fma_f32 v207, v175, v95, v183
	v_fmac_f32_dpp v204, v92, v160 row_shr:1 row_mask:0xf bank_mask:0xf
	v_fmac_f32_dpp v205, v93, v161 row_shr:1 row_mask:0xf bank_mask:0xf
	v_fmac_f32_dpp v206, v94, v162 row_shr:1 row_mask:0xf bank_mask:0xf
	v_fmac_f32_dpp v207, v95, v163 row_shr:1 row_mask:0xf bank_mask:0xf
	v_fmac_f32_dpp v204, v104, v224 row_ror:1 row_mask:0xf bank_mask:0xf
	v_fmac_f32_dpp v205, v105, v225 row_ror:1 row_mask:0xf bank_mask:0xf
	v_fmac_f32_dpp v206, v106, v226 row_ror:1 row_mask:0xf bank_mask:0xf
	v_fmac_f32_dpp v207, v107, v227 row_ror:1 row_mask:0xf bank_mask:0xf
	v_fmac_f32_dpp v204, v92, v176 row_shl:1 row_mask:0xf bank_mask:0xf
	v_fmac_f32_dpp v205, v93, v177 row_shl:1 row_mask:0xf bank_mask:0xf
	v_fmac_f32_dpp v206, v94, v178 row_shl:1 row_mask:0xf bank_mask:0xf
	v_fmac_f32_dpp v207, v95, v179 row_shl:1 row_mask:0xf bank_mask:0xf
	v_fmac_f32_dpp v204, v76, v232 row_ror:15 row_mask:0xf bank_mask:0xf
	v_fmac_f32_dpp v205, v77, v233 row_ror:15 row_mask:0xf bank_mask:0xf
	v_fmac_f32_dpp v206, v78, v234 row_ror:15 row_mask:0xf bank_mask:0xf
	v_fmac_f32_dpp v207, v79, v235 row_ror:15 row_mask:0xf bank_mask:0xf
	v_mul_f32_e32 v208, 0xbfb8aa3b, v200
	v_mul_f32_e32 v209, 0xbfb8aa3b, v201
	v_mul_f32_e32 v210, 0xbfb8aa3b, v202
	v_mul_f32_e32 v211, 0xbfb8aa3b, v203
	v_exp_f32_e32 v208, v208
	v_exp_f32_e32 v209, v209
	v_exp_f32_e32 v210, v210
	v_exp_f32_e32 v211, v211
	v_add_f32_e32 v208, 1.0, v208
	v_add_f32_e32 v209, 1.0, v209
	v_add_f32_e32 v210, 1.0, v210
	v_add_f32_e32 v211, 1.0, v211
	v_rcp_f32_e32 v208, v208
	v_rcp_f32_e32 v209, v209
	v_rcp_f32_e32 v210, v210
	v_rcp_f32_e32 v211, v211
	v_mul_f32_e32 v200, v200, v208
	v_mul_f32_e32 v201, v201, v209
	v_mul_f32_e32 v202, v202, v210
	v_mul_f32_e32 v203, v203, v211
	v_mul_f32_e32 v200, v200, v204
	v_mul_f32_e32 v201, v201, v205
	v_mul_f32_e32 v202, v202, v206
	v_mul_f32_e32 v203, v203, v207
	v_cvt_pk_bf16_f32 v118, v200, v201
	v_cvt_pk_bf16_f32 v119, v202, v203
	v_fma_f32 v200, v132, v88, v140
	v_fma_f32 v201, v133, v89, v141
	v_fma_f32 v202, v134, v90, v142
	v_fma_f32 v203, v135, v91, v143
	v_fmac_f32_dpp v200, v88, v128 row_shr:1 row_mask:0xf bank_mask:0xf
	v_fmac_f32_dpp v201, v89, v129 row_shr:1 row_mask:0xf bank_mask:0xf
	v_fmac_f32_dpp v202, v90, v130 row_shr:1 row_mask:0xf bank_mask:0xf
	v_fmac_f32_dpp v203, v91, v131 row_shr:1 row_mask:0xf bank_mask:0xf
	v_fmac_f32_dpp v200, v112, v216 row_ror:1 row_mask:0xf bank_mask:0xf
	v_fmac_f32_dpp v201, v113, v217 row_ror:1 row_mask:0xf bank_mask:0xf
	v_fmac_f32_dpp v202, v114, v218 row_ror:1 row_mask:0xf bank_mask:0xf
	v_fmac_f32_dpp v203, v115, v219 row_ror:1 row_mask:0xf bank_mask:0xf
	v_fmac_f32_dpp v200, v88, v136 row_shl:1 row_mask:0xf bank_mask:0xf
	v_fmac_f32_dpp v201, v89, v137 row_shl:1 row_mask:0xf bank_mask:0xf
	v_fmac_f32_dpp v202, v90, v138 row_shl:1 row_mask:0xf bank_mask:0xf
	v_fmac_f32_dpp v203, v91, v139 row_shl:1 row_mask:0xf bank_mask:0xf
	v_fmac_f32_dpp v200, v72, v220 row_ror:15 row_mask:0xf bank_mask:0xf
	v_fmac_f32_dpp v201, v73, v221 row_ror:15 row_mask:0xf bank_mask:0xf
	v_fmac_f32_dpp v202, v74, v222 row_ror:15 row_mask:0xf bank_mask:0xf
	v_fmac_f32_dpp v203, v75, v223 row_ror:15 row_mask:0xf bank_mask:0xf
	v_fma_f32 v204, v172, v76, v180
	v_fma_f32 v205, v173, v77, v181
	v_fma_f32 v206, v174, v78, v182
	v_fma_f32 v207, v175, v79, v183
	v_fmac_f32_dpp v204, v76, v160 row_shr:1 row_mask:0xf bank_mask:0xf
	v_fmac_f32_dpp v205, v77, v161 row_shr:1 row_mask:0xf bank_mask:0xf
	v_fmac_f32_dpp v206, v78, v162 row_shr:1 row_mask:0xf bank_mask:0xf
	v_fmac_f32_dpp v207, v79, v163 row_shr:1 row_mask:0xf bank_mask:0xf
	v_fmac_f32_dpp v204, v92, v224 row_ror:1 row_mask:0xf bank_mask:0xf
	v_fmac_f32_dpp v205, v93, v225 row_ror:1 row_mask:0xf bank_mask:0xf
	v_fmac_f32_dpp v206, v94, v226 row_ror:1 row_mask:0xf bank_mask:0xf
	v_fmac_f32_dpp v207, v95, v227 row_ror:1 row_mask:0xf bank_mask:0xf
	v_fmac_f32_dpp v204, v76, v176 row_shl:1 row_mask:0xf bank_mask:0xf
	v_fmac_f32_dpp v205, v77, v177 row_shl:1 row_mask:0xf bank_mask:0xf
	v_fmac_f32_dpp v206, v78, v178 row_shl:1 row_mask:0xf bank_mask:0xf
	v_fmac_f32_dpp v207, v79, v179 row_shl:1 row_mask:0xf bank_mask:0xf
	v_fmac_f32_dpp v204, v64, v232 row_ror:15 row_mask:0xf bank_mask:0xf
	v_fmac_f32_dpp v205, v65, v233 row_ror:15 row_mask:0xf bank_mask:0xf
	v_fmac_f32_dpp v206, v66, v234 row_ror:15 row_mask:0xf bank_mask:0xf
	v_fmac_f32_dpp v207, v67, v235 row_ror:15 row_mask:0xf bank_mask:0xf
	v_mul_f32_e32 v208, 0xbfb8aa3b, v200
	v_mul_f32_e32 v209, 0xbfb8aa3b, v201
	v_mul_f32_e32 v210, 0xbfb8aa3b, v202
	v_mul_f32_e32 v211, 0xbfb8aa3b, v203
	v_exp_f32_e32 v208, v208
	v_exp_f32_e32 v209, v209
	v_exp_f32_e32 v210, v210
	v_exp_f32_e32 v211, v211
	v_add_f32_e32 v208, 1.0, v208
	v_add_f32_e32 v209, 1.0, v209
	v_add_f32_e32 v210, 1.0, v210
	v_add_f32_e32 v211, 1.0, v211
	v_rcp_f32_e32 v208, v208
	v_rcp_f32_e32 v209, v209
	v_rcp_f32_e32 v210, v210
	v_rcp_f32_e32 v211, v211
	v_mul_f32_e32 v200, v200, v208
	v_mul_f32_e32 v201, v201, v209
	v_mul_f32_e32 v202, v202, v210
	v_mul_f32_e32 v203, v203, v211
	v_mul_f32_e32 v200, v200, v204
	v_mul_f32_e32 v201, v201, v205
	v_mul_f32_e32 v202, v202, v206
	v_mul_f32_e32 v203, v203, v207
	v_cvt_pk_bf16_f32 v98, v200, v201
	v_cvt_pk_bf16_f32 v99, v202, v203
	v_fma_f32 v200, v132, v72, v140
	v_fma_f32 v201, v133, v73, v141
	v_fma_f32 v202, v134, v74, v142
	v_fma_f32 v203, v135, v75, v143
	v_fmac_f32_dpp v200, v72, v128 row_shr:1 row_mask:0xf bank_mask:0xf
	v_fmac_f32_dpp v201, v73, v129 row_shr:1 row_mask:0xf bank_mask:0xf
	v_fmac_f32_dpp v202, v74, v130 row_shr:1 row_mask:0xf bank_mask:0xf
	v_fmac_f32_dpp v203, v75, v131 row_shr:1 row_mask:0xf bank_mask:0xf
	v_fmac_f32_dpp v200, v88, v216 row_ror:1 row_mask:0xf bank_mask:0xf
	v_fmac_f32_dpp v201, v89, v217 row_ror:1 row_mask:0xf bank_mask:0xf
	v_fmac_f32_dpp v202, v90, v218 row_ror:1 row_mask:0xf bank_mask:0xf
	v_fmac_f32_dpp v203, v91, v219 row_ror:1 row_mask:0xf bank_mask:0xf
	v_fmac_f32_dpp v200, v72, v136 row_shl:1 row_mask:0xf bank_mask:0xf
	v_fmac_f32_dpp v201, v73, v137 row_shl:1 row_mask:0xf bank_mask:0xf
	v_fmac_f32_dpp v202, v74, v138 row_shl:1 row_mask:0xf bank_mask:0xf
	v_fmac_f32_dpp v203, v75, v139 row_shl:1 row_mask:0xf bank_mask:0xf
	v_fmac_f32_e32 v200, v184, v220
	v_fmac_f32_e32 v201, v185, v221
	v_fmac_f32_e32 v202, v186, v222
	v_fmac_f32_e32 v203, v187, v223
	v_fma_f32 v204, v172, v64, v180
	v_fma_f32 v205, v173, v65, v181
	v_fma_f32 v206, v174, v66, v182
	v_fma_f32 v207, v175, v67, v183
	v_fmac_f32_dpp v204, v64, v160 row_shr:1 row_mask:0xf bank_mask:0xf
	v_fmac_f32_dpp v205, v65, v161 row_shr:1 row_mask:0xf bank_mask:0xf
	v_fmac_f32_dpp v206, v66, v162 row_shr:1 row_mask:0xf bank_mask:0xf
	v_fmac_f32_dpp v207, v67, v163 row_shr:1 row_mask:0xf bank_mask:0xf
	v_fmac_f32_dpp v204, v76, v224 row_ror:1 row_mask:0xf bank_mask:0xf
	v_fmac_f32_dpp v205, v77, v225 row_ror:1 row_mask:0xf bank_mask:0xf
	v_fmac_f32_dpp v206, v78, v226 row_ror:1 row_mask:0xf bank_mask:0xf
	v_fmac_f32_dpp v207, v79, v227 row_ror:1 row_mask:0xf bank_mask:0xf
	v_fmac_f32_dpp v204, v64, v176 row_shl:1 row_mask:0xf bank_mask:0xf
	v_fmac_f32_dpp v205, v65, v177 row_shl:1 row_mask:0xf bank_mask:0xf
	v_fmac_f32_dpp v206, v66, v178 row_shl:1 row_mask:0xf bank_mask:0xf
	v_fmac_f32_dpp v207, v67, v179 row_shl:1 row_mask:0xf bank_mask:0xf
	v_fmac_f32_e32 v204, v188, v232
	v_fmac_f32_e32 v205, v189, v233
	v_fmac_f32_e32 v206, v190, v234
	v_fmac_f32_e32 v207, v191, v235
	v_mul_f32_e32 v208, 0xbfb8aa3b, v200
	v_mul_f32_e32 v209, 0xbfb8aa3b, v201
	v_mul_f32_e32 v210, 0xbfb8aa3b, v202
	v_mul_f32_e32 v211, 0xbfb8aa3b, v203
	v_exp_f32_e32 v208, v208
	v_exp_f32_e32 v209, v209
	v_exp_f32_e32 v210, v210
	v_exp_f32_e32 v211, v211
	v_add_f32_e32 v208, 1.0, v208
	v_add_f32_e32 v209, 1.0, v209
	v_add_f32_e32 v210, 1.0, v210
	v_add_f32_e32 v211, 1.0, v211
	v_rcp_f32_e32 v208, v208
	v_rcp_f32_e32 v209, v209
	v_rcp_f32_e32 v210, v210
	v_rcp_f32_e32 v211, v211
	v_mul_f32_e32 v200, v200, v208
	v_mul_f32_e32 v201, v201, v209
	v_mul_f32_e32 v202, v202, v210
	v_mul_f32_e32 v203, v203, v211
	v_mul_f32_e32 v200, v200, v204
	v_mul_f32_e32 v201, v201, v205
	v_mul_f32_e32 v202, v202, v206
	v_mul_f32_e32 v203, v203, v207
	v_cvt_pk_bf16_f32 v82, v200, v201
	v_cvt_pk_bf16_f32 v83, v202, v203
	v_fma_f32 v200, v132, v56, v140
	v_fma_f32 v201, v133, v57, v141
	v_fma_f32 v202, v134, v58, v142
	v_fma_f32 v203, v135, v59, v143
	v_fmac_f32_dpp v200, v56, v128 row_shr:1 row_mask:0xf bank_mask:0xf
	v_fmac_f32_dpp v201, v57, v129 row_shr:1 row_mask:0xf bank_mask:0xf
	v_fmac_f32_dpp v202, v58, v130 row_shr:1 row_mask:0xf bank_mask:0xf
	v_fmac_f32_dpp v203, v59, v131 row_shr:1 row_mask:0xf bank_mask:0xf
	v_fmac_f32_e32 v200, v192, v216
	v_fmac_f32_e32 v201, v193, v217
	v_fmac_f32_e32 v202, v194, v218
	v_fmac_f32_e32 v203, v195, v219
	v_fmac_f32_dpp v200, v56, v136 row_shl:1 row_mask:0xf bank_mask:0xf
	v_fmac_f32_dpp v201, v57, v137 row_shl:1 row_mask:0xf bank_mask:0xf
	v_fmac_f32_dpp v202, v58, v138 row_shl:1 row_mask:0xf bank_mask:0xf
	v_fmac_f32_dpp v203, v59, v139 row_shl:1 row_mask:0xf bank_mask:0xf
	v_fmac_f32_dpp v200, v40, v220 row_ror:15 row_mask:0xf bank_mask:0xf
	v_fmac_f32_dpp v201, v41, v221 row_ror:15 row_mask:0xf bank_mask:0xf
	v_fmac_f32_dpp v202, v42, v222 row_ror:15 row_mask:0xf bank_mask:0xf
	v_fmac_f32_dpp v203, v43, v223 row_ror:15 row_mask:0xf bank_mask:0xf
	v_fma_f32 v204, v172, v44, v180
	v_fma_f32 v205, v173, v45, v181
	v_fma_f32 v206, v174, v46, v182
	v_fma_f32 v207, v175, v47, v183
	v_fmac_f32_dpp v204, v44, v160 row_shr:1 row_mask:0xf bank_mask:0xf
	v_fmac_f32_dpp v205, v45, v161 row_shr:1 row_mask:0xf bank_mask:0xf
	v_fmac_f32_dpp v206, v46, v162 row_shr:1 row_mask:0xf bank_mask:0xf
	v_fmac_f32_dpp v207, v47, v163 row_shr:1 row_mask:0xf bank_mask:0xf
	v_fmac_f32_e32 v204, v196, v224
	v_fmac_f32_e32 v205, v197, v225
	v_fmac_f32_e32 v206, v198, v226
	v_fmac_f32_e32 v207, v199, v227
	v_fmac_f32_dpp v204, v44, v176 row_shl:1 row_mask:0xf bank_mask:0xf
	v_fmac_f32_dpp v205, v45, v177 row_shl:1 row_mask:0xf bank_mask:0xf
	v_fmac_f32_dpp v206, v46, v178 row_shl:1 row_mask:0xf bank_mask:0xf
	v_fmac_f32_dpp v207, v47, v179 row_shl:1 row_mask:0xf bank_mask:0xf
	v_fmac_f32_dpp v204, v28, v232 row_ror:15 row_mask:0xf bank_mask:0xf
	v_fmac_f32_dpp v205, v29, v233 row_ror:15 row_mask:0xf bank_mask:0xf
	v_fmac_f32_dpp v206, v30, v234 row_ror:15 row_mask:0xf bank_mask:0xf
	v_fmac_f32_dpp v207, v31, v235 row_ror:15 row_mask:0xf bank_mask:0xf
	v_mul_f32_e32 v208, 0xbfb8aa3b, v200
	v_mul_f32_e32 v209, 0xbfb8aa3b, v201
	v_mul_f32_e32 v210, 0xbfb8aa3b, v202
	v_mul_f32_e32 v211, 0xbfb8aa3b, v203
	v_exp_f32_e32 v208, v208
	v_exp_f32_e32 v209, v209
	v_exp_f32_e32 v210, v210
	v_exp_f32_e32 v211, v211
	v_add_f32_e32 v208, 1.0, v208
	v_add_f32_e32 v209, 1.0, v209
	v_add_f32_e32 v210, 1.0, v210
	v_add_f32_e32 v211, 1.0, v211
	v_rcp_f32_e32 v208, v208
	v_rcp_f32_e32 v209, v209
	v_rcp_f32_e32 v210, v210
	v_rcp_f32_e32 v211, v211
	v_mul_f32_e32 v200, v200, v208
	v_mul_f32_e32 v201, v201, v209
	v_mul_f32_e32 v202, v202, v210
	v_mul_f32_e32 v203, v203, v211
	v_mul_f32_e32 v200, v200, v204
	v_mul_f32_e32 v201, v201, v205
	v_mul_f32_e32 v202, v202, v206
	v_mul_f32_e32 v203, v203, v207
	v_cvt_pk_bf16_f32 v62, v200, v201
	v_cvt_pk_bf16_f32 v63, v202, v203
	v_fma_f32 v200, v132, v40, v140
	v_fma_f32 v201, v133, v41, v141
	v_fma_f32 v202, v134, v42, v142
	v_fma_f32 v203, v135, v43, v143
	v_fmac_f32_dpp v200, v40, v128 row_shr:1 row_mask:0xf bank_mask:0xf
	v_fmac_f32_dpp v201, v41, v129 row_shr:1 row_mask:0xf bank_mask:0xf
	v_fmac_f32_dpp v202, v42, v130 row_shr:1 row_mask:0xf bank_mask:0xf
	v_fmac_f32_dpp v203, v43, v131 row_shr:1 row_mask:0xf bank_mask:0xf
	v_fmac_f32_dpp v200, v56, v216 row_ror:1 row_mask:0xf bank_mask:0xf
	v_fmac_f32_dpp v201, v57, v217 row_ror:1 row_mask:0xf bank_mask:0xf
	v_fmac_f32_dpp v202, v58, v218 row_ror:1 row_mask:0xf bank_mask:0xf
	v_fmac_f32_dpp v203, v59, v219 row_ror:1 row_mask:0xf bank_mask:0xf
	v_fmac_f32_dpp v200, v40, v136 row_shl:1 row_mask:0xf bank_mask:0xf
	v_fmac_f32_dpp v201, v41, v137 row_shl:1 row_mask:0xf bank_mask:0xf
	v_fmac_f32_dpp v202, v42, v138 row_shl:1 row_mask:0xf bank_mask:0xf
	v_fmac_f32_dpp v203, v43, v139 row_shl:1 row_mask:0xf bank_mask:0xf
	v_fmac_f32_dpp v200, v24, v220 row_ror:15 row_mask:0xf bank_mask:0xf
	v_fmac_f32_dpp v201, v25, v221 row_ror:15 row_mask:0xf bank_mask:0xf
	v_fmac_f32_dpp v202, v26, v222 row_ror:15 row_mask:0xf bank_mask:0xf
	v_fmac_f32_dpp v203, v27, v223 row_ror:15 row_mask:0xf bank_mask:0xf
	v_fma_f32 v204, v172, v28, v180
	v_fma_f32 v205, v173, v29, v181
	v_fma_f32 v206, v174, v30, v182
	v_fma_f32 v207, v175, v31, v183
	v_fmac_f32_dpp v204, v28, v160 row_shr:1 row_mask:0xf bank_mask:0xf
	v_fmac_f32_dpp v205, v29, v161 row_shr:1 row_mask:0xf bank_mask:0xf
	v_fmac_f32_dpp v206, v30, v162 row_shr:1 row_mask:0xf bank_mask:0xf
	v_fmac_f32_dpp v207, v31, v163 row_shr:1 row_mask:0xf bank_mask:0xf
	v_fmac_f32_dpp v204, v44, v224 row_ror:1 row_mask:0xf bank_mask:0xf
	v_fmac_f32_dpp v205, v45, v225 row_ror:1 row_mask:0xf bank_mask:0xf
	v_fmac_f32_dpp v206, v46, v226 row_ror:1 row_mask:0xf bank_mask:0xf
	v_fmac_f32_dpp v207, v47, v227 row_ror:1 row_mask:0xf bank_mask:0xf
	v_fmac_f32_dpp v204, v28, v176 row_shl:1 row_mask:0xf bank_mask:0xf
	v_fmac_f32_dpp v205, v29, v177 row_shl:1 row_mask:0xf bank_mask:0xf
	v_fmac_f32_dpp v206, v30, v178 row_shl:1 row_mask:0xf bank_mask:0xf
	v_fmac_f32_dpp v207, v31, v179 row_shl:1 row_mask:0xf bank_mask:0xf
	v_fmac_f32_dpp v204, v12, v232 row_ror:15 row_mask:0xf bank_mask:0xf
	v_fmac_f32_dpp v205, v13, v233 row_ror:15 row_mask:0xf bank_mask:0xf
	v_fmac_f32_dpp v206, v14, v234 row_ror:15 row_mask:0xf bank_mask:0xf
	v_fmac_f32_dpp v207, v15, v235 row_ror:15 row_mask:0xf bank_mask:0xf
	v_mul_f32_e32 v208, 0xbfb8aa3b, v200
	v_mul_f32_e32 v209, 0xbfb8aa3b, v201
	v_mul_f32_e32 v210, 0xbfb8aa3b, v202
	v_mul_f32_e32 v211, 0xbfb8aa3b, v203
	v_exp_f32_e32 v208, v208
	v_exp_f32_e32 v209, v209
	v_exp_f32_e32 v210, v210
	v_exp_f32_e32 v211, v211
	v_add_f32_e32 v208, 1.0, v208
	v_add_f32_e32 v209, 1.0, v209
	v_add_f32_e32 v210, 1.0, v210
	v_add_f32_e32 v211, 1.0, v211
	v_rcp_f32_e32 v208, v208
	v_rcp_f32_e32 v209, v209
	v_rcp_f32_e32 v210, v210
	v_rcp_f32_e32 v211, v211
	v_mul_f32_e32 v200, v200, v208
	v_mul_f32_e32 v201, v201, v209
	v_mul_f32_e32 v202, v202, v210
	v_mul_f32_e32 v203, v203, v211
	v_mul_f32_e32 v200, v200, v204
	v_mul_f32_e32 v201, v201, v205
	v_mul_f32_e32 v202, v202, v206
	v_mul_f32_e32 v203, v203, v207
	v_cvt_pk_bf16_f32 v50, v200, v201
	v_cvt_pk_bf16_f32 v51, v202, v203
	v_fma_f32 v200, v132, v24, v140
	v_fma_f32 v201, v133, v25, v141
	v_fma_f32 v202, v134, v26, v142
	v_fma_f32 v203, v135, v27, v143
	v_fmac_f32_dpp v200, v24, v128 row_shr:1 row_mask:0xf bank_mask:0xf
	v_fmac_f32_dpp v201, v25, v129 row_shr:1 row_mask:0xf bank_mask:0xf
	v_fmac_f32_dpp v202, v26, v130 row_shr:1 row_mask:0xf bank_mask:0xf
	v_fmac_f32_dpp v203, v27, v131 row_shr:1 row_mask:0xf bank_mask:0xf
	v_fmac_f32_dpp v200, v40, v216 row_ror:1 row_mask:0xf bank_mask:0xf
	v_fmac_f32_dpp v201, v41, v217 row_ror:1 row_mask:0xf bank_mask:0xf
	v_fmac_f32_dpp v202, v42, v218 row_ror:1 row_mask:0xf bank_mask:0xf
	v_fmac_f32_dpp v203, v43, v219 row_ror:1 row_mask:0xf bank_mask:0xf
	v_fmac_f32_dpp v200, v24, v136 row_shl:1 row_mask:0xf bank_mask:0xf
	v_fmac_f32_dpp v201, v25, v137 row_shl:1 row_mask:0xf bank_mask:0xf
	v_fmac_f32_dpp v202, v26, v138 row_shl:1 row_mask:0xf bank_mask:0xf
	v_fmac_f32_dpp v203, v27, v139 row_shl:1 row_mask:0xf bank_mask:0xf
	v_fmac_f32_dpp v200, v8, v220 row_ror:15 row_mask:0xf bank_mask:0xf
	v_fmac_f32_dpp v201, v9, v221 row_ror:15 row_mask:0xf bank_mask:0xf
	v_fmac_f32_dpp v202, v10, v222 row_ror:15 row_mask:0xf bank_mask:0xf
	v_fmac_f32_dpp v203, v11, v223 row_ror:15 row_mask:0xf bank_mask:0xf
	v_fma_f32 v204, v172, v12, v180
	v_fma_f32 v205, v173, v13, v181
	v_fma_f32 v206, v174, v14, v182
	v_fma_f32 v207, v175, v15, v183
	v_fmac_f32_dpp v204, v12, v160 row_shr:1 row_mask:0xf bank_mask:0xf
	v_fmac_f32_dpp v205, v13, v161 row_shr:1 row_mask:0xf bank_mask:0xf
	v_fmac_f32_dpp v206, v14, v162 row_shr:1 row_mask:0xf bank_mask:0xf
	v_fmac_f32_dpp v207, v15, v163 row_shr:1 row_mask:0xf bank_mask:0xf
	v_fmac_f32_dpp v204, v28, v224 row_ror:1 row_mask:0xf bank_mask:0xf
	v_fmac_f32_dpp v205, v29, v225 row_ror:1 row_mask:0xf bank_mask:0xf
	v_fmac_f32_dpp v206, v30, v226 row_ror:1 row_mask:0xf bank_mask:0xf
	v_fmac_f32_dpp v207, v31, v227 row_ror:1 row_mask:0xf bank_mask:0xf
	v_fmac_f32_dpp v204, v12, v176 row_shl:1 row_mask:0xf bank_mask:0xf
	v_fmac_f32_dpp v205, v13, v177 row_shl:1 row_mask:0xf bank_mask:0xf
	v_fmac_f32_dpp v206, v14, v178 row_shl:1 row_mask:0xf bank_mask:0xf
	v_fmac_f32_dpp v207, v15, v179 row_shl:1 row_mask:0xf bank_mask:0xf
	v_fmac_f32_dpp v204, v0, v232 row_ror:15 row_mask:0xf bank_mask:0xf
	v_fmac_f32_dpp v205, v1, v233 row_ror:15 row_mask:0xf bank_mask:0xf
	v_fmac_f32_dpp v206, v2, v234 row_ror:15 row_mask:0xf bank_mask:0xf
	v_fmac_f32_dpp v207, v3, v235 row_ror:15 row_mask:0xf bank_mask:0xf
	v_mul_f32_e32 v208, 0xbfb8aa3b, v200
	v_mul_f32_e32 v209, 0xbfb8aa3b, v201
	v_mul_f32_e32 v210, 0xbfb8aa3b, v202
	v_mul_f32_e32 v211, 0xbfb8aa3b, v203
	v_exp_f32_e32 v208, v208
	v_exp_f32_e32 v209, v209
	v_exp_f32_e32 v210, v210
	v_exp_f32_e32 v211, v211
	v_add_f32_e32 v208, 1.0, v208
	v_add_f32_e32 v209, 1.0, v209
	v_add_f32_e32 v210, 1.0, v210
	v_add_f32_e32 v211, 1.0, v211
	v_rcp_f32_e32 v208, v208
	v_rcp_f32_e32 v209, v209
	v_rcp_f32_e32 v210, v210
	v_rcp_f32_e32 v211, v211
	v_mul_f32_e32 v200, v200, v208
	v_mul_f32_e32 v201, v201, v209
	v_mul_f32_e32 v202, v202, v210
	v_mul_f32_e32 v203, v203, v211
	v_mul_f32_e32 v200, v200, v204
	v_mul_f32_e32 v201, v201, v205
	v_mul_f32_e32 v202, v202, v206
	v_mul_f32_e32 v203, v203, v207
	v_cvt_pk_bf16_f32 v34, v200, v201
	v_cvt_pk_bf16_f32 v35, v202, v203
	v_fma_f32 v200, v132, v8, v140
	v_fma_f32 v201, v133, v9, v141
	v_fma_f32 v202, v134, v10, v142
	v_fma_f32 v203, v135, v11, v143
	v_fmac_f32_dpp v200, v8, v128 row_shr:1 row_mask:0xf bank_mask:0xf
	v_fmac_f32_dpp v201, v9, v129 row_shr:1 row_mask:0xf bank_mask:0xf
	v_fmac_f32_dpp v202, v10, v130 row_shr:1 row_mask:0xf bank_mask:0xf
	v_fmac_f32_dpp v203, v11, v131 row_shr:1 row_mask:0xf bank_mask:0xf
	v_fmac_f32_dpp v200, v24, v216 row_ror:1 row_mask:0xf bank_mask:0xf
	v_fmac_f32_dpp v201, v25, v217 row_ror:1 row_mask:0xf bank_mask:0xf
	v_fmac_f32_dpp v202, v26, v218 row_ror:1 row_mask:0xf bank_mask:0xf
	v_fmac_f32_dpp v203, v27, v219 row_ror:1 row_mask:0xf bank_mask:0xf
	v_fmac_f32_dpp v200, v8, v136 row_shl:1 row_mask:0xf bank_mask:0xf
	v_fmac_f32_dpp v201, v9, v137 row_shl:1 row_mask:0xf bank_mask:0xf
	v_fmac_f32_dpp v202, v10, v138 row_shl:1 row_mask:0xf bank_mask:0xf
	v_fmac_f32_dpp v203, v11, v139 row_shl:1 row_mask:0xf bank_mask:0xf
	v_fmac_f32_e32 v200, v192, v220
	v_fmac_f32_e32 v201, v193, v221
	v_fmac_f32_e32 v202, v194, v222
	v_fmac_f32_e32 v203, v195, v223
	v_fma_f32 v204, v172, v0, v180
	v_fma_f32 v205, v173, v1, v181
	v_fma_f32 v206, v174, v2, v182
	v_fma_f32 v207, v175, v3, v183
	v_fmac_f32_dpp v204, v0, v160 row_shr:1 row_mask:0xf bank_mask:0xf
	v_fmac_f32_dpp v205, v1, v161 row_shr:1 row_mask:0xf bank_mask:0xf
	v_fmac_f32_dpp v206, v2, v162 row_shr:1 row_mask:0xf bank_mask:0xf
	v_fmac_f32_dpp v207, v3, v163 row_shr:1 row_mask:0xf bank_mask:0xf
	v_fmac_f32_dpp v204, v12, v224 row_ror:1 row_mask:0xf bank_mask:0xf
	v_fmac_f32_dpp v205, v13, v225 row_ror:1 row_mask:0xf bank_mask:0xf
	v_fmac_f32_dpp v206, v14, v226 row_ror:1 row_mask:0xf bank_mask:0xf
	v_fmac_f32_dpp v207, v15, v227 row_ror:1 row_mask:0xf bank_mask:0xf
	v_fmac_f32_dpp v204, v0, v176 row_shl:1 row_mask:0xf bank_mask:0xf
	v_fmac_f32_dpp v205, v1, v177 row_shl:1 row_mask:0xf bank_mask:0xf
	v_fmac_f32_dpp v206, v2, v178 row_shl:1 row_mask:0xf bank_mask:0xf
	v_fmac_f32_dpp v207, v3, v179 row_shl:1 row_mask:0xf bank_mask:0xf
	v_fmac_f32_e32 v204, v196, v232
	v_fmac_f32_e32 v205, v197, v233
	v_fmac_f32_e32 v206, v198, v234
	v_fmac_f32_e32 v207, v199, v235
	v_mul_f32_e32 v208, 0xbfb8aa3b, v200
	v_mul_f32_e32 v209, 0xbfb8aa3b, v201
	v_mul_f32_e32 v210, 0xbfb8aa3b, v202
	v_mul_f32_e32 v211, 0xbfb8aa3b, v203
	v_exp_f32_e32 v208, v208
	v_exp_f32_e32 v209, v209
	v_exp_f32_e32 v210, v210
	v_exp_f32_e32 v211, v211
	v_add_f32_e32 v208, 1.0, v208
	v_add_f32_e32 v209, 1.0, v209
	v_add_f32_e32 v210, 1.0, v210
	v_add_f32_e32 v211, 1.0, v211
	v_rcp_f32_e32 v208, v208
	v_rcp_f32_e32 v209, v209
	v_rcp_f32_e32 v210, v210
	v_rcp_f32_e32 v211, v211
	v_mul_f32_e32 v200, v200, v208
	v_mul_f32_e32 v201, v201, v209
	v_mul_f32_e32 v202, v202, v210
	v_mul_f32_e32 v203, v203, v211
	v_mul_f32_e32 v200, v200, v204
	v_mul_f32_e32 v201, v201, v205
	v_mul_f32_e32 v202, v202, v206
	v_mul_f32_e32 v203, v203, v207
	v_cvt_pk_bf16_f32 v18, v200, v201
	v_cvt_pk_bf16_f32 v19, v202, v203
	global_store_dwordx4 v171, v[124:127], s[40:41]
	v_add_u32_e32 v250, 0x16000, v171
	global_store_dwordx4 v250, v[116:119], s[40:41]
	s_nop 0
	v_add_u32_e32 v250, 0x2c000, v171
	global_store_dwordx4 v250, v[96:99], s[40:41]
	s_nop 0
	v_add_u32_e32 v250, 0x42000, v171
	global_store_dwordx4 v250, v[80:83], s[40:41]
	s_nop 0
	v_add_u32_e32 v250, 0xb0000, v171
	global_store_dwordx4 v250, v[60:63], s[40:41]
	s_nop 0
	v_add_u32_e32 v250, 0xc6000, v171
	global_store_dwordx4 v250, v[48:51], s[40:41]
	s_nop 0
	v_add_u32_e32 v250, 0xdc000, v171
	global_store_dwordx4 v250, v[32:35], s[40:41]
	s_nop 0
	v_add_u32_e32 v250, 0xf2000, v171
	global_store_dwordx4 v250, v[16:19], s[40:41]
	s_nop 0
	s_andn2_b64 vcc, exec, s[6:7]
	s_mov_b64 s[4:5], -1
	s_cbranch_vccnz .LBB0_1748
	s_andn2_b64 vcc, exec, s[12:13]
	s_cbranch_vccnz .LBB0_1747
	s_barrier
	s_branch .LBB0_1747

.LBB0_1759:
	s_waitcnt vmcnt(0) lgkmcnt(0)
	s_barrier
	s_branch .LBB0_1867
	s_cmp_lt_i32 s73, 20
	s_cbranch_scc1 .LBB0_1809
	s_waitcnt vmcnt(0)
	s_waitcnt vmcnt(0) lgkmcnt(0)
	s_barrier
	s_mov_b64 s[6:7], exec
	v_readlane_b32 s4, v254, 59
	v_readlane_b32 s5, v254, 60
	s_and_b64 s[4:5], s[6:7], s[4:5]
	s_mov_b64 exec, s[4:5]
	s_cbranch_execz .LBB0_1808
	v_mov_b32_e32 v0, s78
	s_waitcnt vmcnt(0) expcnt(0) lgkmcnt(0)
	ds_read_b32 v2, v0
	ds_read_b32 v0, v0 offset:4
	s_waitcnt lgkmcnt(1)
	v_cmp_ne_u32_e32 vcc, 0, v2
	s_cbranch_vccnz .LBB0_1776
	v_readlane_b32 s4, v254, 0
	v_readlane_b32 s5, v254, 1
	s_load_dword s4, s[4:5], 0x14
	s_mov_b32 s51, 1
	v_mov_b32_e32 v16, 0
	s_waitcnt lgkmcnt(0)
	s_lshr_b32 s8, s4, 16
	s_and_b32 s4, s4, 0xffff
	s_cmp_lg_u32 s4, 0
	s_cselect_b64 s[4:5], -1, 0
	s_cmp_lg_u64 s[4:5], 0
	s_addc_u32 s4, s3, 0
	s_cmp_lg_u32 s8, 0
	s_mul_i32 s52, s4, s2
	s_cselect_b64 s[4:5], -1, 0
	s_cmp_lg_u64 s[4:5], 0
	v_readlane_b32 s4, v254, 2
	s_addc_u32 s4, s4, 0
	s_add_u32 s8, s70, 0x4200
	s_addc_u32 s9, s71, 0
	s_add_u32 s10, s70, 0x4400
	s_addc_u32 s11, s71, 0
	s_add_u32 s12, s70, 0x4500
	s_addc_u32 s13, s71, 0
	s_add_u32 s14, s70, 0x4600
	s_addc_u32 s15, s71, 0
	s_add_u32 s16, s70, 0x4700
	s_addc_u32 s17, s71, 0
	s_add_u32 s22, s70, 0x4800
	s_addc_u32 s23, s71, 0
	s_add_u32 s24, s70, 0x4900
	s_addc_u32 s25, s71, 0
	s_add_u32 s26, s70, 0x4a00
	s_addc_u32 s27, s71, 0
	s_add_u32 s28, s70, 0x4b00
	s_addc_u32 s29, s71, 0
	s_add_u32 s34, s70, 0x4c00
	s_addc_u32 s35, s71, 0
	s_add_u32 s36, s70, 0x4d00
	s_addc_u32 s37, s71, 0
	s_add_u32 s38, s70, 0x4e00
	s_addc_u32 s39, s71, 0
	s_add_u32 s40, s70, 0x4f00
	s_addc_u32 s41, s71, 0
	s_add_u32 s42, s70, 0x5000
	s_addc_u32 s43, s71, 0
	s_add_u32 s20, s70, 0x5100
	s_addc_u32 s21, s71, 0
	s_add_u32 s30, s70, 0x5200
	s_addc_u32 s31, s71, 0
	s_mul_i32 s52, s52, s4
	s_add_u32 s4, s70, 0x5300
	s_addc_u32 s5, s71, 0
	s_branch .LBB0_1764
